# P1 epilogue stores: (address,data) pairs moved between lanes with ds_bpermute so 4 adjacent lanes write 64 contiguous bytes; side task loads row-contiguous via per-wave LDS transpose; b_f load hoisted
# speedup vs baseline: 1.0036x; 1.0036x over previous
; #define PG8_STAGE(bufoff, gbase, voff) do { _Pragma("unroll") for (int _i = 0; _i < 2; ++_i) \
;         __builtin_amdgcn_global_load_lds((const unsigned*)((const char*)(gbase) + (voff)[_i]), (LAS unsigned*)(lds + (bufoff) + ldsw + _i * 8192), 16, 0, 0); } while (0)
; #define PG8_LDA(dst, b, h) do { _Pragma("unroll") for (int m = 0; m < 4; ++m) _Pragma("unroll") for (int k = 0; k < 2; ++k) dst[m][k] = *(const LAS bf16x8*)(lds + PG8_SA(b, h) + aoff + m * 2048 + k * 1024); } while (0)
; #define PG8_LDB(dst, b, h) do { _Pragma("unroll") for (int n = 0; n < 2; ++n) _Pragma("unroll") for (int k = 0; k < 2; ++k) dst[n][k] = *(const LAS bf16x8*)(lds + PG8_SB(b, h) + boff + n * 2048 + k * 1024); } while (0)
; #define PG8_MMA(ai, bj, At, Bt) do { __builtin_amdgcn_s_setprio(1); _Pragma("unroll") for (int m = 0; m < 4; ++m) _Pragma("unroll") for (int n = 0; n < 2; ++n) _Pragma("unroll") for (int k = 0; k < 2; ++k) \
;         acc[ai][bj][m][n] = __builtin_amdgcn_mfma_f32_16x16x32_bf16(Bt[n][k], At[m][k], acc[ai][bj][m][n], 0, 0, 0); __builtin_amdgcn_s_setprio(0); } while (0)
; #define PG8_WAIT_V(n) asm volatile("s_waitcnt vmcnt(" #n ")" ::: "memory")
; #define PG8_WAIT_L(n) asm volatile("s_waitcnt lgkmcnt(" #n ")" ::: "memory")
; #define PG8_BAR __builtin_amdgcn_s_barrier()
; #define PG8_SCHED __builtin_amdgcn_sched_barrier(0)
; template <class Epi, class Sched, int NSEG, bool ALIGN_EPI = true, bool AFTER_DRAIN = false>
; __device__ __forceinline__ void gemm_phase(LAS unsigned char* lds, const Gemm g, const Sched& S, const Epi& E) {
;     ...
;             PG8_LDB(B0, 0, 0); PG8_LDB(B1, 0, 1); PG8_SCHED; PG8_LDA(At, 0, 0); PG8_STAGE(PG8_SA(1, 1), a1 + hstep, voffA);
;             PG8_WAIT_V(8); PG8_WAIT_L(0); PG8_BAR; PG8_MMA(0, 0, At, B0); PG8_MMA(0, 1, At, B1); PG8_BAR; PG8_SCHED;
;             PG8_LDA(At, 0, 1); PG8_STAGE(PG8_SB(0, 0), b2, voffB); PG8_STAGE(PG8_SB(0, 1), b2 + hstep, voffB); PG8_STAGE(PG8_SA(0, 0), a2, voffA);
;             PG8_WAIT_V(8); PG8_WAIT_L(0); PG8_BAR; PG8_MMA(1, 0, At, B0); PG8_MMA(1, 1, At, B1); PG8_BAR; PG8_SCHED;
.Lp1_kloop:
	s_cmp_eq_u32 s80, 15
	s_cselect_b32 s72, s19, s72
	s_cselect_b32 s73, s3, s73
	s_cselect_b32 s76, s25, s76
	s_cselect_b32 s77, s17, s77
	s_add_u32 s74, s72, 0x80000
	s_addc_u32 s75, s73, 0
	s_add_u32 s78, s76, 0x80000
	s_addc_u32 s79, s77, 0
	v_mfma_f32_16x16x32_bf16 v[124:127], v[128:131], v[192:195], v[124:127]
	ds_read_b128 v[174:177], v162 offset:16384
	v_mfma_f32_16x16x32_bf16 v[120:123], v[166:169], v[192:195], v[120:123]
	ds_read_b128 v[178:181], v162 offset:17408
	v_mfma_f32_16x16x32_bf16 v[108:111], v[128:131], v[200:203], v[108:111]
	ds_read_b128 v[182:185], v162 offset:18432
	v_mfma_f32_16x16x32_bf16 v[104:107], v[166:169], v[200:203], v[104:107]
	ds_read_b128 v[188:191], v162 offset:19456
	v_mfma_f32_16x16x32_bf16 v[92:95], v[128:131], v[208:211], v[92:95]
	s_mov_b32 m0, s33
	v_mfma_f32_16x16x32_bf16 v[88:91], v[166:169], v[208:211], v[88:91]
	global_load_lds_dwordx4 v138, s[72:73]
	v_mfma_f32_16x16x32_bf16 v[76:79], v[128:131], v[216:219], v[76:79]
	ds_read_b128 v[224:227], v164 offset:16384
	v_mfma_f32_16x16x32_bf16 v[72:75], v[166:169], v[216:219], v[72:75]
	ds_read_b128 v[228:231], v164 offset:17408
	v_mfma_f32_16x16x32_bf16 v[124:127], v[132:135], v[196:199], v[124:127]
	ds_read_b128 v[232:235], v164 offset:18432
	v_mfma_f32_16x16x32_bf16 v[120:123], v[170:173], v[196:199], v[120:123]
	ds_read_b128 v[236:239], v164 offset:19456
	v_mfma_f32_16x16x32_bf16 v[108:111], v[132:135], v[204:207], v[108:111]
	s_add_i32 m0, s33, 0x2000
	v_mfma_f32_16x16x32_bf16 v[104:107], v[170:173], v[204:207], v[104:107]
	global_load_lds_dwordx4 v142, s[72:73]
	v_mfma_f32_16x16x32_bf16 v[92:95], v[132:135], v[212:215], v[92:95]
	ds_read_b128 v[240:243], v164 offset:20480
	v_mfma_f32_16x16x32_bf16 v[88:91], v[170:173], v[212:215], v[88:91]
	ds_read_b128 v[244:247], v164 offset:21504
	v_mfma_f32_16x16x32_bf16 v[76:79], v[132:135], v[220:223], v[76:79]
	ds_read_b128 v[250:253], v164 offset:22528
	v_mfma_f32_16x16x32_bf16 v[72:75], v[170:173], v[220:223], v[72:75]
	ds_read_b128 v[150:153], v164 offset:23552
	s_waitcnt lgkmcnt(8)
	v_mfma_f32_16x16x32_bf16 v[116:119], v[174:177], v[192:195], v[116:119]
	s_add_i32 m0, s33, 0x10000
	v_mfma_f32_16x16x32_bf16 v[112:115], v[182:185], v[192:195], v[112:115]
	global_load_lds_dwordx4 v140, s[76:77]
	v_mfma_f32_16x16x32_bf16 v[100:103], v[174:177], v[200:203], v[100:103]
	v_mfma_f32_16x16x32_bf16 v[96:99], v[182:185], v[200:203], v[96:99]
	v_mfma_f32_16x16x32_bf16 v[84:87], v[174:177], v[208:211], v[84:87]
	s_add_i32 m0, s33, 0x12000
	v_mfma_f32_16x16x32_bf16 v[80:83], v[182:185], v[208:211], v[80:83]
	global_load_lds_dwordx4 v144, s[76:77]
	v_mfma_f32_16x16x32_bf16 v[68:71], v[174:177], v[216:219], v[68:71]
	v_mfma_f32_16x16x32_bf16 v[64:67], v[182:185], v[216:219], v[64:67]
	v_mfma_f32_16x16x32_bf16 v[116:119], v[178:181], v[196:199], v[116:119]
	v_mfma_f32_16x16x32_bf16 v[112:115], v[188:191], v[196:199], v[112:115]
	v_mfma_f32_16x16x32_bf16 v[100:103], v[178:181], v[204:207], v[100:103]
	v_mfma_f32_16x16x32_bf16 v[96:99], v[188:191], v[204:207], v[96:99]
	v_mfma_f32_16x16x32_bf16 v[84:87], v[178:181], v[212:215], v[84:87]
	v_mfma_f32_16x16x32_bf16 v[80:83], v[188:191], v[212:215], v[80:83]
	v_mfma_f32_16x16x32_bf16 v[68:71], v[178:181], v[220:223], v[68:71]
	v_mfma_f32_16x16x32_bf16 v[64:67], v[188:191], v[220:223], v[64:67]
	s_waitcnt vmcnt(8) lgkmcnt(0)
	s_barrier
	v_mfma_f32_16x16x32_bf16 v[60:63], v[128:131], v[224:227], v[60:63]
	ds_read_b128 v[192:195], v164 offset:32768
	v_mfma_f32_16x16x32_bf16 v[56:59], v[166:169], v[224:227], v[56:59]
	ds_read_b128 v[196:199], v164 offset:33792
	v_mfma_f32_16x16x32_bf16 v[44:47], v[128:131], v[232:235], v[44:47]
	ds_read_b128 v[200:203], v164 offset:34816
	v_mfma_f32_16x16x32_bf16 v[40:43], v[166:169], v[232:235], v[40:43]
	ds_read_b128 v[204:207], v164 offset:35840
	v_mfma_f32_16x16x32_bf16 v[28:31], v[128:131], v[240:243], v[28:31]
	ds_read_b128 v[208:211], v164 offset:36864
	v_mfma_f32_16x16x32_bf16 v[24:27], v[166:169], v[240:243], v[24:27]
	ds_read_b128 v[212:215], v164 offset:37888
	v_mfma_f32_16x16x32_bf16 v[12:15], v[128:131], v[250:253], v[12:15]
	ds_read_b128 v[216:219], v164 offset:38912
	v_mfma_f32_16x16x32_bf16 v[8:11], v[166:169], v[250:253], v[8:11]
	ds_read_b128 v[220:223], v164 offset:39936
	v_mfma_f32_16x16x32_bf16 v[60:63], v[132:135], v[228:231], v[60:63]
	s_add_i32 m0, s33, 0x4000
	v_mfma_f32_16x16x32_bf16 v[56:59], v[170:173], v[228:231], v[56:59]
	global_load_lds_dwordx4 v138, s[74:75]
	v_mfma_f32_16x16x32_bf16 v[44:47], v[132:135], v[236:239], v[44:47]
	v_mfma_f32_16x16x32_bf16 v[40:43], v[170:173], v[236:239], v[40:43]
	v_mfma_f32_16x16x32_bf16 v[28:31], v[132:135], v[244:247], v[28:31]
	s_add_i32 m0, s33, 0x6000
	v_mfma_f32_16x16x32_bf16 v[24:27], v[170:173], v[244:247], v[24:27]
	global_load_lds_dwordx4 v142, s[74:75]
	v_mfma_f32_16x16x32_bf16 v[12:15], v[132:135], v[150:153], v[12:15]
	v_mfma_f32_16x16x32_bf16 v[8:11], v[170:173], v[150:153], v[8:11]
	v_mfma_f32_16x16x32_bf16 v[52:55], v[174:177], v[224:227], v[52:55]
	ds_read_b128 v[128:131], v162 offset:32768
	v_mfma_f32_16x16x32_bf16 v[48:51], v[182:185], v[224:227], v[48:51]
	ds_read_b128 v[132:135], v162 offset:33792
	v_mfma_f32_16x16x32_bf16 v[36:39], v[174:177], v[232:235], v[36:39]
	ds_read_b128 v[166:169], v162 offset:34816
	v_mfma_f32_16x16x32_bf16 v[32:35], v[182:185], v[232:235], v[32:35]
	ds_read_b128 v[170:173], v162 offset:35840
	v_mfma_f32_16x16x32_bf16 v[20:23], v[174:177], v[240:243], v[20:23]
	s_add_i32 m0, s33, 0x14000
	v_mfma_f32_16x16x32_bf16 v[16:19], v[182:185], v[240:243], v[16:19]
	global_load_lds_dwordx4 v140, s[78:79]
	v_mfma_f32_16x16x32_bf16 v[4:7], v[174:177], v[250:253], v[4:7]
	v_mfma_f32_16x16x32_bf16 v[0:3], v[182:185], v[250:253], v[0:3]
	v_mfma_f32_16x16x32_bf16 v[52:55], v[178:181], v[228:231], v[52:55]
	s_add_i32 m0, s33, 0x16000
	v_mfma_f32_16x16x32_bf16 v[48:51], v[188:191], v[228:231], v[48:51]
	global_load_lds_dwordx4 v144, s[78:79]
	v_mfma_f32_16x16x32_bf16 v[36:39], v[178:181], v[236:239], v[36:39]
	v_mfma_f32_16x16x32_bf16 v[32:35], v[188:191], v[236:239], v[32:35]
	v_mfma_f32_16x16x32_bf16 v[20:23], v[178:181], v[244:247], v[20:23]
	v_mfma_f32_16x16x32_bf16 v[16:19], v[188:191], v[244:247], v[16:19]
	v_mfma_f32_16x16x32_bf16 v[4:7], v[178:181], v[150:153], v[4:7]
	v_mfma_f32_16x16x32_bf16 v[0:3], v[188:191], v[150:153], v[0:3]
	s_waitcnt vmcnt(8) lgkmcnt(0)
	s_barrier
; #define PG8_STAGE(bufoff, gbase, voff) do { _Pragma("unroll") for (int _i = 0; _i < 2; ++_i) \
;         __builtin_amdgcn_global_load_lds((const unsigned*)((const char*)(gbase) + (voff)[_i]), (LAS unsigned*)(lds + (bufoff) + ldsw + _i * 8192), 16, 0, 0); } while (0)
; #define PG8_LDA(dst, b, h) do { _Pragma("unroll") for (int m = 0; m < 4; ++m) _Pragma("unroll") for (int k = 0; k < 2; ++k) dst[m][k] = *(const LAS bf16x8*)(lds + PG8_SA(b, h) + aoff + m * 2048 + k * 1024); } while (0)
; #define PG8_LDB(dst, b, h) do { _Pragma("unroll") for (int n = 0; n < 2; ++n) _Pragma("unroll") for (int k = 0; k < 2; ++k) dst[n][k] = *(const LAS bf16x8*)(lds + PG8_SB(b, h) + boff + n * 2048 + k * 1024); } while (0)
; #define PG8_MMA(ai, bj, At, Bt) do { __builtin_amdgcn_s_setprio(1); _Pragma("unroll") for (int m = 0; m < 4; ++m) _Pragma("unroll") for (int n = 0; n < 2; ++n) _Pragma("unroll") for (int k = 0; k < 2; ++k) \
;         acc[ai][bj][m][n] = __builtin_amdgcn_mfma_f32_16x16x32_bf16(Bt[n][k], At[m][k], acc[ai][bj][m][n], 0, 0, 0); __builtin_amdgcn_s_setprio(0); } while (0)
; #define PG8_WAIT_V(n) asm volatile("s_waitcnt vmcnt(" #n ")" ::: "memory")
; template <class Epi, class Sched, int NSEG, bool ALIGN_EPI = true, bool AFTER_DRAIN = false>
; __device__ __forceinline__ void gemm_phase(LAS unsigned char* lds, const Gemm g, const Sched& S, const Epi& E) {
;     ...
;             PG8_LDB(B0, 0, 0); PG8_LDB(B1, 0, 1); PG8_SCHED; PG8_LDA(At, 0, 0); PG8_STAGE(PG8_SA(1, 1), a1 + hstep, voffA);
;             PG8_WAIT_V(8); PG8_WAIT_L(0); PG8_BAR; PG8_MMA(0, 0, At, B0); PG8_MMA(0, 1, At, B1); PG8_BAR; PG8_SCHED;
;             PG8_LDA(At, 0, 1); PG8_STAGE(PG8_SB(0, 0), b2, voffB); PG8_STAGE(PG8_SB(0, 1), b2 + hstep, voffB); PG8_STAGE(PG8_SA(0, 0), a2, voffA);
;             PG8_WAIT_V(8); PG8_WAIT_L(0); PG8_BAR; PG8_MMA(1, 0, At, B0); PG8_MMA(1, 1, At, B1); PG8_BAR; PG8_SCHED;
;             PG8_LDB(B0, 1, 0); PG8_LDB(B1, 1, 1); PG8_SCHED; PG8_LDA(At, 1, 0); PG8_STAGE(PG8_SA(0, 1), a2 + hstep, voffA);
;             PG8_WAIT_V(8); PG8_WAIT_L(0); PG8_BAR; PG8_MMA(0, 0, At, B0); PG8_MMA(0, 1, At, B1); PG8_BAR; PG8_SCHED;
;             PG8_LDA(At, 1, 1); PG8_STAGE(PG8_SB(1, 0), b3, voffB); PG8_STAGE(PG8_SB(1, 1), b3 + hstep, voffB); PG8_STAGE(PG8_SA(1, 0), a3, voffA);
;             PG8_WAIT_V(8); PG8_WAIT_L(0); PG8_BAR; PG8_MMA(1, 0, At, B0); PG8_MMA(1, 1, At, B1); PG8_BAR; PG8_SCHED;
	v_mfma_f32_16x16x32_bf16 v[124:127], v[128:131], v[192:195], v[124:127]
	ds_read_b128 v[174:177], v162 offset:49152
	s_add_u32 s72, s72, 0x80
	s_addc_u32 s73, s73, 0
	v_mfma_f32_16x16x32_bf16 v[120:123], v[166:169], v[192:195], v[120:123]
	ds_read_b128 v[178:181], v162 offset:50176
	s_add_u32 s76, s76, 0x80
	s_addc_u32 s77, s77, 0
	v_mfma_f32_16x16x32_bf16 v[108:111], v[128:131], v[200:203], v[108:111]
	ds_read_b128 v[182:185], v162 offset:51200
	v_mfma_f32_16x16x32_bf16 v[104:107], v[166:169], v[200:203], v[104:107]
	ds_read_b128 v[188:191], v162 offset:52224
	v_mfma_f32_16x16x32_bf16 v[92:95], v[128:131], v[208:211], v[92:95]
	s_add_i32 m0, s33, 0x8000
	v_mfma_f32_16x16x32_bf16 v[88:91], v[166:169], v[208:211], v[88:91]
	global_load_lds_dwordx4 v138, s[72:73]
	v_mfma_f32_16x16x32_bf16 v[76:79], v[128:131], v[216:219], v[76:79]
	ds_read_b128 v[224:227], v164 offset:49152
	v_mfma_f32_16x16x32_bf16 v[72:75], v[166:169], v[216:219], v[72:75]
	ds_read_b128 v[228:231], v164 offset:50176
	v_mfma_f32_16x16x32_bf16 v[124:127], v[132:135], v[196:199], v[124:127]
	ds_read_b128 v[232:235], v164 offset:51200
	v_mfma_f32_16x16x32_bf16 v[120:123], v[170:173], v[196:199], v[120:123]
	ds_read_b128 v[236:239], v164 offset:52224
	v_mfma_f32_16x16x32_bf16 v[108:111], v[132:135], v[204:207], v[108:111]
	s_add_i32 m0, s33, 0xa000
	v_mfma_f32_16x16x32_bf16 v[104:107], v[170:173], v[204:207], v[104:107]
	global_load_lds_dwordx4 v142, s[72:73]
	v_mfma_f32_16x16x32_bf16 v[92:95], v[132:135], v[212:215], v[92:95]
	ds_read_b128 v[240:243], v164 offset:53248
	v_mfma_f32_16x16x32_bf16 v[88:91], v[170:173], v[212:215], v[88:91]
	ds_read_b128 v[244:247], v164 offset:54272
	v_mfma_f32_16x16x32_bf16 v[76:79], v[132:135], v[220:223], v[76:79]
	ds_read_b128 v[250:253], v164 offset:55296
	v_mfma_f32_16x16x32_bf16 v[72:75], v[170:173], v[220:223], v[72:75]
	ds_read_b128 v[150:153], v164 offset:56320
	s_waitcnt lgkmcnt(8)
	v_mfma_f32_16x16x32_bf16 v[116:119], v[174:177], v[192:195], v[116:119]
	s_add_i32 m0, s33, 0x18000
	v_mfma_f32_16x16x32_bf16 v[112:115], v[182:185], v[192:195], v[112:115]
	global_load_lds_dwordx4 v140, s[76:77]
	v_mfma_f32_16x16x32_bf16 v[100:103], v[174:177], v[200:203], v[100:103]
	v_mfma_f32_16x16x32_bf16 v[96:99], v[182:185], v[200:203], v[96:99]
	v_mfma_f32_16x16x32_bf16 v[84:87], v[174:177], v[208:211], v[84:87]
	s_add_i32 m0, s33, 0x1a000
	v_mfma_f32_16x16x32_bf16 v[80:83], v[182:185], v[208:211], v[80:83]
	global_load_lds_dwordx4 v144, s[76:77]
	v_mfma_f32_16x16x32_bf16 v[68:71], v[174:177], v[216:219], v[68:71]
	v_mfma_f32_16x16x32_bf16 v[64:67], v[182:185], v[216:219], v[64:67]
	v_mfma_f32_16x16x32_bf16 v[116:119], v[178:181], v[196:199], v[116:119]
	s_add_u32 s74, s74, 0x80
	s_addc_u32 s75, s75, 0
	v_mfma_f32_16x16x32_bf16 v[112:115], v[188:191], v[196:199], v[112:115]
	s_add_u32 s78, s78, 0x80
	s_addc_u32 s79, s79, 0
	v_mfma_f32_16x16x32_bf16 v[100:103], v[178:181], v[204:207], v[100:103]
	v_mfma_f32_16x16x32_bf16 v[96:99], v[188:191], v[204:207], v[96:99]
	v_mfma_f32_16x16x32_bf16 v[84:87], v[178:181], v[212:215], v[84:87]
	v_mfma_f32_16x16x32_bf16 v[80:83], v[188:191], v[212:215], v[80:83]
	v_mfma_f32_16x16x32_bf16 v[68:71], v[178:181], v[220:223], v[68:71]
	v_mfma_f32_16x16x32_bf16 v[64:67], v[188:191], v[220:223], v[64:67]
	s_waitcnt vmcnt(8) lgkmcnt(0)
	s_barrier
	v_mfma_f32_16x16x32_bf16 v[60:63], v[128:131], v[224:227], v[60:63]
	ds_read_b128 v[192:195], v164 offset:0
	v_mfma_f32_16x16x32_bf16 v[56:59], v[166:169], v[224:227], v[56:59]
	ds_read_b128 v[196:199], v164 offset:1024
	v_mfma_f32_16x16x32_bf16 v[44:47], v[128:131], v[232:235], v[44:47]
	ds_read_b128 v[200:203], v164 offset:2048
	v_mfma_f32_16x16x32_bf16 v[40:43], v[166:169], v[232:235], v[40:43]
	ds_read_b128 v[204:207], v164 offset:3072
	v_mfma_f32_16x16x32_bf16 v[28:31], v[128:131], v[240:243], v[28:31]
	ds_read_b128 v[208:211], v164 offset:4096
	v_mfma_f32_16x16x32_bf16 v[24:27], v[166:169], v[240:243], v[24:27]
	ds_read_b128 v[212:215], v164 offset:5120
	v_mfma_f32_16x16x32_bf16 v[12:15], v[128:131], v[250:253], v[12:15]
	ds_read_b128 v[216:219], v164 offset:6144
	v_mfma_f32_16x16x32_bf16 v[8:11], v[166:169], v[250:253], v[8:11]
	ds_read_b128 v[220:223], v164 offset:7168
	v_mfma_f32_16x16x32_bf16 v[60:63], v[132:135], v[228:231], v[60:63]
	s_add_i32 m0, s33, 0xc000
	v_mfma_f32_16x16x32_bf16 v[56:59], v[170:173], v[228:231], v[56:59]
	global_load_lds_dwordx4 v138, s[74:75]
	v_mfma_f32_16x16x32_bf16 v[44:47], v[132:135], v[236:239], v[44:47]
	v_mfma_f32_16x16x32_bf16 v[40:43], v[170:173], v[236:239], v[40:43]
	v_mfma_f32_16x16x32_bf16 v[28:31], v[132:135], v[244:247], v[28:31]
	s_add_i32 m0, s33, 0xe000
	v_mfma_f32_16x16x32_bf16 v[24:27], v[170:173], v[244:247], v[24:27]
	global_load_lds_dwordx4 v142, s[74:75]
	v_mfma_f32_16x16x32_bf16 v[12:15], v[132:135], v[150:153], v[12:15]
	v_mfma_f32_16x16x32_bf16 v[8:11], v[170:173], v[150:153], v[8:11]
	v_mfma_f32_16x16x32_bf16 v[52:55], v[174:177], v[224:227], v[52:55]
	ds_read_b128 v[128:131], v162 offset:0
	v_mfma_f32_16x16x32_bf16 v[48:51], v[182:185], v[224:227], v[48:51]
	ds_read_b128 v[132:135], v162 offset:1024
	v_mfma_f32_16x16x32_bf16 v[36:39], v[174:177], v[232:235], v[36:39]
	ds_read_b128 v[166:169], v162 offset:2048
	v_mfma_f32_16x16x32_bf16 v[32:35], v[182:185], v[232:235], v[32:35]
	ds_read_b128 v[170:173], v162 offset:3072
	v_mfma_f32_16x16x32_bf16 v[20:23], v[174:177], v[240:243], v[20:23]
	s_add_i32 m0, s33, 0x1c000
	v_mfma_f32_16x16x32_bf16 v[16:19], v[182:185], v[240:243], v[16:19]
	global_load_lds_dwordx4 v140, s[78:79]
	v_mfma_f32_16x16x32_bf16 v[4:7], v[174:177], v[250:253], v[4:7]
	v_mfma_f32_16x16x32_bf16 v[0:3], v[182:185], v[250:253], v[0:3]
	v_mfma_f32_16x16x32_bf16 v[52:55], v[178:181], v[228:231], v[52:55]
	s_add_i32 m0, s33, 0x1e000
	v_mfma_f32_16x16x32_bf16 v[48:51], v[188:191], v[228:231], v[48:51]
	global_load_lds_dwordx4 v144, s[78:79]
	v_mfma_f32_16x16x32_bf16 v[36:39], v[178:181], v[236:239], v[36:39]
	v_mfma_f32_16x16x32_bf16 v[32:35], v[188:191], v[236:239], v[32:35]
	s_add_u32 s72, s72, 0x80
	s_addc_u32 s73, s73, 0
	v_mfma_f32_16x16x32_bf16 v[20:23], v[178:181], v[244:247], v[20:23]
	s_add_u32 s76, s76, 0x80
	s_addc_u32 s77, s77, 0
	v_mfma_f32_16x16x32_bf16 v[16:19], v[188:191], v[244:247], v[16:19]
	s_add_i32 s80, s80, 1
	v_mfma_f32_16x16x32_bf16 v[4:7], v[178:181], v[150:153], v[4:7]
	v_mfma_f32_16x16x32_bf16 v[0:3], v[188:191], v[150:153], v[0:3]
	s_waitcnt vmcnt(8) lgkmcnt(0)
	s_barrier
	s_cmp_lt_u32 s80, 16
	s_cbranch_scc1 .Lp1_kloop
	s_nop 7
	v_and_b32_e32 v214, 63, v186
	v_lshrrev_b32_e32 v215, 2, v214
	v_and_b32_e32 v214, 3, v214
	v_lshl_add_u32 v214, v214, 4, v215
	v_lshlrev_b32_e32 v214, 2, v214
	s_and_b64 vcc, exec, s[12:13]
	s_cbranch_vccz .LBB0_331
	s_cmp_gt_i32 s2, 31
	s_mov_b64 s[26:27], -1
	s_cbranch_scc1 .LBB0_332

; __device__ __forceinline__ u32x4 pack8(f32x4 v0, f32x4 v1) { u32x4 w; w.x = cvt_pk_bf16(v0[0], v0[1]); w.y = cvt_pk_bf16(v0[2], v0[3]); w.z = cvt_pk_bf16(v1[0], v1[1]); w.w = cvt_pk_bf16(v1[2], v1[3]); return w; }
;     __device__ __forceinline__ void operator()(const Acc& acc, const Unit& u, int wr, int wc, int fr, int fq) const {
;     ...
;                 const size_t o0 = (size_t)(pm * 256 + rloc) * DM + col;
; #pragma unroll
;                 for (int ai = 0; ai < 2; ++ai)
; #pragma unroll
;                     for (int m = 0; m < 4; ++m) { f32x4 r0, r1, s0, s1;
; #pragma unroll
;                         for (int j = 0; j < 4; ++j) { const float e1a = 1.0f + __expf(-acc[ai][0][m][0][j]), e2a = 1.0f + __expf(-acc[ai][1][m][0][j]);
;                             const float e1b = 1.0f + __expf(-acc[ai][0][m][1][j]), e2b = 1.0f + __expf(-acc[ai][1][m][1][j]);
;                             s0[j] = __builtin_amdgcn_rcpf(e2a); s1[j] = __builtin_amdgcn_rcpf(e2b); r0[j] = e2a * __builtin_amdgcn_rcpf(e1a); r1[j] = e2b * __builtin_amdgcn_rcpf(e1b); }
;                         const size_t o = o0 + (size_t)(ai * 128 + m * 16) * DM;
;                         __builtin_nontemporal_store(pack8(r0, r1), (u32x4*)(R + o)); __builtin_nontemporal_store(pack8(s0, s1), (u32x4*)(S2 + o)); }
.LBB0_332:
	s_lshl_b32 s17, s2, 7
	s_sub_i32 s3, s2, 32
	s_and_b32 s17, s17, 0x780
	v_or_b32_e32 v158, s17, v148
	s_cmp_gt_u32 s3, 15
	s_cbranch_scc0 .LBB0_338
	v_lshl_add_u32 v128, s24, 8, v137
	s_and_b32 s3, s3, -16
	v_ashrrev_i32_e32 v129, 31, v128
	s_cmp_lg_u32 s3, 16
	v_lshlrev_b64 v[128:129], 12, v[128:129]
	s_cbranch_scc0 .LBB0_335
	v_mul_f32_e32 v130, 0xbfb8aa3b, v124
	v_mul_f32_e32 v132, 0xbfb8aa3b, v120
	v_exp_f32_e32 v130, v130
	v_exp_f32_e32 v132, v132
	v_mul_f32_e32 v131, 0xbfb8aa3b, v116
	v_mul_f32_e32 v133, 0xbfb8aa3b, v112
	v_exp_f32_e32 v131, v131
	v_exp_f32_e32 v133, v133
	v_add_f32_e32 v130, 1.0, v130
	v_add_f32_e32 v132, 1.0, v132
	v_rcp_f32_e32 v130, v130
	v_rcp_f32_e32 v132, v132
	v_add_f32_e32 v131, 1.0, v131
	v_add_f32_e32 v133, 1.0, v133
	v_rcp_f32_e32 v146, v131
	v_mul_f32_e32 v130, v130, v131
	v_mul_f32_e32 v131, v132, v133
	v_mul_f32_e32 v132, 0xbfb8aa3b, v125
	v_mul_f32_e32 v134, 0xbfb8aa3b, v121
	v_exp_f32_e32 v132, v132
	v_exp_f32_e32 v134, v134
	v_rcp_f32_e32 v159, v133
	v_mul_f32_e32 v133, 0xbfb8aa3b, v117
	v_mul_f32_e32 v135, 0xbfb8aa3b, v113
	v_exp_f32_e32 v133, v133
	v_exp_f32_e32 v135, v135
	v_add_f32_e32 v132, 1.0, v132
	v_add_f32_e32 v134, 1.0, v134
	v_rcp_f32_e32 v132, v132
	v_rcp_f32_e32 v134, v134
	v_add_f32_e32 v133, 1.0, v133
	v_add_f32_e32 v135, 1.0, v135
	v_rcp_f32_e32 v170, v133
	v_mul_f32_e32 v132, v132, v133
	v_mul_f32_e32 v133, v134, v135
	v_mul_f32_e32 v134, 0xbfb8aa3b, v126
	v_mul_f32_e32 v166, 0xbfb8aa3b, v122
	v_exp_f32_e32 v134, v134
	v_exp_f32_e32 v166, v166
	v_rcp_f32_e32 v171, v135
	v_mul_f32_e32 v135, 0xbfb8aa3b, v118
	v_mul_f32_e32 v167, 0xbfb8aa3b, v114
	v_exp_f32_e32 v135, v135
	v_exp_f32_e32 v167, v167
	v_add_f32_e32 v134, 1.0, v134
	v_add_f32_e32 v166, 1.0, v166
	v_rcp_f32_e32 v134, v134
	v_rcp_f32_e32 v166, v166
	v_add_f32_e32 v135, 1.0, v135
	v_add_f32_e32 v167, 1.0, v167
	v_rcp_f32_e32 v172, v135
	v_mul_f32_e32 v134, v134, v135
	v_mul_f32_e32 v135, v166, v167
	v_mul_f32_e32 v166, 0xbfb8aa3b, v127
	v_mul_f32_e32 v168, 0xbfb8aa3b, v123
	v_exp_f32_e32 v166, v166
	v_exp_f32_e32 v168, v168
	v_rcp_f32_e32 v173, v167
	v_mul_f32_e32 v167, 0xbfb8aa3b, v119
	v_mul_f32_e32 v169, 0xbfb8aa3b, v115
	v_exp_f32_e32 v167, v167
	v_exp_f32_e32 v169, v169
	v_add_f32_e32 v166, 1.0, v166
	v_add_f32_e32 v168, 1.0, v168
	v_rcp_f32_e32 v166, v166
	v_rcp_f32_e32 v168, v168
	v_add_f32_e32 v167, 1.0, v167
	v_add_f32_e32 v169, 1.0, v169
	v_rcp_f32_e32 v174, v167
	v_rcp_f32_e32 v175, v169
	v_mul_f32_e32 v167, v166, v167
	v_mul_f32_e32 v169, v168, v169
	v_readlane_b32 s26, v248, 48
	v_cvt_pk_bf16_f32 v166, v130, v132
	v_cvt_pk_bf16_f32 v167, v134, v167
	v_cvt_pk_bf16_f32 v168, v131, v133
	v_cvt_pk_bf16_f32 v169, v135, v169
	v_lshl_or_b32 v134, v158, 1, v128
	v_mov_b32_e32 v135, v129
	v_readlane_b32 s27, v248, 49
	v_readlane_b32 s28, v248, 50
	v_readlane_b32 s29, v248, 51
	v_lshl_add_u64 v[132:133], s[26:27], 0, v[134:135]
	ds_bpermute_b32 v200, v214, v166
	ds_bpermute_b32 v201, v214, v167
	ds_bpermute_b32 v202, v214, v168
	ds_bpermute_b32 v203, v214, v169
	ds_bpermute_b32 v204, v214, v132
	ds_bpermute_b32 v205, v214, v133
	v_lshl_add_u64 v[130:131], s[28:29], 0, v[134:135]
	v_mul_f32_e32 v135, 0xbfb8aa3b, v108
	v_cvt_pk_bf16_f32 v166, v146, v170
	v_cvt_pk_bf16_f32 v167, v172, v174
	v_cvt_pk_bf16_f32 v168, v159, v171
	v_mul_f32_e32 v159, 0xbfb8aa3b, v104
	v_exp_f32_e32 v135, v135
	v_exp_f32_e32 v159, v159
	v_cvt_pk_bf16_f32 v169, v173, v175
	ds_bpermute_b32 v208, v214, v166
	ds_bpermute_b32 v209, v214, v167
	ds_bpermute_b32 v210, v214, v168
	ds_bpermute_b32 v211, v214, v169
	ds_bpermute_b32 v212, v214, v130
	ds_bpermute_b32 v213, v214, v131
	s_waitcnt lgkmcnt(6)
	global_store_dwordx4 v[204:205], v[200:203], off nt
	v_mul_f32_e32 v146, 0xbfb8aa3b, v100
	v_exp_f32_e32 v146, v146
	v_mul_f32_e32 v166, 0xbfb8aa3b, v96
	v_exp_f32_e32 v166, v166
	v_add_f32_e32 v135, 1.0, v135
	v_add_f32_e32 v159, 1.0, v159
	v_rcp_f32_e32 v135, v135
	v_rcp_f32_e32 v159, v159
	v_add_f32_e32 v146, 1.0, v146
	v_add_f32_e32 v166, 1.0, v166
	v_rcp_f32_e32 v174, v146
	v_mul_f32_e32 v135, v135, v146
	v_mul_f32_e32 v146, v159, v166
	v_mul_f32_e32 v159, 0xbfb8aa3b, v109
	v_exp_f32_e32 v159, v159
	v_rcp_f32_e32 v175, v166
	v_mul_f32_e32 v166, 0xbfb8aa3b, v101
	v_mul_f32_e32 v167, 0xbfb8aa3b, v105
	v_exp_f32_e32 v166, v166
	v_exp_f32_e32 v167, v167
	v_add_f32_e32 v159, 1.0, v159
	v_rcp_f32_e32 v159, v159
	v_mul_f32_e32 v168, 0xbfb8aa3b, v97
	v_exp_f32_e32 v168, v168
	v_add_f32_e32 v166, 1.0, v166
	v_add_f32_e32 v167, 1.0, v167
	v_rcp_f32_e32 v167, v167
	v_rcp_f32_e32 v176, v166
	v_mul_f32_e32 v159, v159, v166
	v_mul_f32_e32 v166, 0xbfb8aa3b, v110
	v_exp_f32_e32 v166, v166
	v_add_f32_e32 v168, 1.0, v168
	v_rcp_f32_e32 v177, v168
	v_mul_f32_e32 v168, v167, v168
	v_mul_f32_e32 v167, 0xbfb8aa3b, v102
	v_mul_f32_e32 v169, 0xbfb8aa3b, v106
	v_exp_f32_e32 v167, v167
	v_exp_f32_e32 v169, v169
	v_add_f32_e32 v166, 1.0, v166
	v_rcp_f32_e32 v166, v166
	v_mul_f32_e32 v170, 0xbfb8aa3b, v98
	v_exp_f32_e32 v170, v170
	v_add_f32_e32 v167, 1.0, v167
	v_add_f32_e32 v169, 1.0, v169
	v_rcp_f32_e32 v169, v169
	v_rcp_f32_e32 v178, v167
	v_mul_f32_e32 v167, v166, v167
	v_mul_f32_e32 v166, 0xbfb8aa3b, v111
	v_mul_f32_e32 v171, 0xbfb8aa3b, v107
	v_exp_f32_e32 v166, v166
	v_exp_f32_e32 v171, v171
	v_add_f32_e32 v170, 1.0, v170
	v_rcp_f32_e32 v179, v170
	v_mul_f32_e32 v169, v169, v170
	v_mul_f32_e32 v170, 0xbfb8aa3b, v103
	v_mul_f32_e32 v172, 0xbfb8aa3b, v99
	v_exp_f32_e32 v170, v170
	v_exp_f32_e32 v172, v172
	v_add_f32_e32 v166, 1.0, v166
	v_add_f32_e32 v171, 1.0, v171
	v_rcp_f32_e32 v166, v166
	v_rcp_f32_e32 v171, v171
	v_add_f32_e32 v170, 1.0, v170
	v_add_f32_e32 v172, 1.0, v172
	v_rcp_f32_e32 v180, v170
	v_mul_f32_e32 v170, v166, v170
	v_mul_f32_e32 v171, v171, v172
	v_cvt_pk_bf16_f32 v166, v135, v159
	v_mul_f32_e32 v135, 0xbfb8aa3b, v92
	v_mul_f32_e32 v159, 0xbfb8aa3b, v88
	v_cvt_pk_bf16_f32 v167, v167, v170
	v_cvt_pk_bf16_f32 v168, v146, v168
	v_cvt_pk_bf16_f32 v169, v169, v171
	v_or_b32_e32 v170, 0x10000, v134
	v_mov_b32_e32 v171, v129
	v_exp_f32_e32 v135, v135
	v_exp_f32_e32 v159, v159
	v_rcp_f32_e32 v181, v172
	v_lshl_add_u64 v[172:173], s[26:27], 0, v[170:171]
	ds_bpermute_b32 v200, v214, v166
	ds_bpermute_b32 v201, v214, v167
	ds_bpermute_b32 v202, v214, v168
	ds_bpermute_b32 v203, v214, v169
	ds_bpermute_b32 v204, v214, v172
	ds_bpermute_b32 v205, v214, v173
	s_waitcnt lgkmcnt(6)
; __device__ __forceinline__ u32x4 pack8(f32x4 v0, f32x4 v1) { u32x4 w; w.x = cvt_pk_bf16(v0[0], v0[1]); w.y = cvt_pk_bf16(v0[2], v0[3]); w.z = cvt_pk_bf16(v1[0], v1[1]); w.w = cvt_pk_bf16(v1[2], v1[3]); return w; }
;     __device__ __forceinline__ void operator()(const Acc& acc, const Unit& u, int wr, int wc, int fr, int fq) const {
;     ...
;                 const size_t o0 = (size_t)(pm * 256 + rloc) * DM + col;
; #pragma unroll
;                 for (int ai = 0; ai < 2; ++ai)
; #pragma unroll
;                     for (int m = 0; m < 4; ++m) { f32x4 r0, r1, s0, s1;
; #pragma unroll
;                         for (int j = 0; j < 4; ++j) { const float e1a = 1.0f + __expf(-acc[ai][0][m][0][j]), e2a = 1.0f + __expf(-acc[ai][1][m][0][j]);
;                             const float e1b = 1.0f + __expf(-acc[ai][0][m][1][j]), e2b = 1.0f + __expf(-acc[ai][1][m][1][j]);
;                             s0[j] = __builtin_amdgcn_rcpf(e2a); s1[j] = __builtin_amdgcn_rcpf(e2b); r0[j] = e2a * __builtin_amdgcn_rcpf(e1a); r1[j] = e2b * __builtin_amdgcn_rcpf(e1b); }
;                         const size_t o = o0 + (size_t)(ai * 128 + m * 16) * DM;
;                         __builtin_nontemporal_store(pack8(r0, r1), (u32x4*)(R + o)); __builtin_nontemporal_store(pack8(s0, s1), (u32x4*)(S2 + o)); }
	global_store_dwordx4 v[212:213], v[208:211], off nt
	v_lshl_add_u64 v[170:171], s[28:29], 0, v[170:171]
	v_mul_f32_e32 v146, 0xbfb8aa3b, v84
	v_cvt_pk_bf16_f32 v166, v174, v176
	v_cvt_pk_bf16_f32 v167, v178, v180
	v_cvt_pk_bf16_f32 v168, v175, v177
	v_cvt_pk_bf16_f32 v169, v179, v181
	ds_bpermute_b32 v208, v214, v166
	ds_bpermute_b32 v209, v214, v167
	ds_bpermute_b32 v210, v214, v168
	ds_bpermute_b32 v211, v214, v169
	ds_bpermute_b32 v212, v214, v170
	ds_bpermute_b32 v213, v214, v171
	s_waitcnt lgkmcnt(6)
	global_store_dwordx4 v[204:205], v[200:203], off nt
	v_exp_f32_e32 v146, v146
	v_add_f32_e32 v135, 1.0, v135
	v_mul_f32_e32 v166, 0xbfb8aa3b, v80
	v_exp_f32_e32 v166, v166
	v_add_f32_e32 v159, 1.0, v159
	v_rcp_f32_e32 v135, v135
	v_rcp_f32_e32 v159, v159
	v_add_f32_e32 v146, 1.0, v146
	v_add_f32_e32 v166, 1.0, v166
	v_rcp_f32_e32 v174, v146
	v_mul_f32_e32 v135, v135, v146
	v_mul_f32_e32 v146, v159, v166
	v_mul_f32_e32 v159, 0xbfb8aa3b, v93
	v_exp_f32_e32 v159, v159
	v_rcp_f32_e32 v175, v166
	v_mul_f32_e32 v166, 0xbfb8aa3b, v85
	v_mul_f32_e32 v167, 0xbfb8aa3b, v89
	v_exp_f32_e32 v166, v166
	v_exp_f32_e32 v167, v167
	v_add_f32_e32 v159, 1.0, v159
	v_rcp_f32_e32 v159, v159
	v_mul_f32_e32 v168, 0xbfb8aa3b, v81
	v_exp_f32_e32 v168, v168
	v_add_f32_e32 v166, 1.0, v166
	v_add_f32_e32 v167, 1.0, v167
	v_rcp_f32_e32 v167, v167
	v_rcp_f32_e32 v176, v166
	v_mul_f32_e32 v159, v159, v166
	v_mul_f32_e32 v166, 0xbfb8aa3b, v94
	v_exp_f32_e32 v166, v166
	v_add_f32_e32 v168, 1.0, v168
	v_rcp_f32_e32 v177, v168
	v_mul_f32_e32 v168, v167, v168
	v_mul_f32_e32 v167, 0xbfb8aa3b, v86
	v_mul_f32_e32 v169, 0xbfb8aa3b, v90
	v_exp_f32_e32 v167, v167
	v_exp_f32_e32 v169, v169
	v_add_f32_e32 v166, 1.0, v166
	v_rcp_f32_e32 v166, v166
	v_mul_f32_e32 v170, 0xbfb8aa3b, v82
	v_exp_f32_e32 v170, v170
	v_add_f32_e32 v167, 1.0, v167
	v_add_f32_e32 v169, 1.0, v169
	v_rcp_f32_e32 v169, v169
	v_rcp_f32_e32 v178, v167
	v_mul_f32_e32 v167, v166, v167
	v_mul_f32_e32 v166, 0xbfb8aa3b, v95
	v_mul_f32_e32 v171, 0xbfb8aa3b, v91
	v_exp_f32_e32 v166, v166
	v_exp_f32_e32 v171, v171
	v_add_f32_e32 v170, 1.0, v170
	v_rcp_f32_e32 v179, v170
	v_mul_f32_e32 v169, v169, v170
	v_mul_f32_e32 v170, 0xbfb8aa3b, v87
	v_mul_f32_e32 v172, 0xbfb8aa3b, v83
	v_exp_f32_e32 v170, v170
	v_exp_f32_e32 v172, v172
	v_add_f32_e32 v166, 1.0, v166
	v_add_f32_e32 v171, 1.0, v171
	v_rcp_f32_e32 v166, v166
	v_rcp_f32_e32 v171, v171
	v_add_f32_e32 v170, 1.0, v170
	v_add_f32_e32 v172, 1.0, v172
	v_rcp_f32_e32 v180, v170
	v_mul_f32_e32 v170, v166, v170
	v_mul_f32_e32 v171, v171, v172
	v_cvt_pk_bf16_f32 v166, v135, v159
	v_mul_f32_e32 v135, 0xbfb8aa3b, v76
	v_mul_f32_e32 v159, 0xbfb8aa3b, v72
	v_cvt_pk_bf16_f32 v167, v167, v170
	v_cvt_pk_bf16_f32 v168, v146, v168
	v_cvt_pk_bf16_f32 v169, v169, v171
	v_or_b32_e32 v170, 0x20000, v134
	v_mov_b32_e32 v171, v129
	v_exp_f32_e32 v135, v135
	v_exp_f32_e32 v159, v159
	v_rcp_f32_e32 v181, v172
	v_lshl_add_u64 v[172:173], s[26:27], 0, v[170:171]
	ds_bpermute_b32 v200, v214, v166
	ds_bpermute_b32 v201, v214, v167
	ds_bpermute_b32 v202, v214, v168
	ds_bpermute_b32 v203, v214, v169
	ds_bpermute_b32 v204, v214, v172
	ds_bpermute_b32 v205, v214, v173
	s_waitcnt lgkmcnt(6)
	global_store_dwordx4 v[212:213], v[208:211], off nt
	v_lshl_add_u64 v[170:171], s[28:29], 0, v[170:171]
	v_mul_f32_e32 v146, 0xbfb8aa3b, v68
	v_cvt_pk_bf16_f32 v166, v174, v176
	v_cvt_pk_bf16_f32 v167, v178, v180
	v_cvt_pk_bf16_f32 v168, v175, v177
	v_cvt_pk_bf16_f32 v169, v179, v181
	ds_bpermute_b32 v208, v214, v166
	ds_bpermute_b32 v209, v214, v167
	ds_bpermute_b32 v210, v214, v168
	ds_bpermute_b32 v211, v214, v169
	ds_bpermute_b32 v212, v214, v170
	ds_bpermute_b32 v213, v214, v171
	s_waitcnt lgkmcnt(6)
	global_store_dwordx4 v[204:205], v[200:203], off nt
	v_exp_f32_e32 v146, v146
	v_add_f32_e32 v135, 1.0, v135
	v_mul_f32_e32 v166, 0xbfb8aa3b, v64
	v_exp_f32_e32 v166, v166
	v_add_f32_e32 v159, 1.0, v159
	v_rcp_f32_e32 v135, v135
	v_rcp_f32_e32 v159, v159
	v_add_f32_e32 v146, 1.0, v146
	v_add_f32_e32 v166, 1.0, v166
	v_rcp_f32_e32 v172, v146
	v_mul_f32_e32 v135, v135, v146
	v_mul_f32_e32 v146, v159, v166
	v_mul_f32_e32 v159, 0xbfb8aa3b, v77
	v_exp_f32_e32 v159, v159
	v_rcp_f32_e32 v173, v166
	v_mul_f32_e32 v166, 0xbfb8aa3b, v69
	v_mul_f32_e32 v167, 0xbfb8aa3b, v73
	v_exp_f32_e32 v166, v166
	v_exp_f32_e32 v167, v167
	v_add_f32_e32 v159, 1.0, v159
	v_rcp_f32_e32 v159, v159
	v_mul_f32_e32 v168, 0xbfb8aa3b, v65
	v_exp_f32_e32 v168, v168
	v_add_f32_e32 v166, 1.0, v166
	v_add_f32_e32 v167, 1.0, v167
	v_rcp_f32_e32 v167, v167
	v_rcp_f32_e32 v174, v166
	v_mul_f32_e32 v159, v159, v166
	v_mul_f32_e32 v166, 0xbfb8aa3b, v78
	v_exp_f32_e32 v166, v166
	v_add_f32_e32 v168, 1.0, v168
	v_rcp_f32_e32 v175, v168
	v_mul_f32_e32 v168, v167, v168
	v_mul_f32_e32 v167, 0xbfb8aa3b, v70
	v_mul_f32_e32 v169, 0xbfb8aa3b, v74
	v_exp_f32_e32 v167, v167
	v_exp_f32_e32 v169, v169
	v_add_f32_e32 v166, 1.0, v166
	v_rcp_f32_e32 v166, v166
	v_mul_f32_e32 v170, 0xbfb8aa3b, v66
	v_exp_f32_e32 v170, v170
	v_add_f32_e32 v167, 1.0, v167
	v_add_f32_e32 v169, 1.0, v169
	v_rcp_f32_e32 v169, v169
	v_rcp_f32_e32 v176, v167
	v_mul_f32_e32 v167, v166, v167
	v_mul_f32_e32 v166, 0xbfb8aa3b, v79
	v_mul_f32_e32 v171, 0xbfb8aa3b, v75
	v_exp_f32_e32 v166, v166
	v_exp_f32_e32 v171, v171
	v_add_f32_e32 v170, 1.0, v170
	v_rcp_f32_e32 v177, v170
	v_mul_f32_e32 v169, v169, v170
	v_mul_f32_e32 v170, 0xbfb8aa3b, v71
	v_mul_f32_e32 v178, 0xbfb8aa3b, v67
	v_exp_f32_e32 v170, v170
	v_exp_f32_e32 v178, v178
	v_add_f32_e32 v166, 1.0, v166
	v_add_f32_e32 v171, 1.0, v171
	v_rcp_f32_e32 v166, v166
	v_rcp_f32_e32 v171, v171
	v_add_f32_e32 v170, 1.0, v170
	v_add_f32_e32 v178, 1.0, v178
	v_rcp_f32_e32 v179, v170
	v_mul_f32_e32 v170, v166, v170
	v_mul_f32_e32 v171, v171, v178
	v_cvt_pk_bf16_f32 v166, v135, v159
	v_or_b32_e32 v134, 0x30000, v134
	v_mov_b32_e32 v135, v129
	v_cvt_pk_bf16_f32 v167, v167, v170
	v_cvt_pk_bf16_f32 v168, v146, v168
	v_cvt_pk_bf16_f32 v169, v169, v171
	v_lshl_add_u64 v[170:171], s[26:27], 0, v[134:135]
	v_lshl_add_u64 v[134:135], s[28:29], 0, v[134:135]
	v_rcp_f32_e32 v180, v178
	ds_bpermute_b32 v200, v214, v166
	ds_bpermute_b32 v201, v214, v167
	ds_bpermute_b32 v202, v214, v168
	ds_bpermute_b32 v203, v214, v169
	ds_bpermute_b32 v204, v214, v170
	ds_bpermute_b32 v205, v214, v171
	s_waitcnt lgkmcnt(6)
; __device__ __forceinline__ u32x4 pack8(f32x4 v0, f32x4 v1) { u32x4 w; w.x = cvt_pk_bf16(v0[0], v0[1]); w.y = cvt_pk_bf16(v0[2], v0[3]); w.z = cvt_pk_bf16(v1[0], v1[1]); w.w = cvt_pk_bf16(v1[2], v1[3]); return w; }
;     __device__ __forceinline__ void operator()(const Acc& acc, const Unit& u, int wr, int wc, int fr, int fq) const {
;     ...
;                 const size_t o0 = (size_t)(pm * 256 + rloc) * DM + col;
; #pragma unroll
;                 for (int ai = 0; ai < 2; ++ai)
; #pragma unroll
;                     for (int m = 0; m < 4; ++m) { f32x4 r0, r1, s0, s1;
; #pragma unroll
;                         for (int j = 0; j < 4; ++j) { const float e1a = 1.0f + __expf(-acc[ai][0][m][0][j]), e2a = 1.0f + __expf(-acc[ai][1][m][0][j]);
;                             const float e1b = 1.0f + __expf(-acc[ai][0][m][1][j]), e2b = 1.0f + __expf(-acc[ai][1][m][1][j]);
;                             s0[j] = __builtin_amdgcn_rcpf(e2a); s1[j] = __builtin_amdgcn_rcpf(e2b); r0[j] = e2a * __builtin_amdgcn_rcpf(e1a); r1[j] = e2b * __builtin_amdgcn_rcpf(e1b); }
;                         const size_t o = o0 + (size_t)(ai * 128 + m * 16) * DM;
;                         __builtin_nontemporal_store(pack8(r0, r1), (u32x4*)(R + o)); __builtin_nontemporal_store(pack8(s0, s1), (u32x4*)(S2 + o)); }
	global_store_dwordx4 v[212:213], v[208:211], off nt
	v_mul_f32_e32 v146, 0xbfb8aa3b, v56
	v_exp_f32_e32 v146, v146
	v_cvt_pk_bf16_f32 v166, v172, v174
	v_cvt_pk_bf16_f32 v167, v176, v179
	v_cvt_pk_bf16_f32 v168, v173, v175
	v_cvt_pk_bf16_f32 v169, v177, v180
	ds_bpermute_b32 v208, v214, v166
	ds_bpermute_b32 v209, v214, v167
	ds_bpermute_b32 v210, v214, v168
	ds_bpermute_b32 v211, v214, v169
	ds_bpermute_b32 v212, v214, v134
	ds_bpermute_b32 v213, v214, v135
	s_waitcnt lgkmcnt(6)
	global_store_dwordx4 v[204:205], v[200:203], off nt
	v_mul_f32_e32 v134, 0xbfb8aa3b, v60
	v_exp_f32_e32 v134, v134
	v_mul_f32_e32 v135, 0xbfb8aa3b, v52
	v_mul_f32_e32 v159, 0xbfb8aa3b, v48
	v_exp_f32_e32 v135, v135
	v_exp_f32_e32 v159, v159
	v_add_f32_e32 v134, 1.0, v134
	v_add_f32_e32 v146, 1.0, v146
	v_rcp_f32_e32 v134, v134
	v_rcp_f32_e32 v146, v146
	v_add_f32_e32 v135, 1.0, v135
	v_add_f32_e32 v159, 1.0, v159
	v_rcp_f32_e32 v170, v135
	v_mul_f32_e32 v134, v134, v135
	v_mul_f32_e32 v135, v146, v159
	v_mul_f32_e32 v146, 0xbfb8aa3b, v61
	v_mul_f32_e32 v166, 0xbfb8aa3b, v57
	v_exp_f32_e32 v146, v146
	v_exp_f32_e32 v166, v166
	v_rcp_f32_e32 v171, v159
	v_mul_f32_e32 v159, 0xbfb8aa3b, v53
	v_mul_f32_e32 v167, 0xbfb8aa3b, v49
	v_exp_f32_e32 v159, v159
	v_exp_f32_e32 v167, v167
	v_add_f32_e32 v146, 1.0, v146
	v_add_f32_e32 v166, 1.0, v166
	v_rcp_f32_e32 v146, v146
	v_rcp_f32_e32 v166, v166
	v_add_f32_e32 v159, 1.0, v159
	v_add_f32_e32 v167, 1.0, v167
	v_rcp_f32_e32 v172, v159
	v_mul_f32_e32 v146, v146, v159
	v_mul_f32_e32 v159, v166, v167
	v_mul_f32_e32 v166, 0xbfb8aa3b, v62
	v_exp_f32_e32 v166, v166
	v_rcp_f32_e32 v173, v167
	v_mul_f32_e32 v167, 0xbfb8aa3b, v54
	v_mul_f32_e32 v168, 0xbfb8aa3b, v58
	v_exp_f32_e32 v167, v167
	v_exp_f32_e32 v168, v168
	v_add_f32_e32 v166, 1.0, v166
	v_rcp_f32_e32 v166, v166
	v_mul_f32_e32 v169, 0xbfb8aa3b, v50
	v_exp_f32_e32 v169, v169
	v_add_f32_e32 v167, 1.0, v167
	v_add_f32_e32 v168, 1.0, v168
	v_rcp_f32_e32 v168, v168
	v_rcp_f32_e32 v174, v167
	v_mul_f32_e32 v167, v166, v167
	v_mul_f32_e32 v166, 0xbfb8aa3b, v63
	v_exp_f32_e32 v166, v166
	v_mul_f32_e32 v176, 0xbfb8aa3b, v59
	v_add_f32_e32 v169, 1.0, v169
	v_exp_f32_e32 v176, v176
	v_rcp_f32_e32 v175, v169
	v_mul_f32_e32 v169, v168, v169
	v_mul_f32_e32 v168, 0xbfb8aa3b, v55
	v_exp_f32_e32 v168, v168
	v_add_f32_e32 v166, 1.0, v166
	v_mul_f32_e32 v177, 0xbfb8aa3b, v51
	v_rcp_f32_e32 v166, v166
	v_exp_f32_e32 v177, v177
	v_add_f32_e32 v176, 1.0, v176
	v_rcp_f32_e32 v176, v176
	v_add_f32_e32 v168, 1.0, v168
	v_rcp_f32_e32 v178, v168
	v_mul_f32_e32 v168, v166, v168
	v_cvt_pk_bf16_f32 v166, v134, v146
	v_add_co_u32_e32 v134, vcc, s47, v132
	v_add_f32_e32 v177, 1.0, v177
	v_cvt_pk_bf16_f32 v167, v167, v168
	v_cvt_pk_bf16_f32 v168, v135, v159
	s_nop 0
	v_addc_co_u32_e32 v135, vcc, 0, v133, vcc
	v_mul_f32_e32 v176, v176, v177
	v_cvt_pk_bf16_f32 v169, v169, v176
	ds_bpermute_b32 v200, v214, v166
	ds_bpermute_b32 v201, v214, v167
	ds_bpermute_b32 v202, v214, v168
	ds_bpermute_b32 v203, v214, v169
	ds_bpermute_b32 v204, v214, v134
	ds_bpermute_b32 v205, v214, v135
	s_waitcnt lgkmcnt(6)
	global_store_dwordx4 v[212:213], v[208:211], off nt
	v_add_co_u32_e32 v134, vcc, s47, v130
	v_rcp_f32_e32 v179, v177
	s_nop 0
	v_addc_co_u32_e32 v135, vcc, 0, v131, vcc
	v_cvt_pk_bf16_f32 v166, v170, v172
	v_cvt_pk_bf16_f32 v167, v174, v178
	v_cvt_pk_bf16_f32 v168, v171, v173
	v_cvt_pk_bf16_f32 v169, v175, v179
	ds_bpermute_b32 v208, v214, v166
	ds_bpermute_b32 v209, v214, v167
	ds_bpermute_b32 v210, v214, v168
	ds_bpermute_b32 v211, v214, v169
	ds_bpermute_b32 v212, v214, v134
	ds_bpermute_b32 v213, v214, v135
	s_waitcnt lgkmcnt(6)
	global_store_dwordx4 v[204:205], v[200:203], off nt
	v_mul_f32_e32 v134, 0xbfb8aa3b, v44
	v_mul_f32_e32 v146, 0xbfb8aa3b, v40
	v_exp_f32_e32 v134, v134
	v_exp_f32_e32 v146, v146
	v_mul_f32_e32 v135, 0xbfb8aa3b, v36
	v_mul_f32_e32 v159, 0xbfb8aa3b, v32
	v_exp_f32_e32 v135, v135
	v_exp_f32_e32 v159, v159
	v_add_f32_e32 v134, 1.0, v134
	v_add_f32_e32 v146, 1.0, v146
	v_rcp_f32_e32 v134, v134
	v_rcp_f32_e32 v146, v146
	v_add_f32_e32 v135, 1.0, v135
	v_add_f32_e32 v159, 1.0, v159
	v_rcp_f32_e32 v170, v135
	v_mul_f32_e32 v134, v134, v135
	v_mul_f32_e32 v135, v146, v159
	v_mul_f32_e32 v146, 0xbfb8aa3b, v45
	v_mul_f32_e32 v166, 0xbfb8aa3b, v41
	v_exp_f32_e32 v146, v146
	v_exp_f32_e32 v166, v166
	v_rcp_f32_e32 v171, v159
	v_mul_f32_e32 v159, 0xbfb8aa3b, v37
	v_mul_f32_e32 v167, 0xbfb8aa3b, v33
	v_exp_f32_e32 v159, v159
	v_exp_f32_e32 v167, v167
	v_add_f32_e32 v146, 1.0, v146
	v_add_f32_e32 v166, 1.0, v166
	v_rcp_f32_e32 v146, v146
	v_rcp_f32_e32 v166, v166
	v_add_f32_e32 v159, 1.0, v159
	v_add_f32_e32 v167, 1.0, v167
	v_rcp_f32_e32 v172, v159
	v_mul_f32_e32 v146, v146, v159
	v_mul_f32_e32 v159, v166, v167
	v_mul_f32_e32 v166, 0xbfb8aa3b, v46
	v_exp_f32_e32 v166, v166
	v_rcp_f32_e32 v173, v167
	v_mul_f32_e32 v167, 0xbfb8aa3b, v38
	v_mul_f32_e32 v168, 0xbfb8aa3b, v42
	v_exp_f32_e32 v167, v167
	v_exp_f32_e32 v168, v168
	v_add_f32_e32 v166, 1.0, v166
	v_rcp_f32_e32 v166, v166
	v_mul_f32_e32 v169, 0xbfb8aa3b, v34
	v_exp_f32_e32 v169, v169
	v_add_f32_e32 v167, 1.0, v167
	v_add_f32_e32 v168, 1.0, v168
	v_rcp_f32_e32 v168, v168
	v_rcp_f32_e32 v174, v167
	v_mul_f32_e32 v167, v166, v167
	v_mul_f32_e32 v166, 0xbfb8aa3b, v47
	v_exp_f32_e32 v166, v166
	v_mul_f32_e32 v176, 0xbfb8aa3b, v43
	v_add_f32_e32 v169, 1.0, v169
	v_exp_f32_e32 v176, v176
	v_rcp_f32_e32 v175, v169
	v_mul_f32_e32 v169, v168, v169
	v_mul_f32_e32 v168, 0xbfb8aa3b, v39
	v_exp_f32_e32 v168, v168
	v_add_f32_e32 v166, 1.0, v166
	v_mul_f32_e32 v177, 0xbfb8aa3b, v35
	v_rcp_f32_e32 v166, v166
	v_exp_f32_e32 v177, v177
	v_add_f32_e32 v176, 1.0, v176
	v_rcp_f32_e32 v176, v176
	v_add_f32_e32 v168, 1.0, v168
	v_rcp_f32_e32 v178, v168
	v_mul_f32_e32 v168, v166, v168
	v_cvt_pk_bf16_f32 v166, v134, v146
	v_add_co_u32_e32 v134, vcc, s48, v132
	v_add_f32_e32 v177, 1.0, v177
	v_cvt_pk_bf16_f32 v167, v167, v168
	v_cvt_pk_bf16_f32 v168, v135, v159
	s_nop 0
	v_addc_co_u32_e32 v135, vcc, 0, v133, vcc
	v_mul_f32_e32 v176, v176, v177
	v_cvt_pk_bf16_f32 v169, v169, v176
	ds_bpermute_b32 v200, v214, v166
	ds_bpermute_b32 v201, v214, v167
	ds_bpermute_b32 v202, v214, v168
	ds_bpermute_b32 v203, v214, v169
	ds_bpermute_b32 v204, v214, v134
	ds_bpermute_b32 v205, v214, v135
	s_waitcnt lgkmcnt(6)
; __device__ __forceinline__ u32x4 pack8(f32x4 v0, f32x4 v1) { u32x4 w; w.x = cvt_pk_bf16(v0[0], v0[1]); w.y = cvt_pk_bf16(v0[2], v0[3]); w.z = cvt_pk_bf16(v1[0], v1[1]); w.w = cvt_pk_bf16(v1[2], v1[3]); return w; }
;     __device__ __forceinline__ void operator()(const Acc& acc, const Unit& u, int wr, int wc, int fr, int fq) const {
;     ...
;                 const size_t o0 = (size_t)(pm * 256 + rloc) * DM + col;
; #pragma unroll
;                 for (int ai = 0; ai < 2; ++ai)
; #pragma unroll
;                     for (int m = 0; m < 4; ++m) { f32x4 r0, r1, s0, s1;
; #pragma unroll
;                         for (int j = 0; j < 4; ++j) { const float e1a = 1.0f + __expf(-acc[ai][0][m][0][j]), e2a = 1.0f + __expf(-acc[ai][1][m][0][j]);
;                             const float e1b = 1.0f + __expf(-acc[ai][0][m][1][j]), e2b = 1.0f + __expf(-acc[ai][1][m][1][j]);
;                             s0[j] = __builtin_amdgcn_rcpf(e2a); s1[j] = __builtin_amdgcn_rcpf(e2b); r0[j] = e2a * __builtin_amdgcn_rcpf(e1a); r1[j] = e2b * __builtin_amdgcn_rcpf(e1b); }
;                         const size_t o = o0 + (size_t)(ai * 128 + m * 16) * DM;
;                         __builtin_nontemporal_store(pack8(r0, r1), (u32x4*)(R + o)); __builtin_nontemporal_store(pack8(s0, s1), (u32x4*)(S2 + o)); }
	global_store_dwordx4 v[212:213], v[208:211], off nt
	v_add_co_u32_e32 v134, vcc, s48, v130
	v_rcp_f32_e32 v179, v177
	s_nop 0
	v_addc_co_u32_e32 v135, vcc, 0, v131, vcc
	v_cvt_pk_bf16_f32 v166, v170, v172
	v_cvt_pk_bf16_f32 v167, v174, v178
	v_cvt_pk_bf16_f32 v168, v171, v173
	v_cvt_pk_bf16_f32 v169, v175, v179
	ds_bpermute_b32 v208, v214, v166
	ds_bpermute_b32 v209, v214, v167
	ds_bpermute_b32 v210, v214, v168
	ds_bpermute_b32 v211, v214, v169
	ds_bpermute_b32 v212, v214, v134
	ds_bpermute_b32 v213, v214, v135
	s_waitcnt lgkmcnt(6)
	global_store_dwordx4 v[204:205], v[200:203], off nt
	v_mul_f32_e32 v134, 0xbfb8aa3b, v28
	v_mul_f32_e32 v146, 0xbfb8aa3b, v24
	v_exp_f32_e32 v134, v134
	v_exp_f32_e32 v146, v146
	v_mul_f32_e32 v135, 0xbfb8aa3b, v20
	v_mul_f32_e32 v159, 0xbfb8aa3b, v16
	v_exp_f32_e32 v135, v135
	v_exp_f32_e32 v159, v159
	v_add_f32_e32 v134, 1.0, v134
	v_add_f32_e32 v146, 1.0, v146
	v_rcp_f32_e32 v134, v134
	v_rcp_f32_e32 v146, v146
	v_add_f32_e32 v135, 1.0, v135
	v_add_f32_e32 v159, 1.0, v159
	v_rcp_f32_e32 v170, v135
	v_mul_f32_e32 v134, v134, v135
	v_mul_f32_e32 v135, v146, v159
	v_mul_f32_e32 v146, 0xbfb8aa3b, v29
	v_mul_f32_e32 v166, 0xbfb8aa3b, v25
	v_exp_f32_e32 v146, v146
	v_exp_f32_e32 v166, v166
	v_rcp_f32_e32 v171, v159
	v_mul_f32_e32 v159, 0xbfb8aa3b, v21
	v_mul_f32_e32 v167, 0xbfb8aa3b, v17
	v_exp_f32_e32 v159, v159
	v_exp_f32_e32 v167, v167
	v_add_f32_e32 v146, 1.0, v146
	v_add_f32_e32 v166, 1.0, v166
	v_rcp_f32_e32 v146, v146
	v_rcp_f32_e32 v166, v166
	v_add_f32_e32 v159, 1.0, v159
	v_add_f32_e32 v167, 1.0, v167
	v_rcp_f32_e32 v172, v159
	v_mul_f32_e32 v146, v146, v159
	v_mul_f32_e32 v159, v166, v167
	v_mul_f32_e32 v166, 0xbfb8aa3b, v30
	v_exp_f32_e32 v166, v166
	v_rcp_f32_e32 v173, v167
	v_mul_f32_e32 v167, 0xbfb8aa3b, v22
	v_mul_f32_e32 v168, 0xbfb8aa3b, v26
	v_exp_f32_e32 v167, v167
	v_exp_f32_e32 v168, v168
	v_add_f32_e32 v166, 1.0, v166
	v_rcp_f32_e32 v166, v166
	v_mul_f32_e32 v169, 0xbfb8aa3b, v18
	v_exp_f32_e32 v169, v169
	v_add_f32_e32 v167, 1.0, v167
	v_add_f32_e32 v168, 1.0, v168
	v_rcp_f32_e32 v168, v168
	v_rcp_f32_e32 v174, v167
	v_mul_f32_e32 v167, v166, v167
	v_mul_f32_e32 v166, 0xbfb8aa3b, v31
	v_exp_f32_e32 v166, v166
	v_mul_f32_e32 v176, 0xbfb8aa3b, v27
	v_add_f32_e32 v169, 1.0, v169
	v_exp_f32_e32 v176, v176
	v_rcp_f32_e32 v175, v169
	v_mul_f32_e32 v169, v168, v169
	v_mul_f32_e32 v168, 0xbfb8aa3b, v23
	v_exp_f32_e32 v168, v168
	v_add_f32_e32 v166, 1.0, v166
	v_mul_f32_e32 v177, 0xbfb8aa3b, v19
	v_rcp_f32_e32 v166, v166
	v_exp_f32_e32 v177, v177
	v_add_f32_e32 v176, 1.0, v176
	v_rcp_f32_e32 v176, v176
	v_add_f32_e32 v168, 1.0, v168
	v_rcp_f32_e32 v178, v168
	v_mul_f32_e32 v168, v166, v168
	v_cvt_pk_bf16_f32 v166, v134, v146
	v_add_co_u32_e32 v134, vcc, s49, v132
	v_add_f32_e32 v177, 1.0, v177
	v_cvt_pk_bf16_f32 v167, v167, v168
	v_cvt_pk_bf16_f32 v168, v135, v159
	s_nop 0
	v_addc_co_u32_e32 v135, vcc, 0, v133, vcc
	v_mul_f32_e32 v176, v176, v177
	v_cvt_pk_bf16_f32 v169, v169, v176
	ds_bpermute_b32 v200, v214, v166
	ds_bpermute_b32 v201, v214, v167
	ds_bpermute_b32 v202, v214, v168
	ds_bpermute_b32 v203, v214, v169
	ds_bpermute_b32 v204, v214, v134
	ds_bpermute_b32 v205, v214, v135
	s_waitcnt lgkmcnt(6)
	global_store_dwordx4 v[212:213], v[208:211], off nt
	v_add_co_u32_e32 v134, vcc, s49, v130
	v_rcp_f32_e32 v179, v177
	s_nop 0
	v_addc_co_u32_e32 v135, vcc, 0, v131, vcc
	v_cvt_pk_bf16_f32 v166, v170, v172
	v_cvt_pk_bf16_f32 v167, v174, v178
	v_cvt_pk_bf16_f32 v168, v171, v173
	v_cvt_pk_bf16_f32 v169, v175, v179
	ds_bpermute_b32 v208, v214, v166
	ds_bpermute_b32 v209, v214, v167
	ds_bpermute_b32 v210, v214, v168
	ds_bpermute_b32 v211, v214, v169
	ds_bpermute_b32 v212, v214, v134
	ds_bpermute_b32 v213, v214, v135
	s_waitcnt lgkmcnt(6)
	global_store_dwordx4 v[204:205], v[200:203], off nt
	v_mul_f32_e32 v134, 0xbfb8aa3b, v12
	v_mul_f32_e32 v146, 0xbfb8aa3b, v8
	v_exp_f32_e32 v134, v134
	v_exp_f32_e32 v146, v146
	v_mul_f32_e32 v135, 0xbfb8aa3b, v4
	v_mul_f32_e32 v159, 0xbfb8aa3b, v0
	v_exp_f32_e32 v135, v135
	v_exp_f32_e32 v159, v159
	v_add_f32_e32 v134, 1.0, v134
	v_add_f32_e32 v146, 1.0, v146
	v_rcp_f32_e32 v134, v134
	v_rcp_f32_e32 v146, v146
	v_add_f32_e32 v135, 1.0, v135
	v_add_f32_e32 v159, 1.0, v159
	v_rcp_f32_e32 v170, v135
	v_mul_f32_e32 v134, v134, v135
	v_mul_f32_e32 v135, v146, v159
	v_mul_f32_e32 v146, 0xbfb8aa3b, v13
	v_mul_f32_e32 v166, 0xbfb8aa3b, v9
	v_exp_f32_e32 v146, v146
	v_exp_f32_e32 v166, v166
	v_rcp_f32_e32 v171, v159
	v_mul_f32_e32 v159, 0xbfb8aa3b, v5
	v_mul_f32_e32 v167, 0xbfb8aa3b, v1
	v_exp_f32_e32 v159, v159
	v_exp_f32_e32 v167, v167
	v_add_f32_e32 v146, 1.0, v146
	v_add_f32_e32 v166, 1.0, v166
	v_rcp_f32_e32 v146, v146
	v_rcp_f32_e32 v166, v166
	v_add_f32_e32 v159, 1.0, v159
	v_add_f32_e32 v167, 1.0, v167
	v_rcp_f32_e32 v172, v159
	v_mul_f32_e32 v146, v146, v159
	v_mul_f32_e32 v159, v166, v167
	v_mul_f32_e32 v166, 0xbfb8aa3b, v14
	v_exp_f32_e32 v166, v166
	v_rcp_f32_e32 v173, v167
	v_mul_f32_e32 v167, 0xbfb8aa3b, v6
	v_mul_f32_e32 v168, 0xbfb8aa3b, v10
	v_exp_f32_e32 v167, v167
	v_exp_f32_e32 v168, v168
	v_add_f32_e32 v166, 1.0, v166
	v_rcp_f32_e32 v166, v166
	v_mul_f32_e32 v169, 0xbfb8aa3b, v2
	v_exp_f32_e32 v169, v169
	v_add_f32_e32 v167, 1.0, v167
	v_add_f32_e32 v168, 1.0, v168
	v_rcp_f32_e32 v168, v168
	v_rcp_f32_e32 v174, v167
	v_mul_f32_e32 v167, v166, v167
	v_mul_f32_e32 v166, 0xbfb8aa3b, v15
	v_exp_f32_e32 v166, v166
	v_mul_f32_e32 v176, 0xbfb8aa3b, v11
	v_exp_f32_e32 v176, v176
	v_add_f32_e32 v169, 1.0, v169
	v_rcp_f32_e32 v175, v169
	v_mul_f32_e32 v169, v168, v169
	v_mul_f32_e32 v168, 0xbfb8aa3b, v7
	v_exp_f32_e32 v168, v168
	v_mul_f32_e32 v177, 0xbfb8aa3b, v3
	v_add_f32_e32 v166, 1.0, v166
	v_exp_f32_e32 v177, v177
	v_add_f32_e32 v176, 1.0, v176
	v_rcp_f32_e32 v166, v166
	s_mov_b32 s3, 0xb0000
	v_rcp_f32_e32 v176, v176
	v_add_co_u32_e32 v132, vcc, s3, v132
	v_add_f32_e32 v168, 1.0, v168
	s_nop 0
	v_addc_co_u32_e32 v133, vcc, 0, v133, vcc
	v_add_co_u32_e32 v130, vcc, 0xb0000, v130
	v_add_f32_e32 v177, 1.0, v177
	v_rcp_f32_e32 v178, v168
	v_mul_f32_e32 v168, v166, v168
	v_addc_co_u32_e32 v131, vcc, 0, v131, vcc
	v_rcp_f32_e32 v179, v177
	v_mul_f32_e32 v176, v176, v177
	v_cvt_pk_bf16_f32 v166, v134, v146
	v_cvt_pk_bf16_f32 v167, v167, v168
	v_cvt_pk_bf16_f32 v168, v135, v159
	v_cvt_pk_bf16_f32 v169, v169, v176
	ds_bpermute_b32 v200, v214, v166
	ds_bpermute_b32 v201, v214, v167
	ds_bpermute_b32 v202, v214, v168
	ds_bpermute_b32 v203, v214, v169
	ds_bpermute_b32 v204, v214, v132
	ds_bpermute_b32 v205, v214, v133
	s_waitcnt lgkmcnt(6)
; __device__ __forceinline__ float siluf_(float x) { return x * sigmoidf_(x); }
; __device__ __forceinline__ u32x4 pack8(f32x4 v0, f32x4 v1) { u32x4 w; w.x = cvt_pk_bf16(v0[0], v0[1]); w.y = cvt_pk_bf16(v0[2], v0[3]); w.z = cvt_pk_bf16(v1[0], v1[1]); w.w = cvt_pk_bf16(v1[2], v1[3]); return w; }
;     __device__ __forceinline__ void operator()(const Acc& acc, const Unit& u, int wr, int wc, int fr, int fq) const {
;     ...
;                 bf16_t* base = P2 + (size_t)(pm * 256 + rloc) * DM + col;
; #pragma unroll
;                 for (int ai = 0; ai < 2; ++ai)
; #pragma unroll
;                     for (int m = 0; m < 4; ++m) { f32x4 v0, v1;
; #pragma unroll
;                         for (int j = 0; j < 4; ++j) { v0[j] = acc[ai][0][m][0][j] * siluf_(acc[ai][1][m][0][j]); v1[j] = acc[ai][0][m][1][j] * siluf_(acc[ai][1][m][1][j]); }
;                         __builtin_nontemporal_store(pack8(v0, v1), (u32x4*)(base + (size_t)(ai * 128 + m * 16) * DM)); }
;             } else {
;                 const size_t o0 = (size_t)(pm * 256 + rloc) * DM + col;
; #pragma unroll
;                 for (int ai = 0; ai < 2; ++ai)
; #pragma unroll
;                     for (int m = 0; m < 4; ++m) { f32x4 r0, r1, s0, s1;
; #pragma unroll
;                         for (int j = 0; j < 4; ++j) { const float e1a = 1.0f + __expf(-acc[ai][0][m][0][j]), e2a = 1.0f + __expf(-acc[ai][1][m][0][j]);
;                             const float e1b = 1.0f + __expf(-acc[ai][0][m][1][j]), e2b = 1.0f + __expf(-acc[ai][1][m][1][j]);
;                             s0[j] = __builtin_amdgcn_rcpf(e2a); s1[j] = __builtin_amdgcn_rcpf(e2b); r0[j] = e2a * __builtin_amdgcn_rcpf(e1a); r1[j] = e2b * __builtin_amdgcn_rcpf(e1b); }
;                         const size_t o = o0 + (size_t)(ai * 128 + m * 16) * DM;
;                         __builtin_nontemporal_store(pack8(r0, r1), (u32x4*)(R + o)); __builtin_nontemporal_store(pack8(s0, s1), (u32x4*)(S2 + o)); }
	global_store_dwordx4 v[212:213], v[208:211], off nt
	v_cvt_pk_bf16_f32 v132, v170, v172
	v_cvt_pk_bf16_f32 v133, v174, v178
	v_cvt_pk_bf16_f32 v134, v171, v173
	v_cvt_pk_bf16_f32 v135, v175, v179
	ds_bpermute_b32 v208, v214, v132
	ds_bpermute_b32 v209, v214, v133
	ds_bpermute_b32 v210, v214, v134
	ds_bpermute_b32 v211, v214, v135
	ds_bpermute_b32 v212, v214, v130
	ds_bpermute_b32 v213, v214, v131
	s_waitcnt lgkmcnt(6)
	global_store_dwordx4 v[204:205], v[200:203], off nt
	s_mov_b64 s[26:27], 0
	s_waitcnt lgkmcnt(0)
	global_store_dwordx4 v[212:213], v[208:211], off nt
.LBB0_335:
	s_andn2_b64 vcc, exec, s[26:27]
	s_cbranch_vccnz .LBB0_337
	v_mul_f32_e32 v131, 0xbfb8aa3b, v112
	v_exp_f32_e32 v131, v131
	v_mul_f32_e32 v132, 0xbfb8aa3b, v117
	v_mul_f32_e32 v133, 0xbfb8aa3b, v113
	v_exp_f32_e32 v132, v132
	v_add_f32_e32 v131, 1.0, v131
	v_rcp_f32_e32 v131, v131
	v_exp_f32_e32 v133, v133
	v_readlane_b32 s26, v248, 46
	v_readlane_b32 s27, v248, 47
	v_mul_f32_e32 v131, v112, v131
	v_mul_f32_e32 v130, 0xbfb8aa3b, v116
	v_lshl_add_u64 v[128:129], s[26:27], 0, v[128:129]
	v_lshlrev_b32_e32 v146, 1, v158
	v_mul_f32_e32 v134, v120, v131
	v_add_f32_e32 v131, 1.0, v132
	v_add_f32_e32 v132, 1.0, v133
	v_mul_f32_e32 v133, 0xbfb8aa3b, v118
	v_exp_f32_e32 v130, v130
	v_lshl_add_u64 v[128:129], v[128:129], 0, v[146:147]
	v_exp_f32_e32 v133, v133
	v_mul_f32_e32 v146, 0xbfb8aa3b, v119
	v_exp_f32_e32 v146, v146
	v_add_f32_e32 v130, 1.0, v130
	v_add_f32_e32 v133, 1.0, v133
	v_rcp_f32_e32 v130, v130
	v_rcp_f32_e32 v131, v131
	v_rcp_f32_e32 v133, v133
	v_mul_f32_e32 v135, 0xbfb8aa3b, v114
	v_add_f32_e32 v146, 1.0, v146
	v_rcp_f32_e32 v132, v132
	v_exp_f32_e32 v135, v135
	v_mul_f32_e32 v159, 0xbfb8aa3b, v115
	v_rcp_f32_e32 v146, v146
	v_exp_f32_e32 v159, v159
	v_mul_f32_e32 v130, v116, v130
	v_mul_f32_e32 v131, v117, v131
	v_mul_f32_e32 v133, v118, v133
	v_mul_f32_e32 v130, v124, v130
	v_mul_f32_e32 v131, v125, v131
	v_mul_f32_e32 v132, v113, v132
	v_mul_f32_e32 v133, v126, v133
	v_add_f32_e32 v135, 1.0, v135
	v_mul_f32_e32 v146, v119, v146
	v_mul_f32_e32 v132, v121, v132
	v_rcp_f32_e32 v135, v135
	v_add_f32_e32 v159, 1.0, v159
	v_mul_f32_e32 v146, v127, v146
	v_cvt_pk_bf16_f32 v130, v130, v131
	v_cvt_pk_bf16_f32 v131, v133, v146
	v_mul_f32_e32 v133, 0xbfb8aa3b, v100
	v_rcp_f32_e32 v159, v159
	v_cvt_pk_bf16_f32 v132, v134, v132
	v_exp_f32_e32 v134, v133
	v_mul_f32_e32 v133, 0xbfb8aa3b, v96
	v_exp_f32_e32 v146, v133
	v_mul_f32_e32 v135, v114, v135
	v_mul_f32_e32 v135, v122, v135
	v_mul_f32_e32 v159, v115, v159
	v_mul_f32_e32 v159, v123, v159
	v_cvt_pk_bf16_f32 v133, v135, v159
	v_add_f32_e32 v135, 1.0, v146
	v_add_f32_e32 v134, 1.0, v134
	v_rcp_f32_e32 v135, v135
	ds_bpermute_b32 v200, v214, v130
	ds_bpermute_b32 v201, v214, v131
	ds_bpermute_b32 v202, v214, v132
	ds_bpermute_b32 v203, v214, v133
	ds_bpermute_b32 v204, v214, v128
	ds_bpermute_b32 v205, v214, v129
	v_rcp_f32_e32 v134, v134
	v_mul_f32_e32 v146, 0xbfb8aa3b, v103
	v_mul_f32_e32 v132, 0xbfb8aa3b, v101
	v_mul_f32_e32 v133, 0xbfb8aa3b, v97
	v_exp_f32_e32 v132, v132
	v_exp_f32_e32 v133, v133
	v_mul_f32_e32 v131, v96, v135
	v_mul_f32_e32 v130, v100, v134
	v_mul_f32_e32 v134, v104, v131
	v_add_f32_e32 v131, 1.0, v132
	v_add_f32_e32 v132, 1.0, v133
	v_mul_f32_e32 v133, 0xbfb8aa3b, v102
	v_exp_f32_e32 v133, v133
	v_exp_f32_e32 v146, v146
	v_mul_f32_e32 v159, 0xbfb8aa3b, v99
	v_mul_f32_e32 v135, 0xbfb8aa3b, v98
	v_exp_f32_e32 v159, v159
	v_exp_f32_e32 v135, v135
	v_rcp_f32_e32 v131, v131
	v_rcp_f32_e32 v132, v132
	v_add_f32_e32 v133, 1.0, v133
	v_add_f32_e32 v146, 1.0, v146
	v_rcp_f32_e32 v133, v133
	v_rcp_f32_e32 v146, v146
	v_add_f32_e32 v159, 1.0, v159
	v_add_f32_e32 v135, 1.0, v135
	v_rcp_f32_e32 v159, v159
	v_rcp_f32_e32 v135, v135
	v_mul_f32_e32 v131, v101, v131
	v_mul_f32_e32 v132, v97, v132
	v_mul_f32_e32 v130, v108, v130
	v_mul_f32_e32 v131, v109, v131
	v_mul_f32_e32 v132, v105, v132
	v_mul_f32_e32 v133, v102, v133
	v_mul_f32_e32 v146, v103, v146
	v_mul_f32_e32 v133, v110, v133
	v_mul_f32_e32 v146, v111, v146
	v_mul_f32_e32 v159, v99, v159
	v_cvt_pk_bf16_f32 v130, v130, v131
	v_cvt_pk_bf16_f32 v131, v133, v146
	v_cvt_pk_bf16_f32 v132, v134, v132
	v_mul_f32_e32 v134, 0xbfb8aa3b, v84
	v_mul_f32_e32 v135, v98, v135
	v_mul_f32_e32 v159, v107, v159
	v_exp_f32_e32 v146, v134
	v_mul_f32_e32 v134, 0xbfb8aa3b, v80
	v_mul_f32_e32 v135, v106, v135
	v_cvt_pk_bf16_f32 v133, v135, v159
	v_exp_f32_e32 v159, v134
	v_add_co_u32_e32 v134, vcc, s38, v128
	v_add_f32_e32 v146, 1.0, v146
	s_nop 0
	v_addc_co_u32_e32 v135, vcc, 0, v129, vcc
	v_add_f32_e32 v159, 1.0, v159
	v_rcp_f32_e32 v159, v159
	ds_bpermute_b32 v208, v214, v130
	ds_bpermute_b32 v209, v214, v131
	ds_bpermute_b32 v210, v214, v132
	ds_bpermute_b32 v211, v214, v133
	ds_bpermute_b32 v212, v214, v134
	ds_bpermute_b32 v213, v214, v135
	s_waitcnt lgkmcnt(6)
; __device__ __forceinline__ float siluf_(float x) { return x * sigmoidf_(x); }
; __device__ __forceinline__ u32x4 pack8(f32x4 v0, f32x4 v1) { u32x4 w; w.x = cvt_pk_bf16(v0[0], v0[1]); w.y = cvt_pk_bf16(v0[2], v0[3]); w.z = cvt_pk_bf16(v1[0], v1[1]); w.w = cvt_pk_bf16(v1[2], v1[3]); return w; }
;     __device__ __forceinline__ void operator()(const Acc& acc, const Unit& u, int wr, int wc, int fr, int fq) const {
;     ...
;                 bf16_t* base = P2 + (size_t)(pm * 256 + rloc) * DM + col;
; #pragma unroll
;                 for (int ai = 0; ai < 2; ++ai)
; #pragma unroll
;                     for (int m = 0; m < 4; ++m) { f32x4 v0, v1;
; #pragma unroll
;                         for (int j = 0; j < 4; ++j) { v0[j] = acc[ai][0][m][0][j] * siluf_(acc[ai][1][m][0][j]); v1[j] = acc[ai][0][m][1][j] * siluf_(acc[ai][1][m][1][j]); }
;                         __builtin_nontemporal_store(pack8(v0, v1), (u32x4*)(base + (size_t)(ai * 128 + m * 16) * DM)); }
	global_store_dwordx4 v[204:205], v[200:203], off nt
	v_rcp_f32_e32 v146, v146
	v_mul_f32_e32 v135, 0xbfb8aa3b, v82
	v_mul_f32_e32 v132, 0xbfb8aa3b, v85
	v_mul_f32_e32 v133, 0xbfb8aa3b, v81
	v_exp_f32_e32 v132, v132
	v_exp_f32_e32 v133, v133
	v_mul_f32_e32 v131, v80, v159
	v_mul_f32_e32 v130, v84, v146
	v_mul_f32_e32 v134, v88, v131
	v_add_f32_e32 v131, 1.0, v132
	v_add_f32_e32 v132, 1.0, v133
	v_mul_f32_e32 v133, 0xbfb8aa3b, v86
	v_mul_f32_e32 v146, 0xbfb8aa3b, v87
	v_exp_f32_e32 v133, v133
	v_exp_f32_e32 v146, v146
	v_mul_f32_e32 v159, 0xbfb8aa3b, v83
	v_exp_f32_e32 v159, v159
	v_exp_f32_e32 v135, v135
	v_rcp_f32_e32 v131, v131
	v_rcp_f32_e32 v132, v132
	v_add_f32_e32 v133, 1.0, v133
	v_add_f32_e32 v146, 1.0, v146
	v_rcp_f32_e32 v133, v133
	v_rcp_f32_e32 v146, v146
	v_add_f32_e32 v159, 1.0, v159
	v_add_f32_e32 v135, 1.0, v135
	v_rcp_f32_e32 v159, v159
	v_rcp_f32_e32 v135, v135
	v_mul_f32_e32 v131, v85, v131
	v_mul_f32_e32 v132, v81, v132
	v_mul_f32_e32 v130, v92, v130
	v_mul_f32_e32 v131, v93, v131
	v_mul_f32_e32 v132, v89, v132
	v_mul_f32_e32 v133, v86, v133
	v_mul_f32_e32 v146, v87, v146
	v_mul_f32_e32 v133, v94, v133
	v_mul_f32_e32 v146, v95, v146
	v_mul_f32_e32 v159, v83, v159
	v_cvt_pk_bf16_f32 v130, v130, v131
	v_cvt_pk_bf16_f32 v131, v133, v146
	v_cvt_pk_bf16_f32 v132, v134, v132
	v_mul_f32_e32 v134, 0xbfb8aa3b, v68
	v_mul_f32_e32 v135, v82, v135
	v_mul_f32_e32 v159, v91, v159
	v_exp_f32_e32 v146, v134
	v_mul_f32_e32 v134, 0xbfb8aa3b, v64
	v_mul_f32_e32 v135, v90, v135
	v_cvt_pk_bf16_f32 v133, v135, v159
	v_exp_f32_e32 v159, v134
	v_add_co_u32_e32 v134, vcc, s45, v128
	v_add_f32_e32 v146, 1.0, v146
	s_nop 0
	v_addc_co_u32_e32 v135, vcc, 0, v129, vcc
	v_add_f32_e32 v159, 1.0, v159
	v_rcp_f32_e32 v159, v159
	ds_bpermute_b32 v200, v214, v130
	ds_bpermute_b32 v201, v214, v131
	ds_bpermute_b32 v202, v214, v132
	ds_bpermute_b32 v203, v214, v133
	ds_bpermute_b32 v204, v214, v134
	ds_bpermute_b32 v205, v214, v135
	s_waitcnt lgkmcnt(6)
	global_store_dwordx4 v[212:213], v[208:211], off nt
	v_rcp_f32_e32 v146, v146
	v_mul_f32_e32 v135, 0xbfb8aa3b, v66
	v_mul_f32_e32 v132, 0xbfb8aa3b, v69
	v_mul_f32_e32 v133, 0xbfb8aa3b, v65
	v_exp_f32_e32 v132, v132
	v_exp_f32_e32 v133, v133
	v_mul_f32_e32 v131, v64, v159
	v_mul_f32_e32 v130, v68, v146
	v_mul_f32_e32 v134, v72, v131
	v_add_f32_e32 v131, 1.0, v132
	v_add_f32_e32 v132, 1.0, v133
	v_mul_f32_e32 v133, 0xbfb8aa3b, v70
	v_mul_f32_e32 v146, 0xbfb8aa3b, v71
	v_exp_f32_e32 v133, v133
	v_exp_f32_e32 v146, v146
	v_mul_f32_e32 v159, 0xbfb8aa3b, v67
	v_exp_f32_e32 v159, v159
	v_exp_f32_e32 v135, v135
	v_rcp_f32_e32 v131, v131
	v_rcp_f32_e32 v132, v132
	v_add_f32_e32 v133, 1.0, v133
	v_add_f32_e32 v146, 1.0, v146
	v_rcp_f32_e32 v133, v133
	v_rcp_f32_e32 v146, v146
	v_add_f32_e32 v159, 1.0, v159
	v_add_f32_e32 v135, 1.0, v135
	v_rcp_f32_e32 v159, v159
	v_rcp_f32_e32 v135, v135
	v_mul_f32_e32 v131, v69, v131
	v_mul_f32_e32 v132, v65, v132
	v_mul_f32_e32 v130, v76, v130
	v_mul_f32_e32 v131, v77, v131
	v_mul_f32_e32 v132, v73, v132
	v_mul_f32_e32 v133, v70, v133
	v_mul_f32_e32 v146, v71, v146
	v_mul_f32_e32 v133, v78, v133
	v_mul_f32_e32 v146, v79, v146
	v_mul_f32_e32 v159, v67, v159
	v_cvt_pk_bf16_f32 v130, v130, v131
	v_cvt_pk_bf16_f32 v131, v133, v146
	v_cvt_pk_bf16_f32 v132, v134, v132
	v_mul_f32_e32 v134, 0xbfb8aa3b, v52
	v_mul_f32_e32 v135, v66, v135
	v_mul_f32_e32 v159, v75, v159
	v_exp_f32_e32 v146, v134
	v_mul_f32_e32 v134, 0xbfb8aa3b, v48
	v_mul_f32_e32 v135, v74, v135
	v_cvt_pk_bf16_f32 v133, v135, v159
	v_exp_f32_e32 v159, v134
	v_add_co_u32_e32 v134, vcc, s46, v128
	v_add_f32_e32 v146, 1.0, v146
	s_nop 0
	v_addc_co_u32_e32 v135, vcc, 0, v129, vcc
	v_add_f32_e32 v159, 1.0, v159
	v_rcp_f32_e32 v159, v159
	ds_bpermute_b32 v208, v214, v130
	ds_bpermute_b32 v209, v214, v131
	ds_bpermute_b32 v210, v214, v132
	ds_bpermute_b32 v211, v214, v133
	ds_bpermute_b32 v212, v214, v134
	ds_bpermute_b32 v213, v214, v135
	s_waitcnt lgkmcnt(6)
	global_store_dwordx4 v[204:205], v[200:203], off nt
	v_rcp_f32_e32 v146, v146
	v_mul_f32_e32 v135, 0xbfb8aa3b, v50
	v_mul_f32_e32 v132, 0xbfb8aa3b, v53
	v_mul_f32_e32 v133, 0xbfb8aa3b, v49
	v_exp_f32_e32 v132, v132
	v_exp_f32_e32 v133, v133
	v_mul_f32_e32 v131, v48, v159
	v_mul_f32_e32 v130, v52, v146
	v_mul_f32_e32 v134, v56, v131
	v_add_f32_e32 v131, 1.0, v132
	v_add_f32_e32 v132, 1.0, v133
	v_mul_f32_e32 v133, 0xbfb8aa3b, v54
	v_mul_f32_e32 v146, 0xbfb8aa3b, v55
	v_exp_f32_e32 v133, v133
	v_exp_f32_e32 v146, v146
	v_mul_f32_e32 v159, 0xbfb8aa3b, v51
	v_exp_f32_e32 v159, v159
	v_exp_f32_e32 v135, v135
	v_rcp_f32_e32 v131, v131
	v_rcp_f32_e32 v132, v132
	v_add_f32_e32 v133, 1.0, v133
	v_add_f32_e32 v146, 1.0, v146
	v_rcp_f32_e32 v133, v133
	v_rcp_f32_e32 v146, v146
	v_add_f32_e32 v159, 1.0, v159
	v_add_f32_e32 v135, 1.0, v135
	v_rcp_f32_e32 v159, v159
	v_rcp_f32_e32 v135, v135
	v_mul_f32_e32 v131, v53, v131
	v_mul_f32_e32 v132, v49, v132
	v_mul_f32_e32 v130, v60, v130
	v_mul_f32_e32 v131, v61, v131
	v_mul_f32_e32 v132, v57, v132
	v_mul_f32_e32 v133, v54, v133
	v_mul_f32_e32 v146, v55, v146
	v_mul_f32_e32 v133, v62, v133
	v_mul_f32_e32 v146, v63, v146
	v_mul_f32_e32 v159, v51, v159
	v_cvt_pk_bf16_f32 v130, v130, v131
	v_cvt_pk_bf16_f32 v131, v133, v146
	v_cvt_pk_bf16_f32 v132, v134, v132
	v_mul_f32_e32 v134, 0xbfb8aa3b, v36
	v_mul_f32_e32 v135, v50, v135
	v_mul_f32_e32 v159, v59, v159
	v_exp_f32_e32 v146, v134
	v_mul_f32_e32 v134, 0xbfb8aa3b, v32
	v_mul_f32_e32 v135, v58, v135
	v_cvt_pk_bf16_f32 v133, v135, v159
	v_exp_f32_e32 v159, v134
	v_add_co_u32_e32 v134, vcc, s47, v128
	v_add_f32_e32 v146, 1.0, v146
	s_nop 0
	v_addc_co_u32_e32 v135, vcc, 0, v129, vcc
	v_add_f32_e32 v159, 1.0, v159
	v_rcp_f32_e32 v159, v159
	ds_bpermute_b32 v200, v214, v130
	ds_bpermute_b32 v201, v214, v131
	ds_bpermute_b32 v202, v214, v132
	ds_bpermute_b32 v203, v214, v133
	ds_bpermute_b32 v204, v214, v134
	ds_bpermute_b32 v205, v214, v135
	s_waitcnt lgkmcnt(6)
; __device__ __forceinline__ float siluf_(float x) { return x * sigmoidf_(x); }
; __device__ __forceinline__ u32x4 pack8(f32x4 v0, f32x4 v1) { u32x4 w; w.x = cvt_pk_bf16(v0[0], v0[1]); w.y = cvt_pk_bf16(v0[2], v0[3]); w.z = cvt_pk_bf16(v1[0], v1[1]); w.w = cvt_pk_bf16(v1[2], v1[3]); return w; }
;     __device__ __forceinline__ void operator()(const Acc& acc, const Unit& u, int wr, int wc, int fr, int fq) const {
;     ...
;                 bf16_t* base = P2 + (size_t)(pm * 256 + rloc) * DM + col;
; #pragma unroll
;                 for (int ai = 0; ai < 2; ++ai)
; #pragma unroll
;                     for (int m = 0; m < 4; ++m) { f32x4 v0, v1;
; #pragma unroll
;                         for (int j = 0; j < 4; ++j) { v0[j] = acc[ai][0][m][0][j] * siluf_(acc[ai][1][m][0][j]); v1[j] = acc[ai][0][m][1][j] * siluf_(acc[ai][1][m][1][j]); }
;                         __builtin_nontemporal_store(pack8(v0, v1), (u32x4*)(base + (size_t)(ai * 128 + m * 16) * DM)); }
	global_store_dwordx4 v[212:213], v[208:211], off nt
	v_rcp_f32_e32 v146, v146
	v_mul_f32_e32 v135, 0xbfb8aa3b, v34
	v_mul_f32_e32 v132, 0xbfb8aa3b, v37
	v_mul_f32_e32 v133, 0xbfb8aa3b, v33
	v_exp_f32_e32 v132, v132
	v_exp_f32_e32 v133, v133
	v_mul_f32_e32 v131, v32, v159
	v_mul_f32_e32 v130, v36, v146
	v_mul_f32_e32 v134, v40, v131
	v_add_f32_e32 v131, 1.0, v132
	v_add_f32_e32 v132, 1.0, v133
	v_mul_f32_e32 v133, 0xbfb8aa3b, v38
	v_mul_f32_e32 v146, 0xbfb8aa3b, v39
	v_exp_f32_e32 v133, v133
	v_exp_f32_e32 v146, v146
	v_mul_f32_e32 v159, 0xbfb8aa3b, v35
	v_exp_f32_e32 v159, v159
	v_exp_f32_e32 v135, v135
	v_rcp_f32_e32 v131, v131
	v_rcp_f32_e32 v132, v132
	v_add_f32_e32 v133, 1.0, v133
	v_add_f32_e32 v146, 1.0, v146
	v_rcp_f32_e32 v133, v133
	v_rcp_f32_e32 v146, v146
	v_add_f32_e32 v159, 1.0, v159
	v_add_f32_e32 v135, 1.0, v135
	v_rcp_f32_e32 v159, v159
	v_rcp_f32_e32 v135, v135
	v_mul_f32_e32 v131, v37, v131
	v_mul_f32_e32 v132, v33, v132
	v_mul_f32_e32 v130, v44, v130
	v_mul_f32_e32 v131, v45, v131
	v_mul_f32_e32 v132, v41, v132
	v_mul_f32_e32 v133, v38, v133
	v_mul_f32_e32 v146, v39, v146
	v_mul_f32_e32 v133, v46, v133
	v_mul_f32_e32 v146, v47, v146
	v_mul_f32_e32 v159, v35, v159
	v_cvt_pk_bf16_f32 v130, v130, v131
	v_cvt_pk_bf16_f32 v131, v133, v146
	v_cvt_pk_bf16_f32 v132, v134, v132
	v_mul_f32_e32 v134, 0xbfb8aa3b, v20
	v_mul_f32_e32 v135, v34, v135
	v_mul_f32_e32 v159, v43, v159
	v_exp_f32_e32 v146, v134
	v_mul_f32_e32 v134, 0xbfb8aa3b, v16
	v_mul_f32_e32 v135, v42, v135
	v_cvt_pk_bf16_f32 v133, v135, v159
	v_exp_f32_e32 v159, v134
	v_add_co_u32_e32 v134, vcc, s48, v128
	v_add_f32_e32 v146, 1.0, v146
	s_nop 0
	v_addc_co_u32_e32 v135, vcc, 0, v129, vcc
	v_add_f32_e32 v159, 1.0, v159
	v_rcp_f32_e32 v159, v159
	ds_bpermute_b32 v208, v214, v130
	ds_bpermute_b32 v209, v214, v131
	ds_bpermute_b32 v210, v214, v132
	ds_bpermute_b32 v211, v214, v133
	ds_bpermute_b32 v212, v214, v134
	ds_bpermute_b32 v213, v214, v135
	s_waitcnt lgkmcnt(6)
	global_store_dwordx4 v[204:205], v[200:203], off nt
	v_rcp_f32_e32 v146, v146
	v_mul_f32_e32 v135, 0xbfb8aa3b, v18
	v_mul_f32_e32 v132, 0xbfb8aa3b, v21
	v_mul_f32_e32 v133, 0xbfb8aa3b, v17
	v_exp_f32_e32 v132, v132
	v_exp_f32_e32 v133, v133
	v_mul_f32_e32 v131, v16, v159
	v_mul_f32_e32 v130, v20, v146
	v_mul_f32_e32 v134, v24, v131
	v_add_f32_e32 v131, 1.0, v132
	v_add_f32_e32 v132, 1.0, v133
	v_mul_f32_e32 v133, 0xbfb8aa3b, v22
	v_mul_f32_e32 v146, 0xbfb8aa3b, v23
	v_exp_f32_e32 v133, v133
	v_exp_f32_e32 v146, v146
	v_mul_f32_e32 v159, 0xbfb8aa3b, v19
	v_exp_f32_e32 v159, v159
	v_exp_f32_e32 v135, v135
	v_rcp_f32_e32 v131, v131
	v_rcp_f32_e32 v132, v132
	v_add_f32_e32 v133, 1.0, v133
	v_add_f32_e32 v146, 1.0, v146
	v_rcp_f32_e32 v133, v133
	v_rcp_f32_e32 v146, v146
	v_add_f32_e32 v159, 1.0, v159
	v_add_f32_e32 v135, 1.0, v135
	v_rcp_f32_e32 v159, v159
	v_rcp_f32_e32 v135, v135
	v_mul_f32_e32 v131, v21, v131
	v_mul_f32_e32 v132, v17, v132
	v_mul_f32_e32 v130, v28, v130
	v_mul_f32_e32 v131, v29, v131
	v_mul_f32_e32 v132, v25, v132
	v_mul_f32_e32 v133, v22, v133
	v_mul_f32_e32 v146, v23, v146
	v_mul_f32_e32 v133, v30, v133
	v_mul_f32_e32 v146, v31, v146
	v_mul_f32_e32 v159, v19, v159
	v_cvt_pk_bf16_f32 v130, v130, v131
	v_cvt_pk_bf16_f32 v131, v133, v146
	v_cvt_pk_bf16_f32 v132, v134, v132
	v_mul_f32_e32 v134, 0xbfb8aa3b, v4
	v_mul_f32_e32 v135, v18, v135
	v_mul_f32_e32 v159, v27, v159
	v_exp_f32_e32 v146, v134
	v_mul_f32_e32 v134, 0xbfb8aa3b, v0
	v_mul_f32_e32 v135, v26, v135
	v_cvt_pk_bf16_f32 v133, v135, v159
	v_exp_f32_e32 v159, v134
	v_add_co_u32_e32 v134, vcc, s49, v128
	v_add_f32_e32 v146, 1.0, v146
	s_nop 0
	v_addc_co_u32_e32 v135, vcc, 0, v129, vcc
	v_add_f32_e32 v159, 1.0, v159
	v_rcp_f32_e32 v159, v159
	ds_bpermute_b32 v200, v214, v130
	ds_bpermute_b32 v201, v214, v131
	ds_bpermute_b32 v202, v214, v132
	ds_bpermute_b32 v203, v214, v133
	ds_bpermute_b32 v204, v214, v134
	ds_bpermute_b32 v205, v214, v135
	s_waitcnt lgkmcnt(6)
	global_store_dwordx4 v[212:213], v[208:211], off nt
	v_rcp_f32_e32 v146, v146
	v_mul_f32_e32 v135, 0xbfb8aa3b, v2
	v_mul_f32_e32 v132, 0xbfb8aa3b, v5
	v_mul_f32_e32 v133, 0xbfb8aa3b, v1
	v_exp_f32_e32 v132, v132
	v_exp_f32_e32 v133, v133
	v_mul_f32_e32 v131, v0, v159
	v_mul_f32_e32 v134, v8, v131
	v_add_f32_e32 v131, 1.0, v132
	v_add_f32_e32 v132, 1.0, v133
	v_mul_f32_e32 v133, 0xbfb8aa3b, v6
	v_mul_f32_e32 v130, v4, v146
	v_exp_f32_e32 v133, v133
	v_mul_f32_e32 v146, 0xbfb8aa3b, v7
	v_mul_f32_e32 v159, 0xbfb8aa3b, v3
	v_exp_f32_e32 v135, v135
	v_exp_f32_e32 v146, v146
	v_exp_f32_e32 v159, v159
	v_add_f32_e32 v133, 1.0, v133
	v_rcp_f32_e32 v131, v131
	v_rcp_f32_e32 v132, v132
	v_rcp_f32_e32 v133, v133
	v_add_f32_e32 v135, 1.0, v135
	v_add_f32_e32 v146, 1.0, v146
	v_add_f32_e32 v159, 1.0, v159
	v_rcp_f32_e32 v135, v135
	v_rcp_f32_e32 v146, v146
	v_rcp_f32_e32 v159, v159
	v_mul_f32_e32 v131, v5, v131
	v_mul_f32_e32 v132, v1, v132
	v_mul_f32_e32 v133, v6, v133
	v_add_co_u32_e32 v128, vcc, 0xb0000, v128
	v_mul_f32_e32 v130, v12, v130
	v_mul_f32_e32 v131, v13, v131
	v_mul_f32_e32 v132, v9, v132
	v_mul_f32_e32 v133, v14, v133
	v_mul_f32_e32 v135, v2, v135
	v_mul_f32_e32 v146, v7, v146
	v_mul_f32_e32 v159, v3, v159
	v_addc_co_u32_e32 v129, vcc, 0, v129, vcc
	v_mul_f32_e32 v135, v10, v135
	v_mul_f32_e32 v146, v15, v146
	v_mul_f32_e32 v159, v11, v159
	v_cvt_pk_bf16_f32 v130, v130, v131
	v_cvt_pk_bf16_f32 v131, v133, v146
	v_cvt_pk_bf16_f32 v132, v134, v132
	v_cvt_pk_bf16_f32 v133, v135, v159
	ds_bpermute_b32 v208, v214, v130
	ds_bpermute_b32 v209, v214, v131
	ds_bpermute_b32 v210, v214, v132
	ds_bpermute_b32 v211, v214, v133
	ds_bpermute_b32 v212, v214, v128
	ds_bpermute_b32 v213, v214, v129
	s_waitcnt lgkmcnt(6)
	global_store_dwordx4 v[204:205], v[200:203], off nt
	s_waitcnt lgkmcnt(0)
	global_store_dwordx4 v[212:213], v[208:211], off nt

; __device__ __forceinline__ u32x4 pack8(f32x4 v0, f32x4 v1) { u32x4 w; w.x = cvt_pk_bf16(v0[0], v0[1]); w.y = cvt_pk_bf16(v0[2], v0[3]); w.z = cvt_pk_bf16(v1[0], v1[1]); w.w = cvt_pk_bf16(v1[2], v1[3]); return w; }
;     __device__ __forceinline__ void operator()(const Acc& acc, const Unit& u, int wr, int wc, int fr, int fq) const {
;     ...
;             if (kind == 0) {
;                 bf16_t* base = P1 + (size_t)(pm * 256 + 2 + 2 * b + rloc) * DM + col;
; #pragma unroll
;                 for (int ai = 0; ai < 2; ++ai)
; #pragma unroll
;                     for (int m = 0; m < 4; ++m) __builtin_nontemporal_store(pack8(acc[ai][0][m][0] * acc[ai][1][m][0], acc[ai][0][m][1] * acc[ai][1][m][1]), (u32x4*)(base + (size_t)(ai * 128 + m * 16) * DM));
.LBB0_338:
	s_andn2_b64 vcc, exec, s[26:27]
	s_cbranch_vccnz .LBB0_340
	s_ashr_i32 s17, s24, 3
	s_lshl_b32 s3, s24, 8
	s_and_b32 s17, s17, -2
	s_add_i32 s17, s17, s3
	v_add_u32_e32 v128, s17, v160
	v_ashrrev_i32_e32 v129, 31, v128
	v_readlane_b32 s26, v248, 44
	v_lshlrev_b64 v[128:129], 12, v[128:129]
	v_readlane_b32 s27, v248, 45
	v_lshlrev_b32_e32 v146, 1, v158
	v_pk_mul_f32 v[132:133], v[126:127], v[118:119]
	v_lshl_add_u64 v[128:129], s[26:27], 0, v[128:129]
	v_pk_mul_f32 v[130:131], v[124:125], v[116:117]
	v_lshl_add_u64 v[128:129], v[128:129], 0, v[146:147]
	v_pk_mul_f32 v[134:135], v[122:123], v[114:115]
	v_pk_mul_f32 v[158:159], v[120:121], v[112:113]
	v_cvt_pk_bf16_f32 v130, v130, v131
	v_cvt_pk_bf16_f32 v131, v132, v133
	s_nop 0
	v_cvt_pk_bf16_f32 v132, v158, v159
	v_cvt_pk_bf16_f32 v133, v134, v135
	ds_bpermute_b32 v200, v214, v130
	ds_bpermute_b32 v201, v214, v131
	ds_bpermute_b32 v202, v214, v132
	ds_bpermute_b32 v203, v214, v133
	ds_bpermute_b32 v204, v214, v128
	ds_bpermute_b32 v205, v214, v129
	v_pk_mul_f32 v[134:135], v[106:107], v[98:99]
	v_pk_mul_f32 v[158:159], v[104:105], v[96:97]
	v_pk_mul_f32 v[132:133], v[110:111], v[102:103]
	v_pk_mul_f32 v[130:131], v[108:109], v[100:101]
	s_nop 0
	v_cvt_pk_bf16_f32 v130, v130, v131
	v_cvt_pk_bf16_f32 v131, v132, v133
	v_cvt_pk_bf16_f32 v132, v158, v159
	v_cvt_pk_bf16_f32 v133, v134, v135
	v_add_co_u32_e32 v134, vcc, s38, v128
	v_pk_mul_f32 v[158:159], v[88:89], v[80:81]
	s_nop 0
	v_addc_co_u32_e32 v135, vcc, 0, v129, vcc
	ds_bpermute_b32 v208, v214, v130
	ds_bpermute_b32 v209, v214, v131
	ds_bpermute_b32 v210, v214, v132
	ds_bpermute_b32 v211, v214, v133
	ds_bpermute_b32 v212, v214, v134
	ds_bpermute_b32 v213, v214, v135
	s_waitcnt lgkmcnt(6)
	global_store_dwordx4 v[204:205], v[200:203], off nt
	v_pk_mul_f32 v[134:135], v[90:91], v[82:83]
	s_nop 0
	v_pk_mul_f32 v[132:133], v[94:95], v[86:87]
	v_pk_mul_f32 v[130:131], v[92:93], v[84:85]
	s_nop 0
	v_cvt_pk_bf16_f32 v130, v130, v131
	v_cvt_pk_bf16_f32 v131, v132, v133
	v_cvt_pk_bf16_f32 v132, v158, v159
	v_cvt_pk_bf16_f32 v133, v134, v135
	v_add_co_u32_e32 v134, vcc, s45, v128
	v_pk_mul_f32 v[158:159], v[72:73], v[64:65]
	s_nop 0
	v_addc_co_u32_e32 v135, vcc, 0, v129, vcc
	ds_bpermute_b32 v200, v214, v130
	ds_bpermute_b32 v201, v214, v131
	ds_bpermute_b32 v202, v214, v132
	ds_bpermute_b32 v203, v214, v133
	ds_bpermute_b32 v204, v214, v134
	ds_bpermute_b32 v205, v214, v135
	s_waitcnt lgkmcnt(6)
	global_store_dwordx4 v[212:213], v[208:211], off nt
	v_pk_mul_f32 v[134:135], v[74:75], v[66:67]
	s_nop 0
	v_pk_mul_f32 v[132:133], v[78:79], v[70:71]
	v_pk_mul_f32 v[130:131], v[76:77], v[68:69]
	s_nop 0
	v_cvt_pk_bf16_f32 v130, v130, v131
	v_cvt_pk_bf16_f32 v131, v132, v133
	v_cvt_pk_bf16_f32 v132, v158, v159
	v_cvt_pk_bf16_f32 v133, v134, v135
	v_add_co_u32_e32 v134, vcc, s46, v128
	v_pk_mul_f32 v[158:159], v[56:57], v[48:49]
	s_nop 0
	v_addc_co_u32_e32 v135, vcc, 0, v129, vcc
	ds_bpermute_b32 v208, v214, v130
	ds_bpermute_b32 v209, v214, v131
	ds_bpermute_b32 v210, v214, v132
	ds_bpermute_b32 v211, v214, v133
	ds_bpermute_b32 v212, v214, v134
	ds_bpermute_b32 v213, v214, v135
	s_waitcnt lgkmcnt(6)
	global_store_dwordx4 v[204:205], v[200:203], off nt
	v_pk_mul_f32 v[134:135], v[58:59], v[50:51]
	s_nop 0
	v_pk_mul_f32 v[132:133], v[62:63], v[54:55]
	v_pk_mul_f32 v[130:131], v[60:61], v[52:53]
	s_nop 0
	v_cvt_pk_bf16_f32 v130, v130, v131
	v_cvt_pk_bf16_f32 v131, v132, v133
	v_cvt_pk_bf16_f32 v132, v158, v159
	v_cvt_pk_bf16_f32 v133, v134, v135
	v_add_co_u32_e32 v134, vcc, s47, v128
	v_pk_mul_f32 v[158:159], v[40:41], v[32:33]
	s_nop 0
	v_addc_co_u32_e32 v135, vcc, 0, v129, vcc
	ds_bpermute_b32 v200, v214, v130
	ds_bpermute_b32 v201, v214, v131
	ds_bpermute_b32 v202, v214, v132
	ds_bpermute_b32 v203, v214, v133
	ds_bpermute_b32 v204, v214, v134
	ds_bpermute_b32 v205, v214, v135
	s_waitcnt lgkmcnt(6)
	global_store_dwordx4 v[212:213], v[208:211], off nt
	v_pk_mul_f32 v[134:135], v[42:43], v[34:35]
	s_nop 0
	v_pk_mul_f32 v[132:133], v[46:47], v[38:39]
	v_pk_mul_f32 v[130:131], v[44:45], v[36:37]
	s_nop 0
	v_cvt_pk_bf16_f32 v130, v130, v131
	v_cvt_pk_bf16_f32 v131, v132, v133
	v_cvt_pk_bf16_f32 v132, v158, v159
	v_cvt_pk_bf16_f32 v133, v134, v135
	v_add_co_u32_e32 v134, vcc, s48, v128
	v_pk_mul_f32 v[158:159], v[24:25], v[16:17]
	s_nop 0
	v_addc_co_u32_e32 v135, vcc, 0, v129, vcc
	ds_bpermute_b32 v208, v214, v130
	ds_bpermute_b32 v209, v214, v131
	ds_bpermute_b32 v210, v214, v132
	ds_bpermute_b32 v211, v214, v133
	ds_bpermute_b32 v212, v214, v134
	ds_bpermute_b32 v213, v214, v135
	s_waitcnt lgkmcnt(6)
	global_store_dwordx4 v[204:205], v[200:203], off nt
	v_pk_mul_f32 v[134:135], v[26:27], v[18:19]
	s_nop 0
	v_pk_mul_f32 v[132:133], v[30:31], v[22:23]
	v_pk_mul_f32 v[130:131], v[28:29], v[20:21]
	s_nop 0
	v_cvt_pk_bf16_f32 v130, v130, v131
	v_cvt_pk_bf16_f32 v131, v132, v133
	v_cvt_pk_bf16_f32 v132, v158, v159
	v_cvt_pk_bf16_f32 v133, v134, v135
	v_add_co_u32_e32 v134, vcc, s49, v128
	v_pk_mul_f32 v[158:159], v[8:9], v[0:1]
	s_nop 0
	v_addc_co_u32_e32 v135, vcc, 0, v129, vcc
	v_add_co_u32_e32 v128, vcc, 0xb0000, v128
	ds_bpermute_b32 v200, v214, v130
	ds_bpermute_b32 v201, v214, v131
	ds_bpermute_b32 v202, v214, v132
	ds_bpermute_b32 v203, v214, v133
	ds_bpermute_b32 v204, v214, v134
	ds_bpermute_b32 v205, v214, v135
	s_waitcnt lgkmcnt(6)
	global_store_dwordx4 v[212:213], v[208:211], off nt
	s_nop 0
	v_addc_co_u32_e32 v129, vcc, 0, v129, vcc
	v_pk_mul_f32 v[132:133], v[14:15], v[6:7]
	v_pk_mul_f32 v[130:131], v[12:13], v[4:5]
	v_pk_mul_f32 v[134:135], v[10:11], v[2:3]
	v_cvt_pk_bf16_f32 v130, v130, v131
	v_cvt_pk_bf16_f32 v131, v132, v133
	v_cvt_pk_bf16_f32 v132, v158, v159
	s_nop 0
	v_cvt_pk_bf16_f32 v133, v134, v135
	ds_bpermute_b32 v208, v214, v130
	ds_bpermute_b32 v209, v214, v131
	ds_bpermute_b32 v210, v214, v132
	ds_bpermute_b32 v211, v214, v133
	ds_bpermute_b32 v212, v214, v128
	ds_bpermute_b32 v213, v214, v129
	s_waitcnt lgkmcnt(6)
	global_store_dwordx4 v[204:205], v[200:203], off nt
	s_waitcnt lgkmcnt(0)
	global_store_dwordx4 v[212:213], v[208:211], off nt

; __device__ __forceinline__ u32x4 pack8(f32x4 v0, f32x4 v1) { u32x4 w; w.x = cvt_pk_bf16(v0[0], v0[1]); w.y = cvt_pk_bf16(v0[2], v0[3]); w.z = cvt_pk_bf16(v1[0], v1[1]); w.w = cvt_pk_bf16(v1[2], v1[3]); return w; }
;     __device__ __forceinline__ void operator()(const Acc& acc, const Unit& u, int wr, int wc, int fr, int fq) const {
;     ...
;             } else {
;                 bf16_t* base = (kind == 1 ? K : V) + ((size_t)(b * NH + 2 * (pn & 7)) * KVROWS + 64 + (pm & 15) * 256 + rloc) * HD + cl;
; #pragma unroll
;                 for (int ai = 0; ai < 2; ++ai)
; #pragma unroll
;                     for (int m = 0; m < 4; ++m)
; #pragma unroll
;                         for (int bj = 0; bj < 2; ++bj) *(u32x4*)(base + (size_t)bj * KVROWS * HD + (size_t)(ai * 128 + m * 16) * HD) = pack8(acc[ai][bj][m][0], acc[ai][bj][m][1]);
;             }
.LBB0_341:
	s_ashr_i32 s19, s2, 3
	s_and_b32 s17, s2, 7
	s_cmp_lt_u32 s2, 8
	s_cselect_b64 s[26:27], -1, 0
	s_cmp_gt_u32 s2, 7
	s_cselect_b64 s[28:29], -1, 0
	s_cmp_lg_u32 s19, 3
	s_cselect_b64 s[2:3], -1, 0
	s_and_b64 s[30:31], s[28:29], s[2:3]
	s_mov_b64 s[2:3], -1
	s_and_b64 vcc, exec, s[30:31]
	v_lshlrev_b32_e32 v158, 1, v148
	s_cbranch_vccz .LBB0_343
	s_cmp_eq_u32 s19, 1
	v_readlane_b32 s2, v248, 39
	v_readlane_b32 s3, v248, 41
	s_cselect_b32 s3, s2, s3
	v_readlane_b32 s2, v248, 38
	v_readlane_b32 s19, v248, 40
	s_cselect_b32 s2, s2, s19
	s_and_b32 s19, s24, -16
	s_lshl_b32 s25, s17, 1
	s_or_b32 s19, s25, s19
	s_lshl_b32 s25, s24, 8
	s_and_b32 s25, s25, 0xf00
	v_add_u32_e32 v146, s25, v161
	v_mad_i64_i32 v[128:129], s[30:31], s19, v165, v[146:147]
	v_lshlrev_b64 v[128:129], 8, v[128:129]
	v_lshl_add_u64 v[128:129], s[2:3], 0, v[128:129]
	v_mov_b32_e32 v159, v147
	v_lshl_add_u64 v[128:129], v[128:129], 0, v[158:159]
	s_mov_b32 s2, 0x105000
	v_add_co_u32_e32 v134, vcc, s2, v128
	v_cvt_pk_bf16_f32 v130, v124, v125
	v_cvt_pk_bf16_f32 v131, v126, v127
	v_cvt_pk_bf16_f32 v132, v120, v121
	v_cvt_pk_bf16_f32 v133, v122, v123
	s_nop 1
	v_addc_co_u32_e32 v135, vcc, 0, v129, vcc
	s_movk_i32 s2, 0x2000
	ds_bpermute_b32 v200, v214, v130
	ds_bpermute_b32 v201, v214, v131
	ds_bpermute_b32 v202, v214, v132
	ds_bpermute_b32 v203, v214, v133
	ds_bpermute_b32 v204, v214, v128
	ds_bpermute_b32 v205, v214, v129
	v_add_co_u32_e32 v166, vcc, s2, v128
	s_nop 0
	v_cvt_pk_bf16_f32 v130, v116, v117
	v_cvt_pk_bf16_f32 v131, v118, v119
	v_cvt_pk_bf16_f32 v132, v112, v113
	v_cvt_pk_bf16_f32 v133, v114, v115
	ds_bpermute_b32 v208, v214, v130
	ds_bpermute_b32 v209, v214, v131
	ds_bpermute_b32 v210, v214, v132
	ds_bpermute_b32 v211, v214, v133
	ds_bpermute_b32 v212, v214, v134
	ds_bpermute_b32 v213, v214, v135
	s_waitcnt lgkmcnt(6)
	global_store_dwordx4 v[204:205], v[200:203], off
	v_addc_co_u32_e32 v167, vcc, 0, v129, vcc
	s_nop 0
	v_cvt_pk_bf16_f32 v130, v108, v109
	v_cvt_pk_bf16_f32 v131, v110, v111
	v_cvt_pk_bf16_f32 v132, v104, v105
	v_cvt_pk_bf16_f32 v133, v106, v107
	s_mov_b32 s2, 0x107000
	ds_bpermute_b32 v200, v214, v130
	ds_bpermute_b32 v201, v214, v131
	ds_bpermute_b32 v202, v214, v132
	ds_bpermute_b32 v203, v214, v133
	ds_bpermute_b32 v204, v214, v166
	ds_bpermute_b32 v205, v214, v167
	s_waitcnt lgkmcnt(6)
	global_store_dwordx4 v[212:213], v[208:211], off offset:-4096
	s_nop 1
	v_cvt_pk_bf16_f32 v130, v100, v101
	v_cvt_pk_bf16_f32 v131, v102, v103
	v_cvt_pk_bf16_f32 v132, v96, v97
	v_cvt_pk_bf16_f32 v133, v98, v99
	ds_bpermute_b32 v208, v214, v130
	ds_bpermute_b32 v209, v214, v131
	ds_bpermute_b32 v210, v214, v132
	ds_bpermute_b32 v211, v214, v133
	ds_bpermute_b32 v212, v214, v134
	ds_bpermute_b32 v213, v214, v135
	s_waitcnt lgkmcnt(6)
	global_store_dwordx4 v[204:205], v[200:203], off offset:-4096
	v_add_co_u32_e32 v134, vcc, s2, v128
	s_nop 0
	v_cvt_pk_bf16_f32 v130, v92, v93
	v_cvt_pk_bf16_f32 v131, v94, v95
	v_cvt_pk_bf16_f32 v132, v88, v89
	v_cvt_pk_bf16_f32 v133, v90, v91
	s_nop 0
	v_addc_co_u32_e32 v135, vcc, 0, v129, vcc
	s_movk_i32 s2, 0x3000
	ds_bpermute_b32 v200, v214, v130
	ds_bpermute_b32 v201, v214, v131
	ds_bpermute_b32 v202, v214, v132
	ds_bpermute_b32 v203, v214, v133
	ds_bpermute_b32 v204, v214, v166
	ds_bpermute_b32 v205, v214, v167
	s_waitcnt lgkmcnt(6)
	global_store_dwordx4 v[212:213], v[208:211], off
	v_add_co_u32_e32 v166, vcc, s2, v128
	s_nop 0
	v_cvt_pk_bf16_f32 v130, v84, v85
	v_cvt_pk_bf16_f32 v131, v86, v87
	v_cvt_pk_bf16_f32 v132, v80, v81
	v_cvt_pk_bf16_f32 v133, v82, v83
	ds_bpermute_b32 v208, v214, v130
	ds_bpermute_b32 v209, v214, v131
	ds_bpermute_b32 v210, v214, v132
	ds_bpermute_b32 v211, v214, v133
	ds_bpermute_b32 v212, v214, v134
	ds_bpermute_b32 v213, v214, v135
	s_waitcnt lgkmcnt(6)
	global_store_dwordx4 v[204:205], v[200:203], off
	v_addc_co_u32_e32 v167, vcc, 0, v129, vcc
	s_nop 0
	v_cvt_pk_bf16_f32 v130, v76, v77
	v_cvt_pk_bf16_f32 v131, v78, v79
	v_cvt_pk_bf16_f32 v132, v72, v73
	v_cvt_pk_bf16_f32 v133, v74, v75
	s_mov_b32 s2, 0x9000
	ds_bpermute_b32 v200, v214, v130
	ds_bpermute_b32 v201, v214, v131
	ds_bpermute_b32 v202, v214, v132
	ds_bpermute_b32 v203, v214, v133
	ds_bpermute_b32 v204, v214, v166
	ds_bpermute_b32 v205, v214, v167
	s_waitcnt lgkmcnt(6)
; __device__ __forceinline__ u32x4 pack8(f32x4 v0, f32x4 v1) { u32x4 w; w.x = cvt_pk_bf16(v0[0], v0[1]); w.y = cvt_pk_bf16(v0[2], v0[3]); w.z = cvt_pk_bf16(v1[0], v1[1]); w.w = cvt_pk_bf16(v1[2], v1[3]); return w; }
;     __device__ __forceinline__ void operator()(const Acc& acc, const Unit& u, int wr, int wc, int fr, int fq) const {
;     ...
;             } else {
;                 bf16_t* base = (kind == 1 ? K : V) + ((size_t)(b * NH + 2 * (pn & 7)) * KVROWS + 64 + (pm & 15) * 256 + rloc) * HD + cl;
; #pragma unroll
;                 for (int ai = 0; ai < 2; ++ai)
; #pragma unroll
;                     for (int m = 0; m < 4; ++m)
; #pragma unroll
;                         for (int bj = 0; bj < 2; ++bj) *(u32x4*)(base + (size_t)bj * KVROWS * HD + (size_t)(ai * 128 + m * 16) * HD) = pack8(acc[ai][bj][m][0], acc[ai][bj][m][1]);
;             }
	global_store_dwordx4 v[212:213], v[208:211], off offset:-4096
	s_nop 1
	v_cvt_pk_bf16_f32 v130, v68, v69
	v_cvt_pk_bf16_f32 v131, v70, v71
	v_cvt_pk_bf16_f32 v132, v64, v65
	v_cvt_pk_bf16_f32 v133, v66, v67
	ds_bpermute_b32 v208, v214, v130
	ds_bpermute_b32 v209, v214, v131
	ds_bpermute_b32 v210, v214, v132
	ds_bpermute_b32 v211, v214, v133
	ds_bpermute_b32 v212, v214, v134
	ds_bpermute_b32 v213, v214, v135
	s_waitcnt lgkmcnt(6)
	global_store_dwordx4 v[204:205], v[200:203], off
	v_add_co_u32_e32 v134, vcc, s2, v128
	s_mov_b32 s2, 0x10d000
	s_nop 0
	v_addc_co_u32_e32 v135, vcc, 0, v129, vcc
	v_cvt_pk_bf16_f32 v130, v60, v61
	v_cvt_pk_bf16_f32 v131, v62, v63
	v_cvt_pk_bf16_f32 v132, v56, v57
	v_cvt_pk_bf16_f32 v133, v58, v59
	v_add_co_u32_e32 v166, vcc, s2, v128
	ds_bpermute_b32 v200, v214, v130
	ds_bpermute_b32 v201, v214, v131
	ds_bpermute_b32 v202, v214, v132
	ds_bpermute_b32 v203, v214, v133
	ds_bpermute_b32 v204, v214, v134
	ds_bpermute_b32 v205, v214, v135
	s_waitcnt lgkmcnt(6)
	global_store_dwordx4 v[212:213], v[208:211], off
	s_nop 0
	v_addc_co_u32_e32 v167, vcc, 0, v129, vcc
	v_cvt_pk_bf16_f32 v130, v52, v53
	v_cvt_pk_bf16_f32 v131, v54, v55
	v_cvt_pk_bf16_f32 v132, v48, v49
	v_cvt_pk_bf16_f32 v133, v50, v51
	s_mov_b32 s2, 0xb000
	ds_bpermute_b32 v208, v214, v130
	ds_bpermute_b32 v209, v214, v131
	ds_bpermute_b32 v210, v214, v132
	ds_bpermute_b32 v211, v214, v133
	ds_bpermute_b32 v212, v214, v166
	ds_bpermute_b32 v213, v214, v167
	s_waitcnt lgkmcnt(6)
	global_store_dwordx4 v[204:205], v[200:203], off offset:-4096
	s_nop 1
	v_cvt_pk_bf16_f32 v130, v44, v45
	v_cvt_pk_bf16_f32 v131, v46, v47
	v_cvt_pk_bf16_f32 v132, v40, v41
	v_cvt_pk_bf16_f32 v133, v42, v43
	ds_bpermute_b32 v200, v214, v130
	ds_bpermute_b32 v201, v214, v131
	ds_bpermute_b32 v202, v214, v132
	ds_bpermute_b32 v203, v214, v133
	ds_bpermute_b32 v204, v214, v134
	ds_bpermute_b32 v205, v214, v135
	s_waitcnt lgkmcnt(6)
	global_store_dwordx4 v[212:213], v[208:211], off offset:-4096
	v_add_co_u32_e32 v134, vcc, s2, v128
	s_mov_b32 s2, 0x10e000
	s_nop 0
	v_addc_co_u32_e32 v135, vcc, 0, v129, vcc
	v_cvt_pk_bf16_f32 v130, v36, v37
	v_cvt_pk_bf16_f32 v131, v38, v39
	v_cvt_pk_bf16_f32 v132, v32, v33
	v_cvt_pk_bf16_f32 v133, v34, v35
	ds_bpermute_b32 v208, v214, v130
	ds_bpermute_b32 v209, v214, v131
	ds_bpermute_b32 v210, v214, v132
	ds_bpermute_b32 v211, v214, v133
	ds_bpermute_b32 v212, v214, v166
	ds_bpermute_b32 v213, v214, v167
	s_waitcnt lgkmcnt(6)
	global_store_dwordx4 v[204:205], v[200:203], off
	v_add_co_u32_e32 v166, vcc, s2, v128
	s_nop 0
	v_cvt_pk_bf16_f32 v130, v28, v29
	v_cvt_pk_bf16_f32 v131, v30, v31
	v_cvt_pk_bf16_f32 v132, v24, v25
	v_cvt_pk_bf16_f32 v133, v26, v27
	s_nop 0
	v_addc_co_u32_e32 v167, vcc, 0, v129, vcc
	ds_bpermute_b32 v200, v214, v130
	ds_bpermute_b32 v201, v214, v131
	ds_bpermute_b32 v202, v214, v132
	ds_bpermute_b32 v203, v214, v133
	ds_bpermute_b32 v204, v214, v134
	ds_bpermute_b32 v205, v214, v135
	s_waitcnt lgkmcnt(6)
	global_store_dwordx4 v[212:213], v[208:211], off
	v_add_co_u32_e32 v128, vcc, 0x10f000, v128
	s_nop 0
	v_cvt_pk_bf16_f32 v130, v20, v21
	v_cvt_pk_bf16_f32 v131, v22, v23
	v_cvt_pk_bf16_f32 v132, v16, v17
	v_cvt_pk_bf16_f32 v133, v18, v19
	ds_bpermute_b32 v208, v214, v130
	ds_bpermute_b32 v209, v214, v131
	ds_bpermute_b32 v210, v214, v132
	ds_bpermute_b32 v211, v214, v133
	ds_bpermute_b32 v212, v214, v166
	ds_bpermute_b32 v213, v214, v167
	s_waitcnt lgkmcnt(6)
	global_store_dwordx4 v[204:205], v[200:203], off offset:-4096
	v_addc_co_u32_e32 v129, vcc, 0, v129, vcc
	s_nop 0
	v_cvt_pk_bf16_f32 v130, v12, v13
	v_cvt_pk_bf16_f32 v131, v14, v15
	v_cvt_pk_bf16_f32 v132, v8, v9
	v_cvt_pk_bf16_f32 v133, v10, v11
	ds_bpermute_b32 v200, v214, v130
	ds_bpermute_b32 v201, v214, v131
	ds_bpermute_b32 v202, v214, v132
	ds_bpermute_b32 v203, v214, v133
	ds_bpermute_b32 v204, v214, v134
	ds_bpermute_b32 v205, v214, v135
	s_waitcnt lgkmcnt(6)
	global_store_dwordx4 v[212:213], v[208:211], off
	s_mov_b64 s[2:3], 0
	s_nop 0
	v_cvt_pk_bf16_f32 v130, v4, v5
	v_cvt_pk_bf16_f32 v131, v6, v7
	v_cvt_pk_bf16_f32 v132, v0, v1
	v_cvt_pk_bf16_f32 v133, v2, v3
	ds_bpermute_b32 v208, v214, v130
	ds_bpermute_b32 v209, v214, v131
	ds_bpermute_b32 v210, v214, v132
	ds_bpermute_b32 v211, v214, v133
	ds_bpermute_b32 v212, v214, v128
	ds_bpermute_b32 v213, v214, v129
	s_waitcnt lgkmcnt(6)
	global_store_dwordx4 v[204:205], v[200:203], off
	s_waitcnt lgkmcnt(0)
	global_store_dwordx4 v[212:213], v[208:211], off

; __device__ __forceinline__ float siluf_(float x) { return x * sigmoidf_(x); }
; __device__ __forceinline__ u32x4 pack8(f32x4 v0, f32x4 v1) { u32x4 w; w.x = cvt_pk_bf16(v0[0], v0[1]); w.y = cvt_pk_bf16(v0[2], v0[3]); w.z = cvt_pk_bf16(v1[0], v1[1]); w.w = cvt_pk_bf16(v1[2], v1[3]); return w; }
;     __device__ __forceinline__ void operator()(const Acc& acc, const Unit& u, int wr, int wc, int fr, int fq) const {
;     ...
;             if (kind == 0 || kind == 3) {
;                 bf16_t* base = (kind == 0 ? Q : Z) + (size_t)(pm * 256 + rloc) * DM + colt;
; #pragma unroll
;                 for (int ai = 0; ai < 2; ++ai)
; #pragma unroll
;                     for (int m = 0; m < 4; ++m)
; #pragma unroll
;                         for (int bj = 0; bj < 2; ++bj) { f32x4 v0 = acc[ai][bj][m][0], v1 = acc[ai][bj][m][1];
;                             if (kind == 0) { v0 = v0 * QSCALE; v1 = v1 * QSCALE; }
;                             else {
; #pragma unroll
;                                 for (int j = 0; j < 4; ++j) { v0[j] = siluf_(v0[j]); v1[j] = siluf_(v1[j]); } }
;                             *(u32x4*)(base + (size_t)(ai * 128 + m * 16) * DM + bj * 128) = pack8(v0, v1); }
.LBB0_348:
	s_and_b64 s[26:27], s[26:27], exec
	v_readlane_b32 s19, v248, 37
	v_readlane_b32 s25, v248, 43
	v_lshl_add_u32 v120, s24, 8, v137
	s_cselect_b32 s27, s19, s25
	v_readlane_b32 s19, v248, 42
	v_ashrrev_i32_e32 v121, 31, v120
	s_cselect_b32 s26, s93, s19
	v_lshlrev_b64 v[120:121], 12, v[120:121]
	v_lshl_add_u64 v[120:121], s[26:27], 0, v[120:121]
	v_lshl_or_b32 v146, s17, 9, v158
	v_lshl_add_u64 v[158:159], v[120:121], 0, v[146:147]
	v_cvt_pk_bf16_f32 v120, v128, v129
	v_cvt_pk_bf16_f32 v121, v130, v131
	v_cvt_pk_bf16_f32 v122, v132, v133
	v_cvt_pk_bf16_f32 v123, v134, v135
	s_and_b64 vcc, exec, s[2:3]
	s_mov_b64 s[24:25], -1
	ds_bpermute_b32 v200, v214, v120
	ds_bpermute_b32 v201, v214, v121
	ds_bpermute_b32 v202, v214, v122
	ds_bpermute_b32 v203, v214, v123
	ds_bpermute_b32 v204, v214, v158
	ds_bpermute_b32 v205, v214, v159
	s_waitcnt lgkmcnt(0)
	global_store_dwordx4 v[204:205], v[200:203], off
	s_cbranch_vccnz .LBB0_350
	s_nop 0
	v_mul_f32_e32 v121, 0xbfb8aa3b, v112
	v_mul_f32_e32 v122, 0xbfb8aa3b, v117
	v_exp_f32_e32 v121, v121
	v_exp_f32_e32 v122, v122
	v_mul_f32_e32 v123, 0xbfb8aa3b, v118
	v_mul_f32_e32 v125, 0xbfb8aa3b, v114
	v_add_f32_e32 v121, 1.0, v121
	v_rcp_f32_e32 v124, v121
	v_add_f32_e32 v121, 1.0, v122
	v_mul_f32_e32 v122, 0xbfb8aa3b, v113
	v_exp_f32_e32 v122, v122
	v_exp_f32_e32 v123, v123
	v_exp_f32_e32 v125, v125
	v_mul_f32_e32 v120, 0xbfb8aa3b, v116
	v_add_f32_e32 v128, 1.0, v122
	v_add_f32_e32 v122, 1.0, v123
	v_add_f32_e32 v123, 1.0, v125
	v_mul_f32_e32 v125, 0xbfb8aa3b, v119
	v_mul_f32_e32 v126, 0xbfb8aa3b, v115
	v_exp_f32_e32 v120, v120
	v_exp_f32_e32 v125, v125
	v_exp_f32_e32 v127, v126
	v_rcp_f32_e32 v126, v123
	v_add_f32_e32 v120, 1.0, v120
	v_add_f32_e32 v123, 1.0, v125
	v_add_f32_e32 v125, 1.0, v127
	v_rcp_f32_e32 v120, v120
	v_rcp_f32_e32 v121, v121
	v_rcp_f32_e32 v122, v122
	v_rcp_f32_e32 v123, v123
	v_rcp_f32_e32 v127, v125
	v_rcp_f32_e32 v125, v128
	v_pk_mul_f32 v[120:121], v[116:117], v[120:121]
	v_pk_mul_f32 v[122:123], v[118:119], v[122:123]
	v_pk_mul_f32 v[126:127], v[114:115], v[126:127]
	v_pk_mul_f32 v[124:125], v[112:113], v[124:125]
	s_mov_b64 s[24:25], 0

; __device__ __forceinline__ float siluf_(float x) { return x * sigmoidf_(x); }
; __device__ __forceinline__ u32x4 pack8(f32x4 v0, f32x4 v1) { u32x4 w; w.x = cvt_pk_bf16(v0[0], v0[1]); w.y = cvt_pk_bf16(v0[2], v0[3]); w.z = cvt_pk_bf16(v1[0], v1[1]); w.w = cvt_pk_bf16(v1[2], v1[3]); return w; }
;     __device__ __forceinline__ void operator()(const Acc& acc, const Unit& u, int wr, int wc, int fr, int fq) const {
;     ...
;             if (kind == 0 || kind == 3) {
;                 bf16_t* base = (kind == 0 ? Q : Z) + (size_t)(pm * 256 + rloc) * DM + colt;
; #pragma unroll
;                 for (int ai = 0; ai < 2; ++ai)
; #pragma unroll
;                     for (int m = 0; m < 4; ++m)
; #pragma unroll
;                         for (int bj = 0; bj < 2; ++bj) { f32x4 v0 = acc[ai][bj][m][0], v1 = acc[ai][bj][m][1];
;                             if (kind == 0) { v0 = v0 * QSCALE; v1 = v1 * QSCALE; }
;                             else {
; #pragma unroll
;                                 for (int j = 0; j < 4; ++j) { v0[j] = siluf_(v0[j]); v1[j] = siluf_(v1[j]); } }
;                             *(u32x4*)(base + (size_t)(ai * 128 + m * 16) * DM + bj * 128) = pack8(v0, v1); }
.LBB0_352:
	v_cvt_pk_bf16_f32 v112, v120, v121
	v_cvt_pk_bf16_f32 v113, v122, v123
	s_nop 0
	v_cvt_pk_bf16_f32 v114, v124, v125
	v_cvt_pk_bf16_f32 v115, v126, v127
	s_and_b64 vcc, exec, s[2:3]
	s_mov_b64 s[24:25], -1
	ds_bpermute_b32 v208, v214, v112
	ds_bpermute_b32 v209, v214, v113
	ds_bpermute_b32 v210, v214, v114
	ds_bpermute_b32 v211, v214, v115
	ds_bpermute_b32 v212, v214, v158
	ds_bpermute_b32 v213, v214, v159
	s_waitcnt lgkmcnt(0)
	global_store_dwordx4 v[212:213], v[208:211], off offset:256
	s_cbranch_vccnz .LBB0_354
	s_nop 0
	v_mul_f32_e32 v113, 0xbfb8aa3b, v104
	v_mul_f32_e32 v114, 0xbfb8aa3b, v109
	v_exp_f32_e32 v113, v113
	v_exp_f32_e32 v114, v114
	v_mul_f32_e32 v115, 0xbfb8aa3b, v110
	v_mul_f32_e32 v117, 0xbfb8aa3b, v106
	v_add_f32_e32 v113, 1.0, v113
	v_rcp_f32_e32 v116, v113
	v_add_f32_e32 v113, 1.0, v114
	v_mul_f32_e32 v114, 0xbfb8aa3b, v105
	v_exp_f32_e32 v114, v114
	v_exp_f32_e32 v115, v115
	v_exp_f32_e32 v117, v117
	v_mul_f32_e32 v112, 0xbfb8aa3b, v108
	v_add_f32_e32 v120, 1.0, v114
	v_add_f32_e32 v114, 1.0, v115
	v_add_f32_e32 v115, 1.0, v117
	v_mul_f32_e32 v117, 0xbfb8aa3b, v111
	v_mul_f32_e32 v118, 0xbfb8aa3b, v107
	v_exp_f32_e32 v112, v112
	v_exp_f32_e32 v117, v117
	v_exp_f32_e32 v119, v118
	v_rcp_f32_e32 v118, v115
	v_add_f32_e32 v112, 1.0, v112
	v_add_f32_e32 v115, 1.0, v117
	v_add_f32_e32 v117, 1.0, v119
	v_rcp_f32_e32 v112, v112
	v_rcp_f32_e32 v113, v113
	v_rcp_f32_e32 v114, v114
	v_rcp_f32_e32 v115, v115
	v_rcp_f32_e32 v119, v117
	v_rcp_f32_e32 v117, v120
	v_pk_mul_f32 v[112:113], v[108:109], v[112:113]
	v_pk_mul_f32 v[114:115], v[110:111], v[114:115]
	v_pk_mul_f32 v[118:119], v[106:107], v[118:119]
	v_pk_mul_f32 v[116:117], v[104:105], v[116:117]
	s_mov_b64 s[24:25], 0

; __device__ __forceinline__ float siluf_(float x) { return x * sigmoidf_(x); }
; __device__ __forceinline__ u32x4 pack8(f32x4 v0, f32x4 v1) { u32x4 w; w.x = cvt_pk_bf16(v0[0], v0[1]); w.y = cvt_pk_bf16(v0[2], v0[3]); w.z = cvt_pk_bf16(v1[0], v1[1]); w.w = cvt_pk_bf16(v1[2], v1[3]); return w; }
;     __device__ __forceinline__ void operator()(const Acc& acc, const Unit& u, int wr, int wc, int fr, int fq) const {
;     ...
;             if (kind == 0 || kind == 3) {
;                 bf16_t* base = (kind == 0 ? Q : Z) + (size_t)(pm * 256 + rloc) * DM + colt;
; #pragma unroll
;                 for (int ai = 0; ai < 2; ++ai)
; #pragma unroll
;                     for (int m = 0; m < 4; ++m)
; #pragma unroll
;                         for (int bj = 0; bj < 2; ++bj) { f32x4 v0 = acc[ai][bj][m][0], v1 = acc[ai][bj][m][1];
;                             if (kind == 0) { v0 = v0 * QSCALE; v1 = v1 * QSCALE; }
;                             else {
; #pragma unroll
;                                 for (int j = 0; j < 4; ++j) { v0[j] = siluf_(v0[j]); v1[j] = siluf_(v1[j]); } }
;                             *(u32x4*)(base + (size_t)(ai * 128 + m * 16) * DM + bj * 128) = pack8(v0, v1); }
.LBB0_356:
	v_add_co_u32_e32 v108, vcc, 0x10000, v158
	v_cvt_pk_bf16_f32 v104, v112, v113
	v_cvt_pk_bf16_f32 v105, v114, v115
	v_cvt_pk_bf16_f32 v106, v116, v117
	v_cvt_pk_bf16_f32 v107, v118, v119
	s_nop 1
	v_addc_co_u32_e32 v109, vcc, 0, v159, vcc
	s_and_b64 vcc, exec, s[2:3]
	s_mov_b64 s[24:25], -1
	ds_bpermute_b32 v200, v214, v104
	ds_bpermute_b32 v201, v214, v105
	ds_bpermute_b32 v202, v214, v106
	ds_bpermute_b32 v203, v214, v107
	ds_bpermute_b32 v204, v214, v108
	ds_bpermute_b32 v205, v214, v109
	s_waitcnt lgkmcnt(0)
	global_store_dwordx4 v[204:205], v[200:203], off
	s_cbranch_vccnz .LBB0_358
	s_nop 0
	v_mul_f32_e32 v105, 0xbfb8aa3b, v96
	v_mul_f32_e32 v106, 0xbfb8aa3b, v101
	v_exp_f32_e32 v105, v105
	v_exp_f32_e32 v106, v106
	v_mul_f32_e32 v107, 0xbfb8aa3b, v102
	v_mul_f32_e32 v109, 0xbfb8aa3b, v98
	v_add_f32_e32 v105, 1.0, v105
	v_rcp_f32_e32 v108, v105
	v_add_f32_e32 v105, 1.0, v106
	v_mul_f32_e32 v106, 0xbfb8aa3b, v97
	v_exp_f32_e32 v106, v106
	v_exp_f32_e32 v107, v107
	v_exp_f32_e32 v109, v109
	v_mul_f32_e32 v104, 0xbfb8aa3b, v100
	v_add_f32_e32 v112, 1.0, v106
	v_add_f32_e32 v106, 1.0, v107
	v_add_f32_e32 v107, 1.0, v109
	v_mul_f32_e32 v109, 0xbfb8aa3b, v103
	v_mul_f32_e32 v110, 0xbfb8aa3b, v99
	v_exp_f32_e32 v104, v104
	v_exp_f32_e32 v109, v109
	v_exp_f32_e32 v111, v110
	v_rcp_f32_e32 v110, v107
	v_add_f32_e32 v104, 1.0, v104
	v_add_f32_e32 v107, 1.0, v109
	v_add_f32_e32 v109, 1.0, v111
	v_rcp_f32_e32 v104, v104
	v_rcp_f32_e32 v105, v105
	v_rcp_f32_e32 v106, v106
	v_rcp_f32_e32 v107, v107
	v_rcp_f32_e32 v111, v109
	v_rcp_f32_e32 v109, v112
	v_pk_mul_f32 v[104:105], v[100:101], v[104:105]
	v_pk_mul_f32 v[106:107], v[102:103], v[106:107]
	v_pk_mul_f32 v[110:111], v[98:99], v[110:111]
	v_pk_mul_f32 v[108:109], v[96:97], v[108:109]
	s_mov_b64 s[24:25], 0

; __device__ __forceinline__ float siluf_(float x) { return x * sigmoidf_(x); }
; __device__ __forceinline__ u32x4 pack8(f32x4 v0, f32x4 v1) { u32x4 w; w.x = cvt_pk_bf16(v0[0], v0[1]); w.y = cvt_pk_bf16(v0[2], v0[3]); w.z = cvt_pk_bf16(v1[0], v1[1]); w.w = cvt_pk_bf16(v1[2], v1[3]); return w; }
;     __device__ __forceinline__ void operator()(const Acc& acc, const Unit& u, int wr, int wc, int fr, int fq) const {
;     ...
;             if (kind == 0 || kind == 3) {
;                 bf16_t* base = (kind == 0 ? Q : Z) + (size_t)(pm * 256 + rloc) * DM + colt;
; #pragma unroll
;                 for (int ai = 0; ai < 2; ++ai)
; #pragma unroll
;                     for (int m = 0; m < 4; ++m)
; #pragma unroll
;                         for (int bj = 0; bj < 2; ++bj) { f32x4 v0 = acc[ai][bj][m][0], v1 = acc[ai][bj][m][1];
;                             if (kind == 0) { v0 = v0 * QSCALE; v1 = v1 * QSCALE; }
;                             else {
; #pragma unroll
;                                 for (int j = 0; j < 4; ++j) { v0[j] = siluf_(v0[j]); v1[j] = siluf_(v1[j]); } }
;                             *(u32x4*)(base + (size_t)(ai * 128 + m * 16) * DM + bj * 128) = pack8(v0, v1); }
.LBB0_360:
	v_add_co_u32_e32 v100, vcc, 0x10000, v158
	v_cvt_pk_bf16_f32 v96, v104, v105
	v_cvt_pk_bf16_f32 v97, v106, v107
	v_cvt_pk_bf16_f32 v98, v108, v109
	v_cvt_pk_bf16_f32 v99, v110, v111
	s_nop 1
	v_addc_co_u32_e32 v101, vcc, 0, v159, vcc
	s_and_b64 vcc, exec, s[2:3]
	s_mov_b64 s[24:25], -1
	ds_bpermute_b32 v208, v214, v96
	ds_bpermute_b32 v209, v214, v97
	ds_bpermute_b32 v210, v214, v98
	ds_bpermute_b32 v211, v214, v99
	ds_bpermute_b32 v212, v214, v100
	ds_bpermute_b32 v213, v214, v101
	s_waitcnt lgkmcnt(0)
	global_store_dwordx4 v[212:213], v[208:211], off offset:256
	s_cbranch_vccnz .LBB0_362
	s_nop 0
	v_mul_f32_e32 v97, 0xbfb8aa3b, v88
	v_mul_f32_e32 v98, 0xbfb8aa3b, v93
	v_exp_f32_e32 v97, v97
	v_exp_f32_e32 v98, v98
	v_mul_f32_e32 v99, 0xbfb8aa3b, v94
	v_mul_f32_e32 v101, 0xbfb8aa3b, v90
	v_add_f32_e32 v97, 1.0, v97
	v_rcp_f32_e32 v100, v97
	v_add_f32_e32 v97, 1.0, v98
	v_mul_f32_e32 v98, 0xbfb8aa3b, v89
	v_exp_f32_e32 v98, v98
	v_exp_f32_e32 v99, v99
	v_exp_f32_e32 v101, v101
	v_mul_f32_e32 v96, 0xbfb8aa3b, v92
	v_add_f32_e32 v104, 1.0, v98
	v_add_f32_e32 v98, 1.0, v99
	v_add_f32_e32 v99, 1.0, v101
	v_mul_f32_e32 v101, 0xbfb8aa3b, v95
	v_mul_f32_e32 v102, 0xbfb8aa3b, v91
	v_exp_f32_e32 v96, v96
	v_exp_f32_e32 v101, v101
	v_exp_f32_e32 v103, v102
	v_rcp_f32_e32 v102, v99
	v_add_f32_e32 v96, 1.0, v96
	v_add_f32_e32 v99, 1.0, v101
	v_add_f32_e32 v101, 1.0, v103
	v_rcp_f32_e32 v96, v96
	v_rcp_f32_e32 v97, v97
	v_rcp_f32_e32 v98, v98
	v_rcp_f32_e32 v99, v99
	v_rcp_f32_e32 v103, v101
	v_rcp_f32_e32 v101, v104
	v_pk_mul_f32 v[96:97], v[92:93], v[96:97]
	v_pk_mul_f32 v[98:99], v[94:95], v[98:99]
	v_pk_mul_f32 v[102:103], v[90:91], v[102:103]
	v_pk_mul_f32 v[100:101], v[88:89], v[100:101]
	s_mov_b64 s[24:25], 0

; __device__ __forceinline__ float siluf_(float x) { return x * sigmoidf_(x); }
; __device__ __forceinline__ u32x4 pack8(f32x4 v0, f32x4 v1) { u32x4 w; w.x = cvt_pk_bf16(v0[0], v0[1]); w.y = cvt_pk_bf16(v0[2], v0[3]); w.z = cvt_pk_bf16(v1[0], v1[1]); w.w = cvt_pk_bf16(v1[2], v1[3]); return w; }
;     __device__ __forceinline__ void operator()(const Acc& acc, const Unit& u, int wr, int wc, int fr, int fq) const {
;     ...
;             if (kind == 0 || kind == 3) {
;                 bf16_t* base = (kind == 0 ? Q : Z) + (size_t)(pm * 256 + rloc) * DM + colt;
; #pragma unroll
;                 for (int ai = 0; ai < 2; ++ai)
; #pragma unroll
;                     for (int m = 0; m < 4; ++m)
; #pragma unroll
;                         for (int bj = 0; bj < 2; ++bj) { f32x4 v0 = acc[ai][bj][m][0], v1 = acc[ai][bj][m][1];
;                             if (kind == 0) { v0 = v0 * QSCALE; v1 = v1 * QSCALE; }
;                             else {
; #pragma unroll
;                                 for (int j = 0; j < 4; ++j) { v0[j] = siluf_(v0[j]); v1[j] = siluf_(v1[j]); } }
;                             *(u32x4*)(base + (size_t)(ai * 128 + m * 16) * DM + bj * 128) = pack8(v0, v1); }
.LBB0_364:
	v_add_co_u32_e32 v92, vcc, 0x20000, v158
	v_cvt_pk_bf16_f32 v88, v96, v97
	v_cvt_pk_bf16_f32 v89, v98, v99
	v_cvt_pk_bf16_f32 v90, v100, v101
	v_cvt_pk_bf16_f32 v91, v102, v103
	s_nop 1
	v_addc_co_u32_e32 v93, vcc, 0, v159, vcc
	s_and_b64 vcc, exec, s[2:3]
	s_mov_b64 s[24:25], -1
	ds_bpermute_b32 v200, v214, v88
	ds_bpermute_b32 v201, v214, v89
	ds_bpermute_b32 v202, v214, v90
	ds_bpermute_b32 v203, v214, v91
	ds_bpermute_b32 v204, v214, v92
	ds_bpermute_b32 v205, v214, v93
	s_waitcnt lgkmcnt(0)
	global_store_dwordx4 v[204:205], v[200:203], off
	s_cbranch_vccnz .LBB0_366
	s_nop 0
	v_mul_f32_e32 v89, 0xbfb8aa3b, v80
	v_mul_f32_e32 v90, 0xbfb8aa3b, v85
	v_exp_f32_e32 v89, v89
	v_exp_f32_e32 v90, v90
	v_mul_f32_e32 v91, 0xbfb8aa3b, v86
	v_mul_f32_e32 v93, 0xbfb8aa3b, v82
	v_add_f32_e32 v89, 1.0, v89
	v_rcp_f32_e32 v92, v89
	v_add_f32_e32 v89, 1.0, v90
	v_mul_f32_e32 v90, 0xbfb8aa3b, v81
	v_exp_f32_e32 v90, v90
	v_exp_f32_e32 v91, v91
	v_exp_f32_e32 v93, v93
	v_mul_f32_e32 v88, 0xbfb8aa3b, v84
	v_add_f32_e32 v96, 1.0, v90
	v_add_f32_e32 v90, 1.0, v91
	v_add_f32_e32 v91, 1.0, v93
	v_mul_f32_e32 v93, 0xbfb8aa3b, v87
	v_mul_f32_e32 v94, 0xbfb8aa3b, v83
	v_exp_f32_e32 v88, v88
	v_exp_f32_e32 v93, v93
	v_exp_f32_e32 v95, v94
	v_rcp_f32_e32 v94, v91
	v_add_f32_e32 v88, 1.0, v88
	v_add_f32_e32 v91, 1.0, v93
	v_add_f32_e32 v93, 1.0, v95
	v_rcp_f32_e32 v88, v88
	v_rcp_f32_e32 v89, v89
	v_rcp_f32_e32 v90, v90
	v_rcp_f32_e32 v91, v91
	v_rcp_f32_e32 v95, v93
	v_rcp_f32_e32 v93, v96
	v_pk_mul_f32 v[88:89], v[84:85], v[88:89]
	v_pk_mul_f32 v[90:91], v[86:87], v[90:91]
	v_pk_mul_f32 v[94:95], v[82:83], v[94:95]
	v_pk_mul_f32 v[92:93], v[80:81], v[92:93]
	s_mov_b64 s[24:25], 0

; __device__ __forceinline__ float siluf_(float x) { return x * sigmoidf_(x); }
; __device__ __forceinline__ u32x4 pack8(f32x4 v0, f32x4 v1) { u32x4 w; w.x = cvt_pk_bf16(v0[0], v0[1]); w.y = cvt_pk_bf16(v0[2], v0[3]); w.z = cvt_pk_bf16(v1[0], v1[1]); w.w = cvt_pk_bf16(v1[2], v1[3]); return w; }
;     __device__ __forceinline__ void operator()(const Acc& acc, const Unit& u, int wr, int wc, int fr, int fq) const {
;     ...
;             if (kind == 0 || kind == 3) {
;                 bf16_t* base = (kind == 0 ? Q : Z) + (size_t)(pm * 256 + rloc) * DM + colt;
; #pragma unroll
;                 for (int ai = 0; ai < 2; ++ai)
; #pragma unroll
;                     for (int m = 0; m < 4; ++m)
; #pragma unroll
;                         for (int bj = 0; bj < 2; ++bj) { f32x4 v0 = acc[ai][bj][m][0], v1 = acc[ai][bj][m][1];
;                             if (kind == 0) { v0 = v0 * QSCALE; v1 = v1 * QSCALE; }
;                             else {
; #pragma unroll
;                                 for (int j = 0; j < 4; ++j) { v0[j] = siluf_(v0[j]); v1[j] = siluf_(v1[j]); } }
;                             *(u32x4*)(base + (size_t)(ai * 128 + m * 16) * DM + bj * 128) = pack8(v0, v1); }
.LBB0_368:
	v_add_co_u32_e32 v84, vcc, 0x20000, v158
	v_cvt_pk_bf16_f32 v80, v88, v89
	v_cvt_pk_bf16_f32 v81, v90, v91
	v_cvt_pk_bf16_f32 v82, v92, v93
	v_cvt_pk_bf16_f32 v83, v94, v95
	s_nop 1
	v_addc_co_u32_e32 v85, vcc, 0, v159, vcc
	s_and_b64 vcc, exec, s[2:3]
	s_mov_b64 s[24:25], -1
	ds_bpermute_b32 v208, v214, v80
	ds_bpermute_b32 v209, v214, v81
	ds_bpermute_b32 v210, v214, v82
	ds_bpermute_b32 v211, v214, v83
	ds_bpermute_b32 v212, v214, v84
	ds_bpermute_b32 v213, v214, v85
	s_waitcnt lgkmcnt(0)
	global_store_dwordx4 v[212:213], v[208:211], off offset:256
	s_cbranch_vccnz .LBB0_370
	s_nop 0
	v_mul_f32_e32 v81, 0xbfb8aa3b, v72
	v_mul_f32_e32 v82, 0xbfb8aa3b, v77
	v_exp_f32_e32 v81, v81
	v_exp_f32_e32 v82, v82
	v_mul_f32_e32 v83, 0xbfb8aa3b, v78
	v_mul_f32_e32 v85, 0xbfb8aa3b, v74
	v_add_f32_e32 v81, 1.0, v81
	v_rcp_f32_e32 v84, v81
	v_add_f32_e32 v81, 1.0, v82
	v_mul_f32_e32 v82, 0xbfb8aa3b, v73
	v_exp_f32_e32 v82, v82
	v_exp_f32_e32 v83, v83
	v_exp_f32_e32 v85, v85
	v_mul_f32_e32 v80, 0xbfb8aa3b, v76
	v_add_f32_e32 v88, 1.0, v82
	v_add_f32_e32 v82, 1.0, v83
	v_add_f32_e32 v83, 1.0, v85
	v_mul_f32_e32 v85, 0xbfb8aa3b, v79
	v_mul_f32_e32 v86, 0xbfb8aa3b, v75
	v_exp_f32_e32 v80, v80
	v_exp_f32_e32 v85, v85
	v_exp_f32_e32 v87, v86
	v_rcp_f32_e32 v86, v83
	v_add_f32_e32 v80, 1.0, v80
	v_add_f32_e32 v83, 1.0, v85
	v_add_f32_e32 v85, 1.0, v87
	v_rcp_f32_e32 v80, v80
	v_rcp_f32_e32 v81, v81
	v_rcp_f32_e32 v82, v82
	v_rcp_f32_e32 v83, v83
	v_rcp_f32_e32 v87, v85
	v_rcp_f32_e32 v85, v88
	v_pk_mul_f32 v[80:81], v[76:77], v[80:81]
	v_pk_mul_f32 v[82:83], v[78:79], v[82:83]
	v_pk_mul_f32 v[86:87], v[74:75], v[86:87]
	v_pk_mul_f32 v[84:85], v[72:73], v[84:85]
	s_mov_b64 s[24:25], 0

; __device__ __forceinline__ float siluf_(float x) { return x * sigmoidf_(x); }
; __device__ __forceinline__ u32x4 pack8(f32x4 v0, f32x4 v1) { u32x4 w; w.x = cvt_pk_bf16(v0[0], v0[1]); w.y = cvt_pk_bf16(v0[2], v0[3]); w.z = cvt_pk_bf16(v1[0], v1[1]); w.w = cvt_pk_bf16(v1[2], v1[3]); return w; }
;     __device__ __forceinline__ void operator()(const Acc& acc, const Unit& u, int wr, int wc, int fr, int fq) const {
;     ...
;             if (kind == 0 || kind == 3) {
;                 bf16_t* base = (kind == 0 ? Q : Z) + (size_t)(pm * 256 + rloc) * DM + colt;
; #pragma unroll
;                 for (int ai = 0; ai < 2; ++ai)
; #pragma unroll
;                     for (int m = 0; m < 4; ++m)
; #pragma unroll
;                         for (int bj = 0; bj < 2; ++bj) { f32x4 v0 = acc[ai][bj][m][0], v1 = acc[ai][bj][m][1];
;                             if (kind == 0) { v0 = v0 * QSCALE; v1 = v1 * QSCALE; }
;                             else {
; #pragma unroll
;                                 for (int j = 0; j < 4; ++j) { v0[j] = siluf_(v0[j]); v1[j] = siluf_(v1[j]); } }
;                             *(u32x4*)(base + (size_t)(ai * 128 + m * 16) * DM + bj * 128) = pack8(v0, v1); }
.LBB0_372:
	v_add_co_u32_e32 v76, vcc, 0x30000, v158
	v_cvt_pk_bf16_f32 v72, v80, v81
	v_cvt_pk_bf16_f32 v73, v82, v83
	v_cvt_pk_bf16_f32 v74, v84, v85
	v_cvt_pk_bf16_f32 v75, v86, v87
	s_nop 1
	v_addc_co_u32_e32 v77, vcc, 0, v159, vcc
	s_and_b64 vcc, exec, s[2:3]
	s_mov_b64 s[24:25], -1
	ds_bpermute_b32 v200, v214, v72
	ds_bpermute_b32 v201, v214, v73
	ds_bpermute_b32 v202, v214, v74
	ds_bpermute_b32 v203, v214, v75
	ds_bpermute_b32 v204, v214, v76
	ds_bpermute_b32 v205, v214, v77
	s_waitcnt lgkmcnt(0)
	global_store_dwordx4 v[204:205], v[200:203], off
	s_cbranch_vccnz .LBB0_374
	s_nop 0
	v_mul_f32_e32 v73, 0xbfb8aa3b, v64
	v_mul_f32_e32 v74, 0xbfb8aa3b, v69
	v_exp_f32_e32 v73, v73
	v_exp_f32_e32 v74, v74
	v_mul_f32_e32 v75, 0xbfb8aa3b, v70
	v_mul_f32_e32 v77, 0xbfb8aa3b, v66
	v_add_f32_e32 v73, 1.0, v73
	v_rcp_f32_e32 v76, v73
	v_add_f32_e32 v73, 1.0, v74
	v_mul_f32_e32 v74, 0xbfb8aa3b, v65
	v_exp_f32_e32 v74, v74
	v_exp_f32_e32 v75, v75
	v_exp_f32_e32 v77, v77
	v_mul_f32_e32 v72, 0xbfb8aa3b, v68
	v_add_f32_e32 v80, 1.0, v74
	v_add_f32_e32 v74, 1.0, v75
	v_add_f32_e32 v75, 1.0, v77
	v_mul_f32_e32 v77, 0xbfb8aa3b, v71
	v_mul_f32_e32 v78, 0xbfb8aa3b, v67
	v_exp_f32_e32 v72, v72
	v_exp_f32_e32 v77, v77
	v_exp_f32_e32 v79, v78
	v_rcp_f32_e32 v78, v75
	v_add_f32_e32 v72, 1.0, v72
	v_add_f32_e32 v75, 1.0, v77
	v_add_f32_e32 v77, 1.0, v79
	v_rcp_f32_e32 v72, v72
	v_rcp_f32_e32 v73, v73
	v_rcp_f32_e32 v74, v74
	v_rcp_f32_e32 v75, v75
	v_rcp_f32_e32 v79, v77
	v_rcp_f32_e32 v77, v80
	v_pk_mul_f32 v[72:73], v[68:69], v[72:73]
	v_pk_mul_f32 v[74:75], v[70:71], v[74:75]
	v_pk_mul_f32 v[78:79], v[66:67], v[78:79]
	v_pk_mul_f32 v[76:77], v[64:65], v[76:77]
	s_mov_b64 s[24:25], 0

; __device__ __forceinline__ float siluf_(float x) { return x * sigmoidf_(x); }
; __device__ __forceinline__ u32x4 pack8(f32x4 v0, f32x4 v1) { u32x4 w; w.x = cvt_pk_bf16(v0[0], v0[1]); w.y = cvt_pk_bf16(v0[2], v0[3]); w.z = cvt_pk_bf16(v1[0], v1[1]); w.w = cvt_pk_bf16(v1[2], v1[3]); return w; }
;     __device__ __forceinline__ void operator()(const Acc& acc, const Unit& u, int wr, int wc, int fr, int fq) const {
;     ...
;             if (kind == 0 || kind == 3) {
;                 bf16_t* base = (kind == 0 ? Q : Z) + (size_t)(pm * 256 + rloc) * DM + colt;
; #pragma unroll
;                 for (int ai = 0; ai < 2; ++ai)
; #pragma unroll
;                     for (int m = 0; m < 4; ++m)
; #pragma unroll
;                         for (int bj = 0; bj < 2; ++bj) { f32x4 v0 = acc[ai][bj][m][0], v1 = acc[ai][bj][m][1];
;                             if (kind == 0) { v0 = v0 * QSCALE; v1 = v1 * QSCALE; }
;                             else {
; #pragma unroll
;                                 for (int j = 0; j < 4; ++j) { v0[j] = siluf_(v0[j]); v1[j] = siluf_(v1[j]); } }
;                             *(u32x4*)(base + (size_t)(ai * 128 + m * 16) * DM + bj * 128) = pack8(v0, v1); }
.LBB0_376:
	v_add_co_u32_e32 v68, vcc, 0x30000, v158
	v_cvt_pk_bf16_f32 v64, v72, v73
	v_cvt_pk_bf16_f32 v65, v74, v75
	v_cvt_pk_bf16_f32 v66, v76, v77
	v_cvt_pk_bf16_f32 v67, v78, v79
	s_nop 1
	v_addc_co_u32_e32 v69, vcc, 0, v159, vcc
	s_and_b64 vcc, exec, s[2:3]
	s_mov_b64 s[24:25], -1
	ds_bpermute_b32 v208, v214, v64
	ds_bpermute_b32 v209, v214, v65
	ds_bpermute_b32 v210, v214, v66
	ds_bpermute_b32 v211, v214, v67
	ds_bpermute_b32 v212, v214, v68
	ds_bpermute_b32 v213, v214, v69
	s_waitcnt lgkmcnt(0)
	global_store_dwordx4 v[212:213], v[208:211], off offset:256
	s_cbranch_vccnz .LBB0_378
	s_nop 0
	v_mul_f32_e32 v65, 0xbfb8aa3b, v56
	v_mul_f32_e32 v66, 0xbfb8aa3b, v61
	v_exp_f32_e32 v65, v65
	v_exp_f32_e32 v66, v66
	v_mul_f32_e32 v67, 0xbfb8aa3b, v62
	v_mul_f32_e32 v69, 0xbfb8aa3b, v58
	v_add_f32_e32 v65, 1.0, v65
	v_rcp_f32_e32 v68, v65
	v_add_f32_e32 v65, 1.0, v66
	v_mul_f32_e32 v66, 0xbfb8aa3b, v57
	v_exp_f32_e32 v66, v66
	v_exp_f32_e32 v67, v67
	v_exp_f32_e32 v69, v69
	v_mul_f32_e32 v64, 0xbfb8aa3b, v60
	v_add_f32_e32 v72, 1.0, v66
	v_add_f32_e32 v66, 1.0, v67
	v_add_f32_e32 v67, 1.0, v69
	v_mul_f32_e32 v69, 0xbfb8aa3b, v63
	v_mul_f32_e32 v70, 0xbfb8aa3b, v59
	v_exp_f32_e32 v64, v64
	v_exp_f32_e32 v69, v69
	v_exp_f32_e32 v71, v70
	v_rcp_f32_e32 v70, v67
	v_add_f32_e32 v64, 1.0, v64
	v_add_f32_e32 v67, 1.0, v69
	v_add_f32_e32 v69, 1.0, v71
	v_rcp_f32_e32 v64, v64
	v_rcp_f32_e32 v65, v65
	v_rcp_f32_e32 v66, v66
	v_rcp_f32_e32 v67, v67
	v_rcp_f32_e32 v71, v69
	v_rcp_f32_e32 v69, v72
	v_pk_mul_f32 v[64:65], v[60:61], v[64:65]
	v_pk_mul_f32 v[66:67], v[62:63], v[66:67]
	v_pk_mul_f32 v[70:71], v[58:59], v[70:71]
	v_pk_mul_f32 v[68:69], v[56:57], v[68:69]
	s_mov_b64 s[24:25], 0

; __device__ __forceinline__ float siluf_(float x) { return x * sigmoidf_(x); }
; __device__ __forceinline__ u32x4 pack8(f32x4 v0, f32x4 v1) { u32x4 w; w.x = cvt_pk_bf16(v0[0], v0[1]); w.y = cvt_pk_bf16(v0[2], v0[3]); w.z = cvt_pk_bf16(v1[0], v1[1]); w.w = cvt_pk_bf16(v1[2], v1[3]); return w; }
;     __device__ __forceinline__ void operator()(const Acc& acc, const Unit& u, int wr, int wc, int fr, int fq) const {
;     ...
;             if (kind == 0 || kind == 3) {
;                 bf16_t* base = (kind == 0 ? Q : Z) + (size_t)(pm * 256 + rloc) * DM + colt;
; #pragma unroll
;                 for (int ai = 0; ai < 2; ++ai)
; #pragma unroll
;                     for (int m = 0; m < 4; ++m)
; #pragma unroll
;                         for (int bj = 0; bj < 2; ++bj) { f32x4 v0 = acc[ai][bj][m][0], v1 = acc[ai][bj][m][1];
;                             if (kind == 0) { v0 = v0 * QSCALE; v1 = v1 * QSCALE; }
;                             else {
; #pragma unroll
;                                 for (int j = 0; j < 4; ++j) { v0[j] = siluf_(v0[j]); v1[j] = siluf_(v1[j]); } }
;                             *(u32x4*)(base + (size_t)(ai * 128 + m * 16) * DM + bj * 128) = pack8(v0, v1); }
.LBB0_380:
	v_add_co_u32_e32 v60, vcc, 0x80000, v158
	v_cvt_pk_bf16_f32 v56, v64, v65
	v_cvt_pk_bf16_f32 v57, v66, v67
	v_cvt_pk_bf16_f32 v58, v68, v69
	v_cvt_pk_bf16_f32 v59, v70, v71
	s_nop 1
	v_addc_co_u32_e32 v61, vcc, 0, v159, vcc
	s_and_b64 vcc, exec, s[2:3]
	s_mov_b64 s[24:25], -1
	ds_bpermute_b32 v200, v214, v56
	ds_bpermute_b32 v201, v214, v57
	ds_bpermute_b32 v202, v214, v58
	ds_bpermute_b32 v203, v214, v59
	ds_bpermute_b32 v204, v214, v60
	ds_bpermute_b32 v205, v214, v61
	s_waitcnt lgkmcnt(0)
	global_store_dwordx4 v[204:205], v[200:203], off
	s_cbranch_vccnz .LBB0_382
	s_nop 0
	v_mul_f32_e32 v57, 0xbfb8aa3b, v48
	v_mul_f32_e32 v58, 0xbfb8aa3b, v53
	v_exp_f32_e32 v57, v57
	v_exp_f32_e32 v58, v58
	v_mul_f32_e32 v59, 0xbfb8aa3b, v54
	v_mul_f32_e32 v61, 0xbfb8aa3b, v50
	v_add_f32_e32 v57, 1.0, v57
	v_rcp_f32_e32 v60, v57
	v_add_f32_e32 v57, 1.0, v58
	v_mul_f32_e32 v58, 0xbfb8aa3b, v49
	v_exp_f32_e32 v58, v58
	v_exp_f32_e32 v59, v59
	v_exp_f32_e32 v61, v61
	v_mul_f32_e32 v56, 0xbfb8aa3b, v52
	v_add_f32_e32 v64, 1.0, v58
	v_add_f32_e32 v58, 1.0, v59
	v_add_f32_e32 v59, 1.0, v61
	v_mul_f32_e32 v61, 0xbfb8aa3b, v55
	v_mul_f32_e32 v62, 0xbfb8aa3b, v51
	v_exp_f32_e32 v56, v56
	v_exp_f32_e32 v61, v61
	v_exp_f32_e32 v63, v62
	v_rcp_f32_e32 v62, v59
	v_add_f32_e32 v56, 1.0, v56
	v_add_f32_e32 v59, 1.0, v61
	v_add_f32_e32 v61, 1.0, v63
	v_rcp_f32_e32 v56, v56
	v_rcp_f32_e32 v57, v57
	v_rcp_f32_e32 v58, v58
	v_rcp_f32_e32 v59, v59
	v_rcp_f32_e32 v63, v61
	v_rcp_f32_e32 v61, v64
	v_pk_mul_f32 v[56:57], v[52:53], v[56:57]
	v_pk_mul_f32 v[58:59], v[54:55], v[58:59]
	v_pk_mul_f32 v[62:63], v[50:51], v[62:63]
	v_pk_mul_f32 v[60:61], v[48:49], v[60:61]
	s_mov_b64 s[24:25], 0

; __device__ __forceinline__ float siluf_(float x) { return x * sigmoidf_(x); }
; __device__ __forceinline__ u32x4 pack8(f32x4 v0, f32x4 v1) { u32x4 w; w.x = cvt_pk_bf16(v0[0], v0[1]); w.y = cvt_pk_bf16(v0[2], v0[3]); w.z = cvt_pk_bf16(v1[0], v1[1]); w.w = cvt_pk_bf16(v1[2], v1[3]); return w; }
;     __device__ __forceinline__ void operator()(const Acc& acc, const Unit& u, int wr, int wc, int fr, int fq) const {
;     ...
;             if (kind == 0 || kind == 3) {
;                 bf16_t* base = (kind == 0 ? Q : Z) + (size_t)(pm * 256 + rloc) * DM + colt;
; #pragma unroll
;                 for (int ai = 0; ai < 2; ++ai)
; #pragma unroll
;                     for (int m = 0; m < 4; ++m)
; #pragma unroll
;                         for (int bj = 0; bj < 2; ++bj) { f32x4 v0 = acc[ai][bj][m][0], v1 = acc[ai][bj][m][1];
;                             if (kind == 0) { v0 = v0 * QSCALE; v1 = v1 * QSCALE; }
;                             else {
; #pragma unroll
;                                 for (int j = 0; j < 4; ++j) { v0[j] = siluf_(v0[j]); v1[j] = siluf_(v1[j]); } }
;                             *(u32x4*)(base + (size_t)(ai * 128 + m * 16) * DM + bj * 128) = pack8(v0, v1); }
.LBB0_384:
	v_add_co_u32_e32 v52, vcc, 0x80000, v158
	v_cvt_pk_bf16_f32 v48, v56, v57
	v_cvt_pk_bf16_f32 v49, v58, v59
	v_cvt_pk_bf16_f32 v50, v60, v61
	v_cvt_pk_bf16_f32 v51, v62, v63
	s_nop 1
	v_addc_co_u32_e32 v53, vcc, 0, v159, vcc
	s_and_b64 vcc, exec, s[2:3]
	s_mov_b64 s[24:25], -1
	ds_bpermute_b32 v208, v214, v48
	ds_bpermute_b32 v209, v214, v49
	ds_bpermute_b32 v210, v214, v50
	ds_bpermute_b32 v211, v214, v51
	ds_bpermute_b32 v212, v214, v52
	ds_bpermute_b32 v213, v214, v53
	s_waitcnt lgkmcnt(0)
	global_store_dwordx4 v[212:213], v[208:211], off offset:256
	s_cbranch_vccnz .LBB0_386
	s_nop 0
	v_mul_f32_e32 v49, 0xbfb8aa3b, v40
	v_mul_f32_e32 v50, 0xbfb8aa3b, v45
	v_exp_f32_e32 v49, v49
	v_exp_f32_e32 v50, v50
	v_mul_f32_e32 v51, 0xbfb8aa3b, v46
	v_mul_f32_e32 v53, 0xbfb8aa3b, v42
	v_add_f32_e32 v49, 1.0, v49
	v_rcp_f32_e32 v52, v49
	v_add_f32_e32 v49, 1.0, v50
	v_mul_f32_e32 v50, 0xbfb8aa3b, v41
	v_exp_f32_e32 v50, v50
	v_exp_f32_e32 v51, v51
	v_exp_f32_e32 v53, v53
	v_mul_f32_e32 v48, 0xbfb8aa3b, v44
	v_add_f32_e32 v56, 1.0, v50
	v_add_f32_e32 v50, 1.0, v51
	v_add_f32_e32 v51, 1.0, v53
	v_mul_f32_e32 v53, 0xbfb8aa3b, v47
	v_mul_f32_e32 v54, 0xbfb8aa3b, v43
	v_exp_f32_e32 v48, v48
	v_exp_f32_e32 v53, v53
	v_exp_f32_e32 v55, v54
	v_rcp_f32_e32 v54, v51
	v_add_f32_e32 v48, 1.0, v48
	v_add_f32_e32 v51, 1.0, v53
	v_add_f32_e32 v53, 1.0, v55
	v_rcp_f32_e32 v48, v48
	v_rcp_f32_e32 v49, v49
	v_rcp_f32_e32 v50, v50
	v_rcp_f32_e32 v51, v51
	v_rcp_f32_e32 v55, v53
	v_rcp_f32_e32 v53, v56
	v_pk_mul_f32 v[48:49], v[44:45], v[48:49]
	v_pk_mul_f32 v[50:51], v[46:47], v[50:51]
	v_pk_mul_f32 v[54:55], v[42:43], v[54:55]
	v_pk_mul_f32 v[52:53], v[40:41], v[52:53]
	s_mov_b64 s[24:25], 0

; __device__ __forceinline__ float siluf_(float x) { return x * sigmoidf_(x); }
; __device__ __forceinline__ u32x4 pack8(f32x4 v0, f32x4 v1) { u32x4 w; w.x = cvt_pk_bf16(v0[0], v0[1]); w.y = cvt_pk_bf16(v0[2], v0[3]); w.z = cvt_pk_bf16(v1[0], v1[1]); w.w = cvt_pk_bf16(v1[2], v1[3]); return w; }
;     __device__ __forceinline__ void operator()(const Acc& acc, const Unit& u, int wr, int wc, int fr, int fq) const {
;     ...
;             if (kind == 0 || kind == 3) {
;                 bf16_t* base = (kind == 0 ? Q : Z) + (size_t)(pm * 256 + rloc) * DM + colt;
; #pragma unroll
;                 for (int ai = 0; ai < 2; ++ai)
; #pragma unroll
;                     for (int m = 0; m < 4; ++m)
; #pragma unroll
;                         for (int bj = 0; bj < 2; ++bj) { f32x4 v0 = acc[ai][bj][m][0], v1 = acc[ai][bj][m][1];
;                             if (kind == 0) { v0 = v0 * QSCALE; v1 = v1 * QSCALE; }
;                             else {
; #pragma unroll
;                                 for (int j = 0; j < 4; ++j) { v0[j] = siluf_(v0[j]); v1[j] = siluf_(v1[j]); } }
;                             *(u32x4*)(base + (size_t)(ai * 128 + m * 16) * DM + bj * 128) = pack8(v0, v1); }
.LBB0_388:
	v_add_co_u32_e32 v44, vcc, 0x90000, v158
	v_cvt_pk_bf16_f32 v40, v48, v49
	v_cvt_pk_bf16_f32 v41, v50, v51
	v_cvt_pk_bf16_f32 v42, v52, v53
	v_cvt_pk_bf16_f32 v43, v54, v55
	s_nop 1
	v_addc_co_u32_e32 v45, vcc, 0, v159, vcc
	s_and_b64 vcc, exec, s[2:3]
	s_mov_b64 s[24:25], -1
	ds_bpermute_b32 v200, v214, v40
	ds_bpermute_b32 v201, v214, v41
	ds_bpermute_b32 v202, v214, v42
	ds_bpermute_b32 v203, v214, v43
	ds_bpermute_b32 v204, v214, v44
	ds_bpermute_b32 v205, v214, v45
	s_waitcnt lgkmcnt(0)
	global_store_dwordx4 v[204:205], v[200:203], off
	s_cbranch_vccnz .LBB0_390
	s_nop 0
	v_mul_f32_e32 v41, 0xbfb8aa3b, v32
	v_mul_f32_e32 v42, 0xbfb8aa3b, v37
	v_exp_f32_e32 v41, v41
	v_exp_f32_e32 v42, v42
	v_mul_f32_e32 v43, 0xbfb8aa3b, v38
	v_mul_f32_e32 v45, 0xbfb8aa3b, v34
	v_add_f32_e32 v41, 1.0, v41
	v_rcp_f32_e32 v44, v41
	v_add_f32_e32 v41, 1.0, v42
	v_mul_f32_e32 v42, 0xbfb8aa3b, v33
	v_exp_f32_e32 v42, v42
	v_exp_f32_e32 v43, v43
	v_exp_f32_e32 v45, v45
	v_mul_f32_e32 v40, 0xbfb8aa3b, v36
	v_add_f32_e32 v48, 1.0, v42
	v_add_f32_e32 v42, 1.0, v43
	v_add_f32_e32 v43, 1.0, v45
	v_mul_f32_e32 v45, 0xbfb8aa3b, v39
	v_mul_f32_e32 v46, 0xbfb8aa3b, v35
	v_exp_f32_e32 v40, v40
	v_exp_f32_e32 v45, v45
	v_exp_f32_e32 v47, v46
	v_rcp_f32_e32 v46, v43
	v_add_f32_e32 v40, 1.0, v40
	v_add_f32_e32 v43, 1.0, v45
	v_add_f32_e32 v45, 1.0, v47
	v_rcp_f32_e32 v40, v40
	v_rcp_f32_e32 v41, v41
	v_rcp_f32_e32 v42, v42
	v_rcp_f32_e32 v43, v43
	v_rcp_f32_e32 v47, v45
	v_rcp_f32_e32 v45, v48
	v_pk_mul_f32 v[40:41], v[36:37], v[40:41]
	v_pk_mul_f32 v[42:43], v[38:39], v[42:43]
	v_pk_mul_f32 v[46:47], v[34:35], v[46:47]
	v_pk_mul_f32 v[44:45], v[32:33], v[44:45]
	s_mov_b64 s[24:25], 0

; __device__ __forceinline__ float siluf_(float x) { return x * sigmoidf_(x); }
; __device__ __forceinline__ u32x4 pack8(f32x4 v0, f32x4 v1) { u32x4 w; w.x = cvt_pk_bf16(v0[0], v0[1]); w.y = cvt_pk_bf16(v0[2], v0[3]); w.z = cvt_pk_bf16(v1[0], v1[1]); w.w = cvt_pk_bf16(v1[2], v1[3]); return w; }
;     __device__ __forceinline__ void operator()(const Acc& acc, const Unit& u, int wr, int wc, int fr, int fq) const {
;     ...
;             if (kind == 0 || kind == 3) {
;                 bf16_t* base = (kind == 0 ? Q : Z) + (size_t)(pm * 256 + rloc) * DM + colt;
; #pragma unroll
;                 for (int ai = 0; ai < 2; ++ai)
; #pragma unroll
;                     for (int m = 0; m < 4; ++m)
; #pragma unroll
;                         for (int bj = 0; bj < 2; ++bj) { f32x4 v0 = acc[ai][bj][m][0], v1 = acc[ai][bj][m][1];
;                             if (kind == 0) { v0 = v0 * QSCALE; v1 = v1 * QSCALE; }
;                             else {
; #pragma unroll
;                                 for (int j = 0; j < 4; ++j) { v0[j] = siluf_(v0[j]); v1[j] = siluf_(v1[j]); } }
;                             *(u32x4*)(base + (size_t)(ai * 128 + m * 16) * DM + bj * 128) = pack8(v0, v1); }
.LBB0_392:
	v_add_co_u32_e32 v36, vcc, 0x90000, v158
	v_cvt_pk_bf16_f32 v32, v40, v41
	v_cvt_pk_bf16_f32 v33, v42, v43
	v_cvt_pk_bf16_f32 v34, v44, v45
	v_cvt_pk_bf16_f32 v35, v46, v47
	s_nop 1
	v_addc_co_u32_e32 v37, vcc, 0, v159, vcc
	s_and_b64 vcc, exec, s[2:3]
	s_mov_b64 s[24:25], -1
	ds_bpermute_b32 v208, v214, v32
	ds_bpermute_b32 v209, v214, v33
	ds_bpermute_b32 v210, v214, v34
	ds_bpermute_b32 v211, v214, v35
	ds_bpermute_b32 v212, v214, v36
	ds_bpermute_b32 v213, v214, v37
	s_waitcnt lgkmcnt(0)
	global_store_dwordx4 v[212:213], v[208:211], off offset:256
	s_cbranch_vccnz .LBB0_394
	s_nop 0
	v_mul_f32_e32 v33, 0xbfb8aa3b, v24
	v_mul_f32_e32 v34, 0xbfb8aa3b, v29
	v_exp_f32_e32 v33, v33
	v_exp_f32_e32 v34, v34
	v_mul_f32_e32 v35, 0xbfb8aa3b, v30
	v_mul_f32_e32 v37, 0xbfb8aa3b, v26
	v_add_f32_e32 v33, 1.0, v33
	v_rcp_f32_e32 v36, v33
	v_add_f32_e32 v33, 1.0, v34
	v_mul_f32_e32 v34, 0xbfb8aa3b, v25
	v_exp_f32_e32 v34, v34
	v_exp_f32_e32 v35, v35
	v_exp_f32_e32 v37, v37
	v_mul_f32_e32 v32, 0xbfb8aa3b, v28
	v_add_f32_e32 v40, 1.0, v34
	v_add_f32_e32 v34, 1.0, v35
	v_add_f32_e32 v35, 1.0, v37
	v_mul_f32_e32 v37, 0xbfb8aa3b, v31
	v_mul_f32_e32 v38, 0xbfb8aa3b, v27
	v_exp_f32_e32 v32, v32
	v_exp_f32_e32 v37, v37
	v_exp_f32_e32 v39, v38
	v_rcp_f32_e32 v38, v35
	v_add_f32_e32 v32, 1.0, v32
	v_add_f32_e32 v35, 1.0, v37
	v_add_f32_e32 v37, 1.0, v39
	v_rcp_f32_e32 v32, v32
	v_rcp_f32_e32 v33, v33
	v_rcp_f32_e32 v34, v34
	v_rcp_f32_e32 v35, v35
	v_rcp_f32_e32 v39, v37
	v_rcp_f32_e32 v37, v40
	v_pk_mul_f32 v[32:33], v[28:29], v[32:33]
	v_pk_mul_f32 v[34:35], v[30:31], v[34:35]
	v_pk_mul_f32 v[38:39], v[26:27], v[38:39]
	v_pk_mul_f32 v[36:37], v[24:25], v[36:37]
	s_mov_b64 s[24:25], 0

; __device__ __forceinline__ float siluf_(float x) { return x * sigmoidf_(x); }
; __device__ __forceinline__ u32x4 pack8(f32x4 v0, f32x4 v1) { u32x4 w; w.x = cvt_pk_bf16(v0[0], v0[1]); w.y = cvt_pk_bf16(v0[2], v0[3]); w.z = cvt_pk_bf16(v1[0], v1[1]); w.w = cvt_pk_bf16(v1[2], v1[3]); return w; }
;     __device__ __forceinline__ void operator()(const Acc& acc, const Unit& u, int wr, int wc, int fr, int fq) const {
;     ...
;             if (kind == 0 || kind == 3) {
;                 bf16_t* base = (kind == 0 ? Q : Z) + (size_t)(pm * 256 + rloc) * DM + colt;
; #pragma unroll
;                 for (int ai = 0; ai < 2; ++ai)
; #pragma unroll
;                     for (int m = 0; m < 4; ++m)
; #pragma unroll
;                         for (int bj = 0; bj < 2; ++bj) { f32x4 v0 = acc[ai][bj][m][0], v1 = acc[ai][bj][m][1];
;                             if (kind == 0) { v0 = v0 * QSCALE; v1 = v1 * QSCALE; }
;                             else {
; #pragma unroll
;                                 for (int j = 0; j < 4; ++j) { v0[j] = siluf_(v0[j]); v1[j] = siluf_(v1[j]); } }
;                             *(u32x4*)(base + (size_t)(ai * 128 + m * 16) * DM + bj * 128) = pack8(v0, v1); }
.LBB0_396:
	v_add_co_u32_e32 v28, vcc, 0xa0000, v158
	v_cvt_pk_bf16_f32 v24, v32, v33
	v_cvt_pk_bf16_f32 v25, v34, v35
	v_cvt_pk_bf16_f32 v26, v36, v37
	v_cvt_pk_bf16_f32 v27, v38, v39
	s_nop 1
	v_addc_co_u32_e32 v29, vcc, 0, v159, vcc
	s_and_b64 vcc, exec, s[2:3]
	s_mov_b64 s[24:25], -1
	ds_bpermute_b32 v200, v214, v24
	ds_bpermute_b32 v201, v214, v25
	ds_bpermute_b32 v202, v214, v26
	ds_bpermute_b32 v203, v214, v27
	ds_bpermute_b32 v204, v214, v28
	ds_bpermute_b32 v205, v214, v29
	s_waitcnt lgkmcnt(0)
	global_store_dwordx4 v[204:205], v[200:203], off
	s_cbranch_vccnz .LBB0_398
	s_nop 0
	v_mul_f32_e32 v25, 0xbfb8aa3b, v16
	v_mul_f32_e32 v26, 0xbfb8aa3b, v21
	v_exp_f32_e32 v25, v25
	v_exp_f32_e32 v26, v26
	v_mul_f32_e32 v27, 0xbfb8aa3b, v22
	v_mul_f32_e32 v29, 0xbfb8aa3b, v18
	v_add_f32_e32 v25, 1.0, v25
	v_rcp_f32_e32 v28, v25
	v_add_f32_e32 v25, 1.0, v26
	v_mul_f32_e32 v26, 0xbfb8aa3b, v17
	v_exp_f32_e32 v26, v26
	v_exp_f32_e32 v27, v27
	v_exp_f32_e32 v29, v29
	v_mul_f32_e32 v24, 0xbfb8aa3b, v20
	v_add_f32_e32 v32, 1.0, v26
	v_add_f32_e32 v26, 1.0, v27
	v_add_f32_e32 v27, 1.0, v29
	v_mul_f32_e32 v29, 0xbfb8aa3b, v23
	v_mul_f32_e32 v30, 0xbfb8aa3b, v19
	v_exp_f32_e32 v24, v24
	v_exp_f32_e32 v29, v29
	v_exp_f32_e32 v31, v30
	v_rcp_f32_e32 v30, v27
	v_add_f32_e32 v24, 1.0, v24
	v_add_f32_e32 v27, 1.0, v29
	v_add_f32_e32 v29, 1.0, v31
	v_rcp_f32_e32 v24, v24
	v_rcp_f32_e32 v25, v25
	v_rcp_f32_e32 v26, v26
	v_rcp_f32_e32 v27, v27
	v_rcp_f32_e32 v31, v29
	v_rcp_f32_e32 v29, v32
	v_pk_mul_f32 v[24:25], v[20:21], v[24:25]
	v_pk_mul_f32 v[26:27], v[22:23], v[26:27]
	v_pk_mul_f32 v[30:31], v[18:19], v[30:31]
	v_pk_mul_f32 v[28:29], v[16:17], v[28:29]
	s_mov_b64 s[24:25], 0

; __device__ __forceinline__ float siluf_(float x) { return x * sigmoidf_(x); }
; __device__ __forceinline__ u32x4 pack8(f32x4 v0, f32x4 v1) { u32x4 w; w.x = cvt_pk_bf16(v0[0], v0[1]); w.y = cvt_pk_bf16(v0[2], v0[3]); w.z = cvt_pk_bf16(v1[0], v1[1]); w.w = cvt_pk_bf16(v1[2], v1[3]); return w; }
;     __device__ __forceinline__ void operator()(const Acc& acc, const Unit& u, int wr, int wc, int fr, int fq) const {
;     ...
;             if (kind == 0 || kind == 3) {
;                 bf16_t* base = (kind == 0 ? Q : Z) + (size_t)(pm * 256 + rloc) * DM + colt;
; #pragma unroll
;                 for (int ai = 0; ai < 2; ++ai)
; #pragma unroll
;                     for (int m = 0; m < 4; ++m)
; #pragma unroll
;                         for (int bj = 0; bj < 2; ++bj) { f32x4 v0 = acc[ai][bj][m][0], v1 = acc[ai][bj][m][1];
;                             if (kind == 0) { v0 = v0 * QSCALE; v1 = v1 * QSCALE; }
;                             else {
; #pragma unroll
;                                 for (int j = 0; j < 4; ++j) { v0[j] = siluf_(v0[j]); v1[j] = siluf_(v1[j]); } }
;                             *(u32x4*)(base + (size_t)(ai * 128 + m * 16) * DM + bj * 128) = pack8(v0, v1); }
.LBB0_400:
	v_add_co_u32_e32 v20, vcc, 0xa0000, v158
	v_cvt_pk_bf16_f32 v16, v24, v25
	v_cvt_pk_bf16_f32 v17, v26, v27
	v_cvt_pk_bf16_f32 v18, v28, v29
	v_cvt_pk_bf16_f32 v19, v30, v31
	s_nop 1
	v_addc_co_u32_e32 v21, vcc, 0, v159, vcc
	s_and_b64 vcc, exec, s[2:3]
	s_mov_b64 s[24:25], -1
	ds_bpermute_b32 v208, v214, v16
	ds_bpermute_b32 v209, v214, v17
	ds_bpermute_b32 v210, v214, v18
	ds_bpermute_b32 v211, v214, v19
	ds_bpermute_b32 v212, v214, v20
	ds_bpermute_b32 v213, v214, v21
	s_waitcnt lgkmcnt(0)
	global_store_dwordx4 v[212:213], v[208:211], off offset:256
	s_cbranch_vccnz .LBB0_402
	s_nop 0
	v_mul_f32_e32 v17, 0xbfb8aa3b, v8
	v_mul_f32_e32 v18, 0xbfb8aa3b, v13
	v_exp_f32_e32 v17, v17
	v_exp_f32_e32 v18, v18
	v_mul_f32_e32 v19, 0xbfb8aa3b, v14
	v_mul_f32_e32 v21, 0xbfb8aa3b, v10
	v_add_f32_e32 v17, 1.0, v17
	v_rcp_f32_e32 v20, v17
	v_add_f32_e32 v17, 1.0, v18
	v_mul_f32_e32 v18, 0xbfb8aa3b, v9
	v_exp_f32_e32 v18, v18
	v_exp_f32_e32 v19, v19
	v_exp_f32_e32 v21, v21
	v_mul_f32_e32 v16, 0xbfb8aa3b, v12
	v_add_f32_e32 v24, 1.0, v18
	v_add_f32_e32 v18, 1.0, v19
	v_add_f32_e32 v19, 1.0, v21
	v_mul_f32_e32 v21, 0xbfb8aa3b, v15
	v_mul_f32_e32 v22, 0xbfb8aa3b, v11
	v_exp_f32_e32 v16, v16
	v_exp_f32_e32 v21, v21
	v_exp_f32_e32 v23, v22
	v_rcp_f32_e32 v22, v19
	v_add_f32_e32 v16, 1.0, v16
	v_add_f32_e32 v19, 1.0, v21
	v_add_f32_e32 v21, 1.0, v23
	v_rcp_f32_e32 v16, v16
	v_rcp_f32_e32 v17, v17
	v_rcp_f32_e32 v18, v18
	v_rcp_f32_e32 v19, v19
	v_rcp_f32_e32 v23, v21
	v_rcp_f32_e32 v21, v24
	v_pk_mul_f32 v[16:17], v[12:13], v[16:17]
	v_pk_mul_f32 v[18:19], v[14:15], v[18:19]
	v_pk_mul_f32 v[22:23], v[10:11], v[22:23]
	v_pk_mul_f32 v[20:21], v[8:9], v[20:21]
	s_mov_b64 s[24:25], 0

; __device__ __forceinline__ float siluf_(float x) { return x * sigmoidf_(x); }
; __device__ __forceinline__ u32x4 pack8(f32x4 v0, f32x4 v1) { u32x4 w; w.x = cvt_pk_bf16(v0[0], v0[1]); w.y = cvt_pk_bf16(v0[2], v0[3]); w.z = cvt_pk_bf16(v1[0], v1[1]); w.w = cvt_pk_bf16(v1[2], v1[3]); return w; }
;     __device__ __forceinline__ void operator()(const Acc& acc, const Unit& u, int wr, int wc, int fr, int fq) const {
;     ...
;             if (kind == 0 || kind == 3) {
;                 bf16_t* base = (kind == 0 ? Q : Z) + (size_t)(pm * 256 + rloc) * DM + colt;
; #pragma unroll
;                 for (int ai = 0; ai < 2; ++ai)
; #pragma unroll
;                     for (int m = 0; m < 4; ++m)
; #pragma unroll
;                         for (int bj = 0; bj < 2; ++bj) { f32x4 v0 = acc[ai][bj][m][0], v1 = acc[ai][bj][m][1];
;                             if (kind == 0) { v0 = v0 * QSCALE; v1 = v1 * QSCALE; }
;                             else {
; #pragma unroll
;                                 for (int j = 0; j < 4; ++j) { v0[j] = siluf_(v0[j]); v1[j] = siluf_(v1[j]); } }
;                             *(u32x4*)(base + (size_t)(ai * 128 + m * 16) * DM + bj * 128) = pack8(v0, v1); }
.LBB0_404:
	v_add_co_u32_e32 v12, vcc, 0xb0000, v158
	v_cvt_pk_bf16_f32 v8, v16, v17
	v_cvt_pk_bf16_f32 v9, v18, v19
	v_cvt_pk_bf16_f32 v10, v20, v21
	v_cvt_pk_bf16_f32 v11, v22, v23
	s_nop 1
	v_addc_co_u32_e32 v13, vcc, 0, v159, vcc
	s_and_b64 vcc, exec, s[2:3]
	s_mov_b64 s[2:3], -1
	ds_bpermute_b32 v200, v214, v8
	ds_bpermute_b32 v201, v214, v9
	ds_bpermute_b32 v202, v214, v10
	ds_bpermute_b32 v203, v214, v11
	ds_bpermute_b32 v204, v214, v12
	ds_bpermute_b32 v205, v214, v13
	s_waitcnt lgkmcnt(0)
	global_store_dwordx4 v[204:205], v[200:203], off
	s_cbranch_vccnz .LBB0_406
	s_nop 0
	v_mul_f32_e32 v9, 0xbfb8aa3b, v0
	v_mul_f32_e32 v10, 0xbfb8aa3b, v5
	v_exp_f32_e32 v9, v9
	v_exp_f32_e32 v10, v10
	v_mul_f32_e32 v11, 0xbfb8aa3b, v6
	v_mul_f32_e32 v13, 0xbfb8aa3b, v2
	v_add_f32_e32 v9, 1.0, v9
	v_rcp_f32_e32 v12, v9
	v_add_f32_e32 v9, 1.0, v10
	v_mul_f32_e32 v10, 0xbfb8aa3b, v1
	v_exp_f32_e32 v10, v10
	v_exp_f32_e32 v11, v11
	v_exp_f32_e32 v13, v13
	v_mul_f32_e32 v8, 0xbfb8aa3b, v4
	v_add_f32_e32 v16, 1.0, v10
	v_add_f32_e32 v10, 1.0, v11
	v_add_f32_e32 v11, 1.0, v13
	v_mul_f32_e32 v13, 0xbfb8aa3b, v7
	v_mul_f32_e32 v14, 0xbfb8aa3b, v3
	v_exp_f32_e32 v8, v8
	v_exp_f32_e32 v13, v13
	v_exp_f32_e32 v15, v14
	v_rcp_f32_e32 v14, v11
	v_add_f32_e32 v8, 1.0, v8
	v_add_f32_e32 v11, 1.0, v13
	v_add_f32_e32 v13, 1.0, v15
	v_rcp_f32_e32 v8, v8
	v_rcp_f32_e32 v9, v9
	v_rcp_f32_e32 v10, v10
	v_rcp_f32_e32 v11, v11
	v_rcp_f32_e32 v15, v13
	v_rcp_f32_e32 v13, v16
	v_pk_mul_f32 v[8:9], v[4:5], v[8:9]
	v_pk_mul_f32 v[10:11], v[6:7], v[10:11]
	v_pk_mul_f32 v[14:15], v[2:3], v[14:15]
	v_pk_mul_f32 v[12:13], v[0:1], v[12:13]
	s_mov_b64 s[2:3], 0

; __device__ __forceinline__ float siluf_(float x) { return x * sigmoidf_(x); }
; __device__ __forceinline__ u32x4 pack8(f32x4 v0, f32x4 v1) { u32x4 w; w.x = cvt_pk_bf16(v0[0], v0[1]); w.y = cvt_pk_bf16(v0[2], v0[3]); w.z = cvt_pk_bf16(v1[0], v1[1]); w.w = cvt_pk_bf16(v1[2], v1[3]); return w; }
;     __device__ __forceinline__ void operator()(const Acc& acc, const Unit& u, int wr, int wc, int fr, int fq) const {
;     ...
;             if (kind == 0 || kind == 3) {
;                 bf16_t* base = (kind == 0 ? Q : Z) + (size_t)(pm * 256 + rloc) * DM + colt;
; #pragma unroll
;                 for (int ai = 0; ai < 2; ++ai)
; #pragma unroll
;                     for (int m = 0; m < 4; ++m)
; #pragma unroll
;                         for (int bj = 0; bj < 2; ++bj) { f32x4 v0 = acc[ai][bj][m][0], v1 = acc[ai][bj][m][1];
;                             if (kind == 0) { v0 = v0 * QSCALE; v1 = v1 * QSCALE; }
;                             else {
; #pragma unroll
;                                 for (int j = 0; j < 4; ++j) { v0[j] = siluf_(v0[j]); v1[j] = siluf_(v1[j]); } }
;                             *(u32x4*)(base + (size_t)(ai * 128 + m * 16) * DM + bj * 128) = pack8(v0, v1); }
.LBB0_408:
	v_add_co_u32_e32 v4, vcc, 0xb0000, v158
	v_cvt_pk_bf16_f32 v0, v8, v9
	v_cvt_pk_bf16_f32 v1, v10, v11
	v_cvt_pk_bf16_f32 v2, v12, v13
	v_cvt_pk_bf16_f32 v3, v14, v15
	s_nop 1
	v_addc_co_u32_e32 v5, vcc, 0, v159, vcc
	ds_bpermute_b32 v208, v214, v0
	ds_bpermute_b32 v209, v214, v1
	ds_bpermute_b32 v210, v214, v2
	ds_bpermute_b32 v211, v214, v3
	ds_bpermute_b32 v212, v214, v4
	ds_bpermute_b32 v213, v214, v5
	s_waitcnt lgkmcnt(0)
	global_store_dwordx4 v[212:213], v[208:211], off offset:256

; __device__ __forceinline__ void p1_side_task(int c, LAS unsigned char* lds, const bf16_t* XN, const bf16_t* WIN, const float* b_f, float* LF, bf16_t* Kb, bf16_t* Vb, bf16_t* P1b) {
;     const int tid = threadIdx.x, lane = tid & 63, w = __builtin_amdgcn_readfirstlane(tid >> 6), fr = lane & 15, fq = lane >> 4;
;     const bf16_t* XM = XN + (size_t)MREAL * DM;
;     const bf16_t* WF = WIN + (size_t)20480 * DM;
;     int n0, n1;
;     if (c < 64) { n0 = 2048 + 32 * c; n1 = n0 + 16; } else if (c < 128) { n0 = 4096 + 32 * (c - 64); n1 = n0 + 16; }
;     else { const int ch0 = 16 * (c - 128); n0 = 8192 + 256 * (ch0 >> 7) + (ch0 & 127); n1 = n0 + 128; }
;     const size_t lo_ = (size_t)fr * DM + 256 * w + 8 * fq;
;     const bf16_t* P6[6] = {XN + (size_t)(32 * c) * DM + lo_, XN + (size_t)(32 * c + 16) * DM + lo_, XM + lo_, WF + lo_, WIN + (size_t)n0 * DM + lo_, WIN + (size_t)n1 * DM + lo_};
;     bf16x8 fr6[6][8];
; #pragma unroll
;     for (int s = 0; s < 6; ++s)
; #pragma unroll
;         for (int i = 0; i < 8; ++i) fr6[s][i] = *(const bf16x8*)(P6[s] + 32 * i);
;     f32x4 acc[5];
; #pragma unroll
;     for (int g = 0; g < 5; ++g) acc[g] = (f32x4){0.f, 0.f, 0.f, 0.f};
; #pragma unroll
;     for (int i = 0; i < 8; ++i) {
;         acc[0] = __builtin_amdgcn_mfma_f32_16x16x32_bf16(fr6[0][i], fr6[3][i], acc[0], 0, 0, 0);
;         acc[1] = __builtin_amdgcn_mfma_f32_16x16x32_bf16(fr6[1][i], fr6[3][i], acc[1], 0, 0, 0);
;         acc[2] = __builtin_amdgcn_mfma_f32_16x16x32_bf16(fr6[2][i], fr6[3][i], acc[2], 0, 0, 0);
;         acc[3] = __builtin_amdgcn_mfma_f32_16x16x32_bf16(fr6[4][i], fr6[2][i], acc[3], 0, 0, 0);
;         acc[4] = __builtin_amdgcn_mfma_f32_16x16x32_bf16(fr6[5][i], fr6[2][i], acc[4], 0, 0, 0);
.LBB0_423:
	s_ashr_i32 s11, s10, 31
	s_lshr_b32 s30, s37, 6
	s_lshl_b64 s[38:39], s[10:11], 12
	s_add_u32 s82, s4, s38
	s_addc_u32 s83, s5, s39
	s_add_i32 s40, s10, 16
	s_ashr_i32 s41, s40, 31
	s_lshl_b64 s[38:39], s[40:41], 12
	s_add_u32 s84, s4, s38
	s_addc_u32 s85, s5, s39
	v_and_b32_e32 v120, 63, v186
	v_lshrrev_b32_e32 v121, 5, v120
	v_and_b32_e32 v120, 31, v120
	v_lshlrev_b32_e32 v110, 12, v121
	v_lshl_add_u32 v110, v120, 4, v110
	s_lshl_b32 s86, s30, 9
	v_add_u32_e32 v110, s86, v110
	v_add_u32_e32 v111, 0x2000, v110
	v_add_u32_e32 v112, 0x4000, v110
	v_add_u32_e32 v113, 0x6000, v110
	v_add_u32_e32 v114, 0x8000, v110
	v_add_u32_e32 v115, 0xa000, v110
	v_add_u32_e32 v116, 0xc000, v110
	v_add_u32_e32 v117, 0xe000, v110
	s_mul_i32 s86, s30, 0x2100
	s_add_i32 s86, s86, 0x10000
	v_mul_u32_u24_e32 v118, 0x210, v121
	v_lshl_add_u32 v118, v120, 4, v118
	v_add_u32_e32 v118, s86, v118
	v_and_b32_e32 v120, 15, v186
	v_bfe_u32 v121, v186, 4, 2
	v_mul_u32_u24_e32 v119, 0x210, v120
	v_lshl_add_u32 v119, v121, 4, v119
	v_add_u32_e32 v119, s86, v119
	global_load_dword v97, v[66:67], off
	global_load_dwordx4 v[24:27], v110, s[8:9]
	global_load_dwordx4 v[28:31], v111, s[8:9]
	global_load_dwordx4 v[32:35], v112, s[8:9]
	global_load_dwordx4 v[36:39], v113, s[8:9]
	global_load_dwordx4 v[40:43], v114, s[8:9]
	global_load_dwordx4 v[44:47], v115, s[8:9]
	global_load_dwordx4 v[48:51], v116, s[8:9]
	global_load_dwordx4 v[52:55], v117, s[8:9]
	global_load_dwordx4 v[56:59], v110, s[82:83]
	global_load_dwordx4 v[60:63], v111, s[82:83]
	global_load_dwordx4 v[82:85], v112, s[82:83]
	global_load_dwordx4 v[86:89], v113, s[82:83]
	global_load_dwordx4 v[162:165], v114, s[82:83]
	global_load_dwordx4 v[166:169], v115, s[82:83]
	global_load_dwordx4 v[170:173], v116, s[82:83]
	global_load_dwordx4 v[174:177], v117, s[82:83]
	global_load_dwordx4 v[178:181], v110, s[84:85]
	global_load_dwordx4 v[182:185], v111, s[84:85]
	global_load_dwordx4 v[188:191], v112, s[84:85]
	global_load_dwordx4 v[192:195], v113, s[84:85]
	global_load_dwordx4 v[196:199], v114, s[84:85]
	global_load_dwordx4 v[200:203], v115, s[84:85]
	global_load_dwordx4 v[204:207], v116, s[84:85]
	global_load_dwordx4 v[208:211], v117, s[84:85]
	global_load_dwordx4 v[212:215], v110, s[2:3]
	global_load_dwordx4 v[216:219], v111, s[2:3]
	global_load_dwordx4 v[220:223], v112, s[2:3]
	global_load_dwordx4 v[224:227], v113, s[2:3]
	global_load_dwordx4 v[228:231], v114, s[2:3]
	global_load_dwordx4 v[232:235], v115, s[2:3]
	global_load_dwordx4 v[236:239], v116, s[2:3]
	global_load_dwordx4 v[240:243], v117, s[2:3]
	v_readlane_b32 s40, v248, 29
	v_readlane_b32 s41, v248, 30
	v_readlane_b32 s42, v248, 31
	v_readlane_b32 s43, v248, 32
	v_readlane_b32 s44, v248, 33
	v_readlane_b32 s45, v248, 34
	s_ashr_i32 s29, s28, 31
	v_readlane_b32 s46, v248, 35
	v_readlane_b32 s47, v248, 36
	s_mov_b64 s[40:41], s[44:45]
	s_lshl_b64 s[28:29], s[28:29], 12
	s_mov_b64 s[42:43], s[46:47]
	s_add_u32 s28, s42, s28
	s_addc_u32 s29, s43, s29
	s_ashr_i32 s27, s26, 31
	s_lshl_b64 s[26:27], s[26:27], 12
	s_add_u32 s26, s42, s26
	s_addc_u32 s27, s43, s27
	s_mulk_i32 s30, 0x1400
	v_add_u32_e32 v20, s30, v91
	s_waitcnt vmcnt(24)
	ds_write_b128 v118, v[24:27]
	ds_write_b128 v118, v[28:31] offset:1056
	ds_write_b128 v118, v[32:35] offset:2112
	ds_write_b128 v118, v[36:39] offset:3168
	ds_write_b128 v118, v[40:43] offset:4224
	ds_write_b128 v118, v[44:47] offset:5280
	ds_write_b128 v118, v[48:51] offset:6336
	ds_write_b128 v118, v[52:55] offset:7392
	s_waitcnt lgkmcnt(0)
	ds_read_b128 v[24:27], v119
	ds_read_b128 v[28:31], v119 offset:64
	ds_read_b128 v[32:35], v119 offset:128
	ds_read_b128 v[36:39], v119 offset:192
	ds_read_b128 v[40:43], v119 offset:256
	ds_read_b128 v[44:47], v119 offset:320
	ds_read_b128 v[48:51], v119 offset:384
	ds_read_b128 v[52:55], v119 offset:448
	s_waitcnt lgkmcnt(0)
	s_waitcnt vmcnt(16)
	ds_write_b128 v118, v[56:59]
	ds_write_b128 v118, v[60:63] offset:1056
	ds_write_b128 v118, v[82:85] offset:2112
	ds_write_b128 v118, v[86:89] offset:3168
	ds_write_b128 v118, v[162:165] offset:4224
	ds_write_b128 v118, v[166:169] offset:5280
	ds_write_b128 v118, v[170:173] offset:6336
	ds_write_b128 v118, v[174:177] offset:7392
	s_waitcnt lgkmcnt(0)
	ds_read_b128 v[56:59], v119
	ds_read_b128 v[60:63], v119 offset:64
	ds_read_b128 v[82:85], v119 offset:128
	ds_read_b128 v[86:89], v119 offset:192
	ds_read_b128 v[162:165], v119 offset:256
	ds_read_b128 v[166:169], v119 offset:320
	ds_read_b128 v[170:173], v119 offset:384
	ds_read_b128 v[174:177], v119 offset:448
	s_waitcnt lgkmcnt(0)
	v_mfma_f32_16x16x32_bf16 v[0:3], v[56:59], v[24:27], 0
	v_mfma_f32_16x16x32_bf16 v[0:3], v[60:63], v[28:31], v[0:3]
	v_mfma_f32_16x16x32_bf16 v[0:3], v[82:85], v[32:35], v[0:3]
	v_mfma_f32_16x16x32_bf16 v[0:3], v[86:89], v[36:39], v[0:3]
	v_mfma_f32_16x16x32_bf16 v[0:3], v[162:165], v[40:43], v[0:3]
	v_mfma_f32_16x16x32_bf16 v[0:3], v[166:169], v[44:47], v[0:3]
	v_mfma_f32_16x16x32_bf16 v[0:3], v[170:173], v[48:51], v[0:3]
	v_mfma_f32_16x16x32_bf16 v[0:3], v[174:177], v[52:55], v[0:3]
	s_nop 3
	global_load_dwordx4 v[56:59], v110, s[28:29]
	global_load_dwordx4 v[60:63], v111, s[28:29]
	global_load_dwordx4 v[82:85], v112, s[28:29]
	global_load_dwordx4 v[86:89], v113, s[28:29]
	global_load_dwordx4 v[162:165], v114, s[28:29]
	global_load_dwordx4 v[166:169], v115, s[28:29]
	global_load_dwordx4 v[170:173], v116, s[28:29]
	global_load_dwordx4 v[174:177], v117, s[28:29]
	s_waitcnt vmcnt(16)
	ds_write_b128 v118, v[178:181]
	ds_write_b128 v118, v[182:185] offset:1056
	ds_write_b128 v118, v[188:191] offset:2112
	ds_write_b128 v118, v[192:195] offset:3168
	ds_write_b128 v118, v[196:199] offset:4224
	ds_write_b128 v118, v[200:203] offset:5280
	ds_write_b128 v118, v[204:207] offset:6336
	ds_write_b128 v118, v[208:211] offset:7392
	s_waitcnt lgkmcnt(0)
; #define LAS __attribute__((address_space(3)))
; __device__ __forceinline__ void p1_side_task(int c, LAS unsigned char* lds, const bf16_t* XN, const bf16_t* WIN, const float* b_f, float* LF, bf16_t* Kb, bf16_t* Vb, bf16_t* P1b) {
;     ...
;     for (int i = 0; i < 8; ++i) {
;         acc[0] = __builtin_amdgcn_mfma_f32_16x16x32_bf16(fr6[0][i], fr6[3][i], acc[0], 0, 0, 0);
;         acc[1] = __builtin_amdgcn_mfma_f32_16x16x32_bf16(fr6[1][i], fr6[3][i], acc[1], 0, 0, 0);
;         acc[2] = __builtin_amdgcn_mfma_f32_16x16x32_bf16(fr6[2][i], fr6[3][i], acc[2], 0, 0, 0);
;         acc[3] = __builtin_amdgcn_mfma_f32_16x16x32_bf16(fr6[4][i], fr6[2][i], acc[3], 0, 0, 0);
;         acc[4] = __builtin_amdgcn_mfma_f32_16x16x32_bf16(fr6[5][i], fr6[2][i], acc[4], 0, 0, 0);
;     }
;     LAS f32x4* red = (LAS f32x4*)lds;
; #pragma unroll
;     for (int g = 0; g < 5; ++g) red[(w * 5 + g) * 64 + lane] = acc[g];
;     __syncthreads();
	ds_read_b128 v[178:181], v119
	ds_read_b128 v[182:185], v119 offset:64
	ds_read_b128 v[188:191], v119 offset:128
	ds_read_b128 v[192:195], v119 offset:192
	ds_read_b128 v[196:199], v119 offset:256
	ds_read_b128 v[200:203], v119 offset:320
	ds_read_b128 v[204:207], v119 offset:384
	ds_read_b128 v[208:211], v119 offset:448
	s_waitcnt lgkmcnt(0)
	v_mfma_f32_16x16x32_bf16 v[4:7], v[178:181], v[24:27], 0
	v_mfma_f32_16x16x32_bf16 v[4:7], v[182:185], v[28:31], v[4:7]
	v_mfma_f32_16x16x32_bf16 v[4:7], v[188:191], v[32:35], v[4:7]
	v_mfma_f32_16x16x32_bf16 v[4:7], v[192:195], v[36:39], v[4:7]
	v_mfma_f32_16x16x32_bf16 v[4:7], v[196:199], v[40:43], v[4:7]
	v_mfma_f32_16x16x32_bf16 v[4:7], v[200:203], v[44:47], v[4:7]
	v_mfma_f32_16x16x32_bf16 v[4:7], v[204:207], v[48:51], v[4:7]
	v_mfma_f32_16x16x32_bf16 v[4:7], v[208:211], v[52:55], v[4:7]
	s_nop 3
	global_load_dwordx4 v[178:181], v110, s[26:27]
	global_load_dwordx4 v[182:185], v111, s[26:27]
	global_load_dwordx4 v[188:191], v112, s[26:27]
	global_load_dwordx4 v[192:195], v113, s[26:27]
	global_load_dwordx4 v[196:199], v114, s[26:27]
	global_load_dwordx4 v[200:203], v115, s[26:27]
	global_load_dwordx4 v[204:207], v116, s[26:27]
	global_load_dwordx4 v[208:211], v117, s[26:27]
	s_waitcnt vmcnt(16)
	ds_write_b128 v118, v[212:215]
	ds_write_b128 v118, v[216:219] offset:1056
	ds_write_b128 v118, v[220:223] offset:2112
	ds_write_b128 v118, v[224:227] offset:3168
	ds_write_b128 v118, v[228:231] offset:4224
	ds_write_b128 v118, v[232:235] offset:5280
	ds_write_b128 v118, v[236:239] offset:6336
	ds_write_b128 v118, v[240:243] offset:7392
	s_waitcnt lgkmcnt(0)
	ds_read_b128 v[212:215], v119
	ds_read_b128 v[216:219], v119 offset:64
	ds_read_b128 v[220:223], v119 offset:128
	ds_read_b128 v[224:227], v119 offset:192
	ds_read_b128 v[228:231], v119 offset:256
	ds_read_b128 v[232:235], v119 offset:320
	ds_read_b128 v[236:239], v119 offset:384
	ds_read_b128 v[240:243], v119 offset:448
	s_waitcnt lgkmcnt(0)
	v_mfma_f32_16x16x32_bf16 v[8:11], v[212:215], v[24:27], 0
	v_mfma_f32_16x16x32_bf16 v[8:11], v[216:219], v[28:31], v[8:11]
	v_mfma_f32_16x16x32_bf16 v[8:11], v[220:223], v[32:35], v[8:11]
	v_mfma_f32_16x16x32_bf16 v[8:11], v[224:227], v[36:39], v[8:11]
	v_mfma_f32_16x16x32_bf16 v[8:11], v[228:231], v[40:43], v[8:11]
	v_mfma_f32_16x16x32_bf16 v[8:11], v[232:235], v[44:47], v[8:11]
	v_mfma_f32_16x16x32_bf16 v[8:11], v[236:239], v[48:51], v[8:11]
	v_mfma_f32_16x16x32_bf16 v[8:11], v[240:243], v[52:55], v[8:11]
	s_waitcnt vmcnt(8)
	ds_write_b128 v118, v[56:59]
	ds_write_b128 v118, v[60:63] offset:1056
	ds_write_b128 v118, v[82:85] offset:2112
	ds_write_b128 v118, v[86:89] offset:3168
	ds_write_b128 v118, v[162:165] offset:4224
	ds_write_b128 v118, v[166:169] offset:5280
	ds_write_b128 v118, v[170:173] offset:6336
	ds_write_b128 v118, v[174:177] offset:7392
	s_waitcnt lgkmcnt(0)
	ds_read_b128 v[56:59], v119
	ds_read_b128 v[60:63], v119 offset:64
	ds_read_b128 v[82:85], v119 offset:128
	ds_read_b128 v[86:89], v119 offset:192
	ds_read_b128 v[162:165], v119 offset:256
	ds_read_b128 v[166:169], v119 offset:320
	ds_read_b128 v[170:173], v119 offset:384
	ds_read_b128 v[174:177], v119 offset:448
	s_waitcnt lgkmcnt(0)
	v_mfma_f32_16x16x32_bf16 v[12:15], v[56:59], v[212:215], 0
	v_mfma_f32_16x16x32_bf16 v[12:15], v[60:63], v[216:219], v[12:15]
	v_mfma_f32_16x16x32_bf16 v[12:15], v[82:85], v[220:223], v[12:15]
	v_mfma_f32_16x16x32_bf16 v[12:15], v[86:89], v[224:227], v[12:15]
	v_mfma_f32_16x16x32_bf16 v[12:15], v[162:165], v[228:231], v[12:15]
	v_mfma_f32_16x16x32_bf16 v[12:15], v[166:169], v[232:235], v[12:15]
	v_mfma_f32_16x16x32_bf16 v[12:15], v[170:173], v[236:239], v[12:15]
	v_mfma_f32_16x16x32_bf16 v[12:15], v[174:177], v[240:243], v[12:15]
	s_waitcnt vmcnt(0)
	ds_write_b128 v118, v[178:181]
	ds_write_b128 v118, v[182:185] offset:1056
	ds_write_b128 v118, v[188:191] offset:2112
	ds_write_b128 v118, v[192:195] offset:3168
	ds_write_b128 v118, v[196:199] offset:4224
	ds_write_b128 v118, v[200:203] offset:5280
	ds_write_b128 v118, v[204:207] offset:6336
	ds_write_b128 v118, v[208:211] offset:7392
	s_waitcnt lgkmcnt(0)
	ds_read_b128 v[178:181], v119
	ds_read_b128 v[182:185], v119 offset:64
	ds_read_b128 v[188:191], v119 offset:128
	ds_read_b128 v[192:195], v119 offset:192
	ds_read_b128 v[196:199], v119 offset:256
	ds_read_b128 v[200:203], v119 offset:320
	ds_read_b128 v[204:207], v119 offset:384
	ds_read_b128 v[208:211], v119 offset:448
	s_waitcnt lgkmcnt(0)
	v_mfma_f32_16x16x32_bf16 v[16:19], v[178:181], v[212:215], 0
	v_mfma_f32_16x16x32_bf16 v[16:19], v[182:185], v[216:219], v[16:19]
	v_mfma_f32_16x16x32_bf16 v[16:19], v[188:191], v[220:223], v[16:19]
	v_mfma_f32_16x16x32_bf16 v[16:19], v[192:195], v[224:227], v[16:19]
	v_mfma_f32_16x16x32_bf16 v[16:19], v[196:199], v[228:231], v[16:19]
	v_mfma_f32_16x16x32_bf16 v[16:19], v[200:203], v[232:235], v[16:19]
	v_mfma_f32_16x16x32_bf16 v[16:19], v[204:207], v[236:239], v[16:19]
	v_mfma_f32_16x16x32_bf16 v[16:19], v[208:211], v[240:243], v[16:19]
	s_cmp_gt_u32 s37, 63
	s_nop 7
	s_nop 7
	s_nop 3
	ds_write_b128 v20, v[0:3]
	ds_write_b128 v20, v[4:7] offset:1024
	ds_write_b128 v20, v[8:11] offset:2048
	ds_write_b128 v20, v[12:15] offset:3072
	ds_write_b128 v20, v[16:19] offset:4096
	s_waitcnt lgkmcnt(0)
	s_barrier
	s_cbranch_scc1 .LBB0_414
; __device__ __forceinline__ void p1_side_task(int c, LAS unsigned char* lds, const bf16_t* XN, const bf16_t* WIN, const float* b_f, float* LF, bf16_t* Kb, bf16_t* Vb, bf16_t* P1b) {
;     ...
;     if (w == 0) {
; #pragma unroll
;         for (int g = 0; g < 5; ++g) { f32x4 s = red[g * 64 + lane];
; #pragma unroll
;             for (int ww = 1; ww < 8; ++ww) s += red[(ww * 5 + g) * 64 + lane];
;             acc[g] = s; }
;         const float bfh = b_f[fr];
; #pragma unroll
;         for (int g = 0; g < 3; ++g)
; #pragma unroll
;             for (int j = 0; j < 4; ++j) { const float xx = acc[g][j] + bfh; const float v = (fminf(xx, 0.f) - log1pf(__expf(-fabsf(xx)))) * LOG2E; const int m = 4 * fq + j;
;                 if (g < 2) { const int row = 32 * c + 16 * g + m; LF[(size_t)((row >> 12) * NH + fr) * KVROWS + 64 + (row & 4095)] = v; }
	ds_read_b128 v[82:85], v91
	ds_read_b128 v[98:101], v91 offset:1024
	ds_read_b128 v[102:105], v91 offset:5120
	ds_read_b128 v[106:109], v91 offset:6144
	ds_read_b128 v[110:113], v91 offset:10240
	ds_read_b128 v[114:117], v91 offset:11264
	ds_read_b128 v[118:121], v91 offset:15360
	ds_read_b128 v[122:125], v91 offset:16384
	ds_read_b128 v[126:129], v91 offset:20480
	ds_read_b128 v[130:133], v91 offset:21504
	ds_read_b128 v[138:141], v91 offset:25600
	ds_read_b128 v[142:145], v91 offset:26624
	ds_read_b128 v[146:149], v91 offset:30720
	ds_read_b128 v[150:153], v91 offset:31744
	ds_read_b128 v[154:157], v91 offset:35840
	ds_read_b128 v[158:161], v91 offset:36864
	ds_read_b128 v[52:55], v91 offset:3072
	ds_read_b128 v[20:23], v91 offset:4096
	ds_read_b128 v[60:63], v91 offset:8192
	ds_read_b128 v[28:31], v91 offset:9216
	ds_read_b128 v[56:59], v91 offset:13312
	ds_read_b128 v[24:27], v91 offset:14336
	ds_read_b128 v[48:51], v91 offset:18432
	ds_read_b128 v[16:19], v91 offset:19456
	ds_read_b128 v[44:47], v91 offset:23552
	ds_read_b128 v[12:15], v91 offset:24576
	ds_read_b128 v[40:43], v91 offset:28672
	ds_read_b128 v[8:11], v91 offset:29696
	ds_read_b128 v[36:39], v91 offset:33792
	ds_read_b128 v[4:7], v91 offset:34816
	ds_read_b128 v[32:35], v91 offset:38912
	ds_read_b128 v[0:3], v91 offset:39936
	s_waitcnt lgkmcnt(14)
	v_pk_add_f32 v[84:85], v[84:85], v[104:105]
	v_pk_add_f32 v[82:83], v[82:83], v[102:103]
	v_pk_add_f32 v[84:85], v[84:85], v[112:113]
	v_pk_add_f32 v[82:83], v[82:83], v[110:111]
	v_pk_add_f32 v[88:89], v[100:101], v[108:109]
	v_pk_add_f32 v[98:99], v[98:99], v[106:107]
	v_pk_add_f32 v[84:85], v[84:85], v[120:121]
	v_pk_add_f32 v[82:83], v[82:83], v[118:119]
	v_pk_add_f32 v[88:89], v[88:89], v[116:117]
	v_pk_add_f32 v[98:99], v[98:99], v[114:115]
	v_pk_add_f32 v[84:85], v[84:85], v[128:129]
	v_pk_add_f32 v[82:83], v[82:83], v[126:127]
	v_pk_add_f32 v[88:89], v[88:89], v[124:125]
	v_pk_add_f32 v[98:99], v[98:99], v[122:123]
	v_pk_add_f32 v[84:85], v[84:85], v[140:141]
	v_pk_add_f32 v[82:83], v[82:83], v[138:139]
	v_pk_add_f32 v[88:89], v[88:89], v[132:133]
	v_pk_add_f32 v[98:99], v[98:99], v[130:131]
	v_pk_add_f32 v[84:85], v[84:85], v[148:149]
	v_pk_add_f32 v[82:83], v[82:83], v[146:147]
	v_pk_add_f32 v[88:89], v[88:89], v[144:145]
	v_pk_add_f32 v[98:99], v[98:99], v[142:143]
	v_pk_add_f32 v[100:101], v[84:85], v[156:157]
	v_pk_add_f32 v[84:85], v[82:83], v[154:155]
	v_pk_add_f32 v[88:89], v[88:89], v[152:153]
	v_pk_add_f32 v[98:99], v[98:99], v[150:151]
	v_pk_add_f32 v[82:83], v[88:89], v[160:161]
	v_pk_add_f32 v[88:89], v[98:99], v[158:159]
	s_lshr_b32 s11, s10, 8
	s_and_b32 s26, s10, 0xfe0
	s_and_b32 s11, s11, 0xfffff0
	v_or_b32_e32 v64, s26, v92
	v_or_b32_e32 v86, s11, v136
	v_readlane_b32 s26, v248, 52
	v_mul_hi_i32_i24_e32 v87, 0x4100, v86
	v_mul_i32_i24_e32 v86, 0x4100, v86
	v_readlane_b32 s27, v248, 53
	v_lshlrev_b32_e32 v64, 2, v64
	s_cmp_lg_u32 s36, 0
	v_lshl_add_u64 v[86:87], s[26:27], 0, v[86:87]
	v_lshl_add_u64 v[86:87], v[86:87], 0, v[64:65]
	s_waitcnt vmcnt(0)
	v_add_f32_e32 v84, v84, v97
	v_add_f32_e32 v85, v85, v97
	v_mul_f32_e64 v98, |v84|, s19
	v_mul_f32_e64 v99, |v85|, s19
	v_exp_f32_e32 v130, v98
	v_exp_f32_e32 v131, v99
	v_min_f32_e32 v98, 0, v84
	v_min_f32_e32 v99, 0, v85
	v_add_f32_e32 v104, 1.0, v130
	v_add_f32_e32 v106, 1.0, v131
	v_cvt_f64_f32_e32 v[84:85], v104
	v_add_f32_e32 v107, -1.0, v104
	v_cvt_f64_f32_e32 v[102:103], v106
	v_frexp_exp_i32_f64_e32 v84, v[84:85]
	v_sub_f32_e32 v85, v130, v107
	v_sub_f32_e32 v107, v107, v104
	v_frexp_exp_i32_f64_e32 v102, v[102:103]
	v_add_f32_e32 v103, 1.0, v107
	v_add_f32_e32 v85, v85, v103
	v_add_f32_e32 v103, -1.0, v106
	v_frexp_mant_f32_e32 v108, v106
	v_sub_f32_e32 v107, v131, v103
	v_sub_f32_e32 v103, v103, v106
	v_add_f32_e32 v103, 1.0, v103
	v_cmp_gt_f32_e32 vcc, s21, v108
	v_frexp_mant_f32_e32 v105, v104
	v_add_f32_e32 v103, v107, v103
	v_subbrev_co_u32_e32 v107, vcc, 0, v102, vcc
	v_cmp_gt_f32_e32 vcc, s21, v105
	v_cvt_f32_i32_e32 v105, v107
	v_sub_u32_e32 v107, 0, v107
	v_subbrev_co_u32_e32 v108, vcc, 0, v84, vcc
	v_sub_u32_e32 v102, 0, v108
	v_ldexp_f32 v84, v104, v102
	v_ldexp_f32 v102, v85, v102
	v_ldexp_f32 v85, v106, v107
	v_pk_add_f32 v[116:117], v[84:85], 1.0 op_sel_hi:[1,0]
	v_ldexp_f32 v103, v103, v107
	v_pk_add_f32 v[118:119], v[116:117], -1.0 op_sel_hi:[1,0]
	v_pk_add_f32 v[112:113], v[84:85], -1.0 op_sel_hi:[1,0]
	v_pk_add_f32 v[118:119], v[84:85], v[118:119] neg_lo:[0,1] neg_hi:[0,1]
	v_pk_add_f32 v[114:115], v[112:113], 1.0 op_sel_hi:[1,0]
	v_pk_add_f32 v[118:119], v[102:103], v[118:119]
	v_pk_add_f32 v[84:85], v[84:85], v[114:115] neg_lo:[0,1] neg_hi:[0,1]
	v_pk_add_f32 v[120:121], v[116:117], v[118:119]
	v_pk_add_f32 v[84:85], v[102:103], v[84:85]
	v_rcp_f32_e32 v122, v120
	v_rcp_f32_e32 v123, v121
	v_pk_add_f32 v[102:103], v[112:113], v[84:85]
	v_pk_add_f32 v[116:117], v[120:121], v[116:117] neg_lo:[0,1] neg_hi:[0,1]
	v_pk_add_f32 v[112:113], v[102:103], v[112:113] neg_lo:[0,1] neg_hi:[0,1]
	v_pk_mul_f32 v[114:115], v[102:103], v[122:123]
	v_pk_add_f32 v[116:117], v[118:119], v[116:117] neg_lo:[0,1] neg_hi:[0,1]
	v_pk_mul_f32 v[124:125], v[120:121], v[114:115]
	v_pk_add_f32 v[84:85], v[84:85], v[112:113] neg_lo:[0,1] neg_hi:[0,1]
	v_pk_fma_f32 v[118:119], v[114:115], v[120:121], v[124:125] neg_lo:[0,0,1] neg_hi:[0,0,1]
	v_cvt_f32_i32_e32 v104, v108
	v_pk_fma_f32 v[118:119], v[114:115], v[116:117], v[118:119]
	v_cmp_neq_f32_e32 vcc, s33, v130
	v_pk_add_f32 v[126:127], v[124:125], v[118:119]
	v_pk_mul_f32 v[106:107], v[104:105], s[12:13] op_sel_hi:[1,0]
	v_pk_add_f32 v[128:129], v[102:103], v[126:127] neg_lo:[0,1] neg_hi:[0,1]
; __device__ __forceinline__ void p1_side_task(int c, LAS unsigned char* lds, const bf16_t* XN, const bf16_t* WIN, const float* b_f, float* LF, bf16_t* Kb, bf16_t* Vb, bf16_t* P1b) {
;     ...
;             for (int j = 0; j < 4; ++j) { const float xx = acc[g][j] + bfh; const float v = (fminf(xx, 0.f) - log1pf(__expf(-fabsf(xx)))) * LOG2E; const int m = 4 * fq + j;
;                 if (g < 2) { const int row = 32 * c + 16 * g + m; LF[(size_t)((row >> 12) * NH + fr) * KVROWS + 64 + (row & 4095)] = v; }
	v_pk_add_f32 v[124:125], v[126:127], v[124:125] neg_lo:[0,1] neg_hi:[0,1]
	v_pk_add_f32 v[102:103], v[102:103], v[128:129] neg_lo:[0,1] neg_hi:[0,1]
	v_pk_add_f32 v[118:119], v[124:125], v[118:119] neg_lo:[0,1] neg_hi:[0,1]
	v_pk_add_f32 v[102:103], v[102:103], v[126:127] neg_lo:[0,1] neg_hi:[0,1]
	v_pk_fma_f32 v[108:109], v[104:105], s[12:13], v[106:107] op_sel_hi:[1,0,1] neg_lo:[0,0,1] neg_hi:[0,0,1]
	v_pk_add_f32 v[84:85], v[84:85], v[102:103]
	v_pk_fma_f32 v[104:105], v[104:105], s[14:15], v[108:109] op_sel_hi:[1,0,1]
	v_pk_add_f32 v[84:85], v[118:119], v[84:85]
	v_pk_add_f32 v[108:109], v[106:107], v[104:105]
	v_pk_add_f32 v[102:103], v[128:129], v[84:85]
	v_pk_add_f32 v[110:111], v[108:109], v[106:107] neg_lo:[0,1] neg_hi:[0,1]
	v_pk_mul_f32 v[112:113], v[122:123], v[102:103]
	v_mov_b32_e32 v106, v108
	v_pk_mul_f32 v[118:119], v[120:121], v[112:113]
	v_pk_add_f32 v[124:125], v[114:115], v[112:113]
	v_pk_fma_f32 v[120:121], v[112:113], v[120:121], v[118:119] neg_lo:[0,0,1] neg_hi:[0,0,1]
	v_pk_add_f32 v[114:115], v[124:125], v[114:115] neg_lo:[0,1] neg_hi:[0,1]
	v_add_f32_e32 v100, v100, v97
	v_pk_add_f32 v[114:115], v[112:113], v[114:115] neg_lo:[0,1] neg_hi:[0,1]
	v_pk_fma_f32 v[112:113], v[112:113], v[116:117], v[120:121]
	v_add_f32_e32 v101, v101, v97
	v_pk_add_f32 v[116:117], v[118:119], v[112:113]
	v_add_f32_e32 v89, v89, v97
	v_pk_add_f32 v[120:121], v[102:103], v[116:117] neg_lo:[0,1] neg_hi:[0,1]
	v_pk_add_f32 v[118:119], v[116:117], v[118:119] neg_lo:[0,1] neg_hi:[0,1]
	v_add_f32_e32 v83, v83, v97
	v_pk_add_f32 v[112:113], v[118:119], v[112:113] neg_lo:[0,1] neg_hi:[0,1]
	v_pk_add_f32 v[118:119], v[128:129], v[102:103] neg_lo:[0,1] neg_hi:[0,1]
	v_pk_add_f32 v[102:103], v[102:103], v[120:121] neg_lo:[0,1] neg_hi:[0,1]
	v_pk_add_f32 v[84:85], v[84:85], v[118:119]
	v_pk_add_f32 v[102:103], v[102:103], v[116:117] neg_lo:[0,1] neg_hi:[0,1]
	s_nop 0
	v_pk_add_f32 v[84:85], v[84:85], v[102:103]
	s_nop 0
	v_pk_add_f32 v[84:85], v[112:113], v[84:85]
	s_nop 0
	v_pk_add_f32 v[84:85], v[120:121], v[84:85]
	v_mov_b32_e32 v121, v109
	v_pk_mul_f32 v[84:85], v[122:123], v[84:85]
	s_nop 0
	v_pk_add_f32 v[84:85], v[114:115], v[84:85]
	s_nop 0
	v_pk_add_f32 v[102:103], v[124:125], v[84:85]
	s_nop 0
	v_pk_add_f32 v[114:115], v[102:103], v[124:125] neg_lo:[0,1] neg_hi:[0,1]
	v_pk_mul_f32 v[116:117], v[102:103], v[102:103]
	v_pk_add_f32 v[114:115], v[84:85], v[114:115] neg_lo:[0,1] neg_hi:[0,1]
	v_mov_b64_e32 v[84:85], s[16:17]
	v_pk_fma_f32 v[118:119], v[116:117], s[18:19], v[84:85] op_sel_hi:[1,0,0]
	v_ldexp_f32 v112, v102, 1
	v_ldexp_f32 v113, v103, 1
	v_pk_mul_f32 v[102:103], v[102:103], v[116:117]
	v_pk_fma_f32 v[116:117], v[116:117], v[118:119], s[20:21] op_sel_hi:[1,1,0]
	v_ldexp_f32 v114, v114, 1
	v_pk_mul_f32 v[102:103], v[102:103], v[116:117]
	v_ldexp_f32 v115, v115, 1
	v_pk_add_f32 v[116:117], v[112:113], v[102:103]
	s_nop 0
	v_pk_add_f32 v[112:113], v[116:117], v[112:113] neg_lo:[0,1] neg_hi:[0,1]
	s_nop 0
	v_pk_add_f32 v[102:103], v[102:103], v[112:113] neg_lo:[0,1] neg_hi:[0,1]
	s_nop 0
	v_pk_add_f32 v[102:103], v[114:115], v[102:103]
	s_nop 0
	v_pk_add_f32 v[112:113], v[116:117], v[102:103]
	s_nop 0
	v_pk_add_f32 v[118:119], v[108:109], v[112:113]
	v_pk_add_f32 v[114:115], v[112:113], v[116:117] neg_lo:[0,1] neg_hi:[0,1]
	v_mov_b32_e32 v120, v118
	v_pk_add_f32 v[106:107], v[120:121], v[106:107] neg_lo:[0,1] neg_hi:[0,1]
	v_mov_b32_e32 v120, v112
	v_mov_b32_e32 v121, v105
	v_pk_add_f32 v[120:121], v[120:121], v[106:107] neg_lo:[0,1] neg_hi:[0,1]
	v_mov_b32_e32 v111, v107
	v_mov_b32_e32 v112, v118
	v_mov_b32_e32 v107, v117
	v_pk_add_f32 v[106:107], v[112:113], v[106:107] neg_lo:[0,1] neg_hi:[0,1]
	v_mov_b32_e32 v116, v108
	v_mov_b32_e32 v117, v103
	v_mov_b32_e32 v115, v107
	v_pk_add_f32 v[124:125], v[118:119], v[108:109] neg_lo:[0,1] neg_hi:[0,1]
	v_pk_add_f32 v[116:117], v[116:117], v[106:107] neg_lo:[0,1] neg_hi:[0,1]
	v_pk_add_f32 v[106:107], v[102:103], v[114:115] neg_lo:[0,1] neg_hi:[0,1]
	v_mov_b32_e32 v103, v113
	v_pk_add_f32 v[112:113], v[118:119], v[124:125] neg_lo:[0,1] neg_hi:[0,1]
	v_pk_add_f32 v[122:123], v[104:105], v[110:111] neg_lo:[0,1] neg_hi:[0,1]
	v_mov_b32_e32 v115, v125
	v_mov_b32_e32 v105, v109
	v_mov_b32_e32 v111, v113
	v_pk_add_f32 v[102:103], v[102:103], v[114:115] neg_lo:[0,1] neg_hi:[0,1]
	v_pk_add_f32 v[104:105], v[104:105], v[110:111] neg_lo:[0,1] neg_hi:[0,1]
	v_pk_add_f32 v[116:117], v[120:121], v[116:117]
	v_pk_add_f32 v[102:103], v[102:103], v[104:105]
	v_mov_b32_e32 v105, v121
	v_pk_add_f32 v[108:109], v[116:117], v[102:103]
	v_mov_b32_e32 v103, v117
	v_pk_add_f32 v[104:105], v[102:103], v[104:105] neg_lo:[0,1] neg_hi:[0,1]
	v_pk_add_f32 v[110:111], v[118:119], v[108:109]
	v_pk_add_f32 v[102:103], v[102:103], v[104:105] neg_lo:[0,1] neg_hi:[0,1]
	v_pk_add_f32 v[106:107], v[106:107], v[104:105] neg_lo:[0,1] neg_hi:[0,1]
	v_pk_add_f32 v[102:103], v[122:123], v[102:103] neg_lo:[0,1] neg_hi:[0,1]
	v_pk_add_f32 v[104:105], v[110:111], v[118:119] neg_lo:[0,1] neg_hi:[0,1]
	v_pk_add_f32 v[102:103], v[106:107], v[102:103]
	v_pk_add_f32 v[104:105], v[108:109], v[104:105] neg_lo:[0,1] neg_hi:[0,1]
	s_nop 0
	v_pk_add_f32 v[102:103], v[102:103], v[104:105]
	v_mul_f32_e64 v104, |v100|, s19
	v_pk_add_f32 v[102:103], v[110:111], v[102:103]
	v_exp_f32_e32 v132, v104
	v_cndmask_b32_e32 v102, v94, v102, vcc
	v_cmp_neq_f32_e32 vcc, s33, v131
	v_min_f32_e32 v100, 0, v100
	v_add_f32_e32 v104, 1.0, v132
	v_cndmask_b32_e32 v103, v94, v103, vcc
	v_cmp_ngt_f32_e32 vcc, -1.0, v131
	v_frexp_mant_f32_e32 v106, v104
	s_nop 0
	v_cndmask_b32_e32 v103, v95, v103, vcc
	v_cmp_ngt_f32_e32 vcc, -1.0, v130
	s_nop 1
; __device__ __forceinline__ void p1_side_task(int c, LAS unsigned char* lds, const bf16_t* XN, const bf16_t* WIN, const float* b_f, float* LF, bf16_t* Kb, bf16_t* Vb, bf16_t* P1b) {
;     ...
;             for (int j = 0; j < 4; ++j) { const float xx = acc[g][j] + bfh; const float v = (fminf(xx, 0.f) - log1pf(__expf(-fabsf(xx)))) * LOG2E; const int m = 4 * fq + j;
;                 if (g < 2) { const int row = 32 * c + 16 * g + m; LF[(size_t)((row >> 12) * NH + fr) * KVROWS + 64 + (row & 4095)] = v; }
	v_cndmask_b32_e32 v102, v95, v102, vcc
	v_cmp_neq_f32_e32 vcc, -1.0, v130
	s_nop 1
	v_cndmask_b32_e32 v102, v96, v102, vcc
	v_cmp_neq_f32_e32 vcc, -1.0, v131
	s_nop 1
	v_cndmask_b32_e32 v103, v96, v103, vcc
	v_cmp_lt_f32_e64 vcc, |v131|, s23
	s_nop 1
	v_cndmask_b32_e32 v103, v103, v131, vcc
	v_cmp_lt_f32_e64 vcc, |v130|, s23
	s_nop 1
	v_cndmask_b32_e32 v102, v102, v130, vcc
	v_pk_add_f32 v[98:99], v[98:99], v[102:103] neg_lo:[0,1] neg_hi:[0,1]
	v_cvt_f64_f32_e32 v[102:103], v104
	v_frexp_exp_i32_f64_e32 v105, v[102:103]
	v_add_f32_e32 v102, -1.0, v104
	v_sub_f32_e32 v103, v132, v102
	v_sub_f32_e32 v102, v102, v104
	v_add_f32_e32 v102, 1.0, v102
	v_add_f32_e32 v107, v103, v102
	v_mul_f32_e64 v102, |v101|, s19
	v_exp_f32_e32 v133, v102
	v_min_f32_e32 v101, 0, v101
	v_pk_mul_f32 v[98:99], v[98:99], s[22:23] op_sel_hi:[1,0]
	v_add_f32_e32 v64, 1.0, v133
	v_cvt_f64_f32_e32 v[102:103], v64
	v_frexp_exp_i32_f64_e32 v102, v[102:103]
	v_frexp_mant_f32_e32 v103, v64
	v_cmp_gt_f32_e32 vcc, s21, v103
	v_add_f32_e32 v108, -1.0, v64
	v_sub_f32_e32 v109, v133, v108
	v_subbrev_co_u32_e32 v103, vcc, 0, v102, vcc
	v_cmp_gt_f32_e32 vcc, s21, v106
	v_sub_f32_e32 v108, v108, v64
	v_add_f32_e32 v108, 1.0, v108
	v_subbrev_co_u32_e32 v105, vcc, 0, v105, vcc
	v_sub_u32_e32 v106, 0, v105
	v_ldexp_f32 v102, v104, v106
	v_ldexp_f32 v104, v107, v106
	v_cvt_f32_i32_e32 v106, v105
	v_sub_u32_e32 v105, 0, v103
	v_cvt_f32_i32_e32 v107, v103
	v_ldexp_f32 v103, v64, v105
	v_pk_add_f32 v[118:119], v[102:103], 1.0 op_sel_hi:[1,0]
	v_add_f32_e32 v108, v109, v108
	v_pk_add_f32 v[120:121], v[118:119], -1.0 op_sel_hi:[1,0]
	v_ldexp_f32 v105, v108, v105
	v_pk_add_f32 v[120:121], v[102:103], v[120:121] neg_lo:[0,1] neg_hi:[0,1]
	v_pk_add_f32 v[114:115], v[102:103], -1.0 op_sel_hi:[1,0]
	v_pk_add_f32 v[120:121], v[104:105], v[120:121]
	v_pk_add_f32 v[116:117], v[114:115], 1.0 op_sel_hi:[1,0]
	v_pk_add_f32 v[122:123], v[118:119], v[120:121]
	v_pk_add_f32 v[102:103], v[102:103], v[116:117] neg_lo:[0,1] neg_hi:[0,1]
	v_rcp_f32_e32 v124, v122
	v_rcp_f32_e32 v125, v123
	v_pk_add_f32 v[102:103], v[104:105], v[102:103]
	v_pk_add_f32 v[118:119], v[122:123], v[118:119] neg_lo:[0,1] neg_hi:[0,1]
	v_pk_add_f32 v[104:105], v[114:115], v[102:103]
	v_pk_add_f32 v[118:119], v[120:121], v[118:119] neg_lo:[0,1] neg_hi:[0,1]
	v_pk_mul_f32 v[116:117], v[104:105], v[124:125]
	v_pk_add_f32 v[114:115], v[104:105], v[114:115] neg_lo:[0,1] neg_hi:[0,1]
	v_pk_mul_f32 v[126:127], v[122:123], v[116:117]
	v_pk_add_f32 v[102:103], v[102:103], v[114:115] neg_lo:[0,1] neg_hi:[0,1]
	v_pk_fma_f32 v[120:121], v[116:117], v[122:123], v[126:127] neg_lo:[0,0,1] neg_hi:[0,0,1]
	v_pk_mul_f32 v[108:109], v[106:107], s[12:13] op_sel_hi:[1,0]
	v_pk_fma_f32 v[120:121], v[116:117], v[118:119], v[120:121]
	v_pk_fma_f32 v[110:111], v[106:107], s[12:13], v[108:109] op_sel_hi:[1,0,1] neg_lo:[0,0,1] neg_hi:[0,0,1]
	v_pk_add_f32 v[128:129], v[126:127], v[120:121]
	v_pk_fma_f32 v[106:107], v[106:107], s[14:15], v[110:111] op_sel_hi:[1,0,1]
	v_pk_add_f32 v[130:131], v[104:105], v[128:129] neg_lo:[0,1] neg_hi:[0,1]
	v_pk_add_f32 v[126:127], v[128:129], v[126:127] neg_lo:[0,1] neg_hi:[0,1]
	v_pk_add_f32 v[104:105], v[104:105], v[130:131] neg_lo:[0,1] neg_hi:[0,1]
	v_pk_add_f32 v[120:121], v[126:127], v[120:121] neg_lo:[0,1] neg_hi:[0,1]
	v_pk_add_f32 v[104:105], v[104:105], v[128:129] neg_lo:[0,1] neg_hi:[0,1]
	v_pk_add_f32 v[110:111], v[108:109], v[106:107]
	v_pk_add_f32 v[102:103], v[102:103], v[104:105]
	v_pk_add_f32 v[112:113], v[110:111], v[108:109] neg_lo:[0,1] neg_hi:[0,1]
	v_pk_add_f32 v[102:103], v[120:121], v[102:103]
	v_mov_b32_e32 v108, v110
	v_pk_add_f32 v[104:105], v[130:131], v[102:103]
	v_cmp_neq_f32_e32 vcc, s33, v132
	v_pk_mul_f32 v[114:115], v[124:125], v[104:105]
	s_nop 0
	v_pk_mul_f32 v[120:121], v[122:123], v[114:115]
	v_pk_add_f32 v[126:127], v[116:117], v[114:115]
	v_pk_fma_f32 v[122:123], v[114:115], v[122:123], v[120:121] neg_lo:[0,0,1] neg_hi:[0,0,1]
	v_pk_add_f32 v[116:117], v[126:127], v[116:117] neg_lo:[0,1] neg_hi:[0,1]
	s_nop 0
	v_pk_add_f32 v[116:117], v[114:115], v[116:117] neg_lo:[0,1] neg_hi:[0,1]
	v_pk_fma_f32 v[114:115], v[114:115], v[118:119], v[122:123]
	s_nop 0
	v_pk_add_f32 v[118:119], v[120:121], v[114:115]
	s_nop 0
	v_pk_add_f32 v[122:123], v[104:105], v[118:119] neg_lo:[0,1] neg_hi:[0,1]
	v_pk_add_f32 v[120:121], v[118:119], v[120:121] neg_lo:[0,1] neg_hi:[0,1]
	s_nop 0
	v_pk_add_f32 v[114:115], v[120:121], v[114:115] neg_lo:[0,1] neg_hi:[0,1]
	v_pk_add_f32 v[120:121], v[130:131], v[104:105] neg_lo:[0,1] neg_hi:[0,1]
	v_pk_add_f32 v[104:105], v[104:105], v[122:123] neg_lo:[0,1] neg_hi:[0,1]
	v_pk_add_f32 v[102:103], v[102:103], v[120:121]
	v_pk_add_f32 v[104:105], v[104:105], v[118:119] neg_lo:[0,1] neg_hi:[0,1]
	v_mov_b32_e32 v121, v111
	v_pk_add_f32 v[102:103], v[102:103], v[104:105]
	s_nop 0
	v_pk_add_f32 v[102:103], v[114:115], v[102:103]
	s_nop 0
	v_pk_add_f32 v[102:103], v[122:123], v[102:103]
	s_nop 0
	v_pk_mul_f32 v[102:103], v[124:125], v[102:103]
	s_nop 0
	v_pk_add_f32 v[102:103], v[116:117], v[102:103]
	s_nop 0
	v_pk_add_f32 v[104:105], v[126:127], v[102:103]
	s_nop 0
	v_pk_add_f32 v[116:117], v[104:105], v[126:127] neg_lo:[0,1] neg_hi:[0,1]
	v_ldexp_f32 v114, v104, 1
	v_pk_add_f32 v[102:103], v[102:103], v[116:117] neg_lo:[0,1] neg_hi:[0,1]
	v_pk_mul_f32 v[116:117], v[104:105], v[104:105]
	v_ldexp_f32 v115, v105, 1
	v_pk_fma_f32 v[118:119], v[116:117], s[18:19], v[84:85] op_sel_hi:[1,0,0]
	v_pk_mul_f32 v[104:105], v[104:105], v[116:117]
	v_pk_fma_f32 v[116:117], v[116:117], v[118:119], s[20:21] op_sel_hi:[1,1,0]
	v_ldexp_f32 v102, v102, 1
	v_pk_mul_f32 v[104:105], v[104:105], v[116:117]
; __device__ __forceinline__ void p1_side_task(int c, LAS unsigned char* lds, const bf16_t* XN, const bf16_t* WIN, const float* b_f, float* LF, bf16_t* Kb, bf16_t* Vb, bf16_t* P1b) {
;     ...
;             for (int j = 0; j < 4; ++j) { const float xx = acc[g][j] + bfh; const float v = (fminf(xx, 0.f) - log1pf(__expf(-fabsf(xx)))) * LOG2E; const int m = 4 * fq + j;
;                 if (g < 2) { const int row = 32 * c + 16 * g + m; LF[(size_t)((row >> 12) * NH + fr) * KVROWS + 64 + (row & 4095)] = v; }
	v_ldexp_f32 v103, v103, 1
	v_pk_add_f32 v[116:117], v[114:115], v[104:105]
	s_nop 0
	v_pk_add_f32 v[114:115], v[116:117], v[114:115] neg_lo:[0,1] neg_hi:[0,1]
	s_nop 0
	v_pk_add_f32 v[104:105], v[104:105], v[114:115] neg_lo:[0,1] neg_hi:[0,1]
	s_nop 0
	v_pk_add_f32 v[102:103], v[102:103], v[104:105]
	s_nop 0
	v_pk_add_f32 v[104:105], v[116:117], v[102:103]
	s_nop 0
	v_pk_add_f32 v[118:119], v[110:111], v[104:105]
	v_pk_add_f32 v[114:115], v[104:105], v[116:117] neg_lo:[0,1] neg_hi:[0,1]
	v_mov_b32_e32 v120, v118
	v_pk_add_f32 v[108:109], v[120:121], v[108:109] neg_lo:[0,1] neg_hi:[0,1]
	v_mov_b32_e32 v120, v104
	v_mov_b32_e32 v121, v107
	v_pk_add_f32 v[120:121], v[120:121], v[108:109] neg_lo:[0,1] neg_hi:[0,1]
	v_mov_b32_e32 v113, v109
	v_mov_b32_e32 v104, v118
	v_mov_b32_e32 v109, v117
	v_pk_add_f32 v[108:109], v[104:105], v[108:109] neg_lo:[0,1] neg_hi:[0,1]
	v_mov_b32_e32 v116, v110
	v_mov_b32_e32 v117, v103
	v_mov_b32_e32 v115, v109
	v_pk_add_f32 v[124:125], v[118:119], v[110:111] neg_lo:[0,1] neg_hi:[0,1]
	v_pk_add_f32 v[116:117], v[116:117], v[108:109] neg_lo:[0,1] neg_hi:[0,1]
	v_pk_add_f32 v[108:109], v[102:103], v[114:115] neg_lo:[0,1] neg_hi:[0,1]
	v_mov_b32_e32 v103, v105
	v_pk_add_f32 v[104:105], v[118:119], v[124:125] neg_lo:[0,1] neg_hi:[0,1]
	v_pk_add_f32 v[122:123], v[106:107], v[112:113] neg_lo:[0,1] neg_hi:[0,1]
	v_mov_b32_e32 v115, v125
	v_mov_b32_e32 v107, v111
	v_mov_b32_e32 v113, v105
	v_pk_add_f32 v[102:103], v[102:103], v[114:115] neg_lo:[0,1] neg_hi:[0,1]
	v_pk_add_f32 v[104:105], v[106:107], v[112:113] neg_lo:[0,1] neg_hi:[0,1]
	v_pk_add_f32 v[116:117], v[120:121], v[116:117]
	v_pk_add_f32 v[102:103], v[102:103], v[104:105]
	v_mov_b32_e32 v105, v121
	v_pk_add_f32 v[106:107], v[116:117], v[102:103]
	v_mov_b32_e32 v103, v117
	v_pk_add_f32 v[104:105], v[102:103], v[104:105] neg_lo:[0,1] neg_hi:[0,1]
	v_pk_add_f32 v[110:111], v[118:119], v[106:107]
	v_pk_add_f32 v[102:103], v[102:103], v[104:105] neg_lo:[0,1] neg_hi:[0,1]
	v_pk_add_f32 v[108:109], v[108:109], v[104:105] neg_lo:[0,1] neg_hi:[0,1]
	v_pk_add_f32 v[102:103], v[122:123], v[102:103] neg_lo:[0,1] neg_hi:[0,1]
	v_pk_add_f32 v[104:105], v[110:111], v[118:119] neg_lo:[0,1] neg_hi:[0,1]
	v_pk_add_f32 v[102:103], v[108:109], v[102:103]
	v_pk_add_f32 v[104:105], v[106:107], v[104:105] neg_lo:[0,1] neg_hi:[0,1]
	s_nop 0
	v_pk_add_f32 v[102:103], v[102:103], v[104:105]
	s_nop 0
	v_pk_add_f32 v[102:103], v[110:111], v[102:103]
	s_nop 0
	v_cndmask_b32_e32 v64, v94, v102, vcc
	v_cmp_neq_f32_e32 vcc, s33, v133
	s_nop 1
	v_cndmask_b32_e32 v102, v94, v103, vcc
	v_cmp_ngt_f32_e32 vcc, -1.0, v133
	s_nop 1
	v_cndmask_b32_e32 v102, v95, v102, vcc
	v_cmp_ngt_f32_e32 vcc, -1.0, v132
	s_nop 1
	v_cndmask_b32_e32 v64, v95, v64, vcc
	v_cmp_neq_f32_e32 vcc, -1.0, v132
	s_nop 1
	v_cndmask_b32_e32 v64, v96, v64, vcc
	v_cmp_neq_f32_e32 vcc, -1.0, v133
	s_nop 1
	v_cndmask_b32_e32 v102, v96, v102, vcc
	v_cmp_lt_f32_e64 vcc, |v133|, s23
	s_nop 1
	v_cndmask_b32_e32 v103, v102, v133, vcc
	v_cmp_lt_f32_e64 vcc, |v132|, s23
	s_nop 1
	v_cndmask_b32_e32 v102, v64, v132, vcc
	v_add_f32_e32 v64, v88, v97
	v_mul_f32_e64 v88, |v64|, s19
	v_exp_f32_e32 v128, v88
	v_pk_add_f32 v[100:101], v[100:101], v[102:103] neg_lo:[0,1] neg_hi:[0,1]
	v_mul_f32_e64 v102, |v89|, s19
	v_pk_mul_f32 v[100:101], v[100:101], s[22:23] op_sel_hi:[1,0]
	v_min_f32_e32 v88, 0, v64
	v_add_f32_e32 v64, 1.0, v128
	v_exp_f32_e32 v129, v102
	global_store_dwordx4 v[86:87], v[98:101], off offset:256
	v_min_f32_e32 v89, 0, v89
	v_add_f32_e32 v104, 1.0, v129
	v_cvt_f64_f32_e32 v[98:99], v64
	v_frexp_exp_i32_f64_e32 v100, v[98:99]
	v_add_f32_e32 v98, -1.0, v64
	v_sub_f32_e32 v99, v128, v98
	v_sub_f32_e32 v98, v98, v64
	v_add_f32_e32 v98, 1.0, v98
	v_add_f32_e32 v102, v99, v98
	v_cvt_f64_f32_e32 v[98:99], v104
	v_frexp_exp_i32_f64_e32 v98, v[98:99]
	v_frexp_mant_f32_e32 v99, v104
	v_cmp_gt_f32_e32 vcc, s21, v99
	v_frexp_mant_f32_e32 v101, v64
	v_add_f32_e32 v103, -1.0, v104
	v_subbrev_co_u32_e32 v99, vcc, 0, v98, vcc
	v_cmp_gt_f32_e32 vcc, s21, v101
	v_sub_f32_e32 v105, v129, v103
	v_sub_f32_e32 v103, v103, v104
	v_subbrev_co_u32_e32 v101, vcc, 0, v100, vcc
	v_sub_u32_e32 v100, 0, v101
	v_add_f32_e32 v103, 1.0, v103
	v_ldexp_f32 v98, v64, v100
	v_sub_u32_e32 v64, 0, v99
	v_add_f32_e32 v105, v105, v103
	v_cvt_f32_i32_e32 v103, v99
	v_ldexp_f32 v99, v104, v64
	v_pk_add_f32 v[114:115], v[98:99], 1.0 op_sel_hi:[1,0]
	v_ldexp_f32 v100, v102, v100
	v_pk_add_f32 v[116:117], v[114:115], -1.0 op_sel_hi:[1,0]
	v_cvt_f32_i32_e32 v102, v101
	v_ldexp_f32 v101, v105, v64
	v_pk_add_f32 v[116:117], v[98:99], v[116:117] neg_lo:[0,1] neg_hi:[0,1]
	v_pk_add_f32 v[110:111], v[98:99], -1.0 op_sel_hi:[1,0]
	v_pk_add_f32 v[116:117], v[100:101], v[116:117]
	v_pk_add_f32 v[112:113], v[110:111], 1.0 op_sel_hi:[1,0]
	v_pk_add_f32 v[118:119], v[114:115], v[116:117]
	v_pk_add_f32 v[98:99], v[98:99], v[112:113] neg_lo:[0,1] neg_hi:[0,1]
	v_rcp_f32_e32 v120, v118
	v_rcp_f32_e32 v121, v119
	v_pk_add_f32 v[98:99], v[100:101], v[98:99]
	v_pk_add_f32 v[114:115], v[118:119], v[114:115] neg_lo:[0,1] neg_hi:[0,1]
	v_pk_add_f32 v[100:101], v[110:111], v[98:99]
	v_pk_add_f32 v[114:115], v[116:117], v[114:115] neg_lo:[0,1] neg_hi:[0,1]
	v_pk_mul_f32 v[112:113], v[100:101], v[120:121]
	v_pk_add_f32 v[110:111], v[100:101], v[110:111] neg_lo:[0,1] neg_hi:[0,1]
	v_pk_mul_f32 v[122:123], v[118:119], v[112:113]
	v_pk_add_f32 v[98:99], v[98:99], v[110:111] neg_lo:[0,1] neg_hi:[0,1]
	v_pk_fma_f32 v[116:117], v[112:113], v[118:119], v[122:123] neg_lo:[0,0,1] neg_hi:[0,0,1]
	v_pk_mul_f32 v[104:105], v[102:103], s[12:13] op_sel_hi:[1,0]
	v_pk_fma_f32 v[116:117], v[112:113], v[114:115], v[116:117]
; __device__ __forceinline__ void p1_side_task(int c, LAS unsigned char* lds, const bf16_t* XN, const bf16_t* WIN, const float* b_f, float* LF, bf16_t* Kb, bf16_t* Vb, bf16_t* P1b) {
;     ...
;             for (int j = 0; j < 4; ++j) { const float xx = acc[g][j] + bfh; const float v = (fminf(xx, 0.f) - log1pf(__expf(-fabsf(xx)))) * LOG2E; const int m = 4 * fq + j;
;                 if (g < 2) { const int row = 32 * c + 16 * g + m; LF[(size_t)((row >> 12) * NH + fr) * KVROWS + 64 + (row & 4095)] = v; }
	v_pk_fma_f32 v[106:107], v[102:103], s[12:13], v[104:105] op_sel_hi:[1,0,1] neg_lo:[0,0,1] neg_hi:[0,0,1]
	v_pk_add_f32 v[124:125], v[122:123], v[116:117]
	v_pk_fma_f32 v[102:103], v[102:103], s[14:15], v[106:107] op_sel_hi:[1,0,1]
	v_pk_add_f32 v[126:127], v[100:101], v[124:125] neg_lo:[0,1] neg_hi:[0,1]
	v_pk_add_f32 v[122:123], v[124:125], v[122:123] neg_lo:[0,1] neg_hi:[0,1]
	v_pk_add_f32 v[100:101], v[100:101], v[126:127] neg_lo:[0,1] neg_hi:[0,1]
	v_pk_add_f32 v[116:117], v[122:123], v[116:117] neg_lo:[0,1] neg_hi:[0,1]
	v_pk_add_f32 v[100:101], v[100:101], v[124:125] neg_lo:[0,1] neg_hi:[0,1]
	v_pk_add_f32 v[106:107], v[104:105], v[102:103]
	v_pk_add_f32 v[98:99], v[98:99], v[100:101]
	v_pk_add_f32 v[108:109], v[106:107], v[104:105] neg_lo:[0,1] neg_hi:[0,1]
	v_pk_add_f32 v[98:99], v[116:117], v[98:99]
	v_mov_b32_e32 v104, v106
	v_pk_add_f32 v[100:101], v[126:127], v[98:99]
	v_cmp_neq_f32_e32 vcc, s33, v128
	v_pk_mul_f32 v[110:111], v[120:121], v[100:101]
	s_nop 0
	v_pk_mul_f32 v[116:117], v[118:119], v[110:111]
	v_pk_add_f32 v[122:123], v[112:113], v[110:111]
	v_pk_fma_f32 v[118:119], v[110:111], v[118:119], v[116:117] neg_lo:[0,0,1] neg_hi:[0,0,1]
	v_pk_add_f32 v[112:113], v[122:123], v[112:113] neg_lo:[0,1] neg_hi:[0,1]
	s_nop 0
	v_pk_add_f32 v[112:113], v[110:111], v[112:113] neg_lo:[0,1] neg_hi:[0,1]
	v_pk_fma_f32 v[110:111], v[110:111], v[114:115], v[118:119]
	s_nop 0
	v_pk_add_f32 v[114:115], v[116:117], v[110:111]
	s_nop 0
	v_pk_add_f32 v[118:119], v[100:101], v[114:115] neg_lo:[0,1] neg_hi:[0,1]
	v_pk_add_f32 v[116:117], v[114:115], v[116:117] neg_lo:[0,1] neg_hi:[0,1]
	s_nop 0
	v_pk_add_f32 v[110:111], v[116:117], v[110:111] neg_lo:[0,1] neg_hi:[0,1]
	v_pk_add_f32 v[116:117], v[126:127], v[100:101] neg_lo:[0,1] neg_hi:[0,1]
	v_pk_add_f32 v[100:101], v[100:101], v[118:119] neg_lo:[0,1] neg_hi:[0,1]
	v_pk_add_f32 v[98:99], v[98:99], v[116:117]
	v_pk_add_f32 v[100:101], v[100:101], v[114:115] neg_lo:[0,1] neg_hi:[0,1]
	v_mov_b32_e32 v117, v107
	v_pk_add_f32 v[98:99], v[98:99], v[100:101]
	s_nop 0
	v_pk_add_f32 v[98:99], v[110:111], v[98:99]
	s_nop 0
	v_pk_add_f32 v[98:99], v[118:119], v[98:99]
	s_nop 0
	v_pk_mul_f32 v[98:99], v[120:121], v[98:99]
	s_nop 0
	v_pk_add_f32 v[98:99], v[112:113], v[98:99]
	s_nop 0
	v_pk_add_f32 v[100:101], v[122:123], v[98:99]
	s_nop 0
	v_pk_add_f32 v[112:113], v[100:101], v[122:123] neg_lo:[0,1] neg_hi:[0,1]
	v_ldexp_f32 v110, v100, 1
	v_pk_add_f32 v[98:99], v[98:99], v[112:113] neg_lo:[0,1] neg_hi:[0,1]
	v_pk_mul_f32 v[112:113], v[100:101], v[100:101]
	v_ldexp_f32 v111, v101, 1
	v_pk_fma_f32 v[114:115], v[112:113], s[18:19], v[84:85] op_sel_hi:[1,0,0]
	v_pk_mul_f32 v[100:101], v[100:101], v[112:113]
	v_pk_fma_f32 v[112:113], v[112:113], v[114:115], s[20:21] op_sel_hi:[1,1,0]
	v_ldexp_f32 v98, v98, 1
	v_pk_mul_f32 v[100:101], v[100:101], v[112:113]
	v_ldexp_f32 v99, v99, 1
	v_pk_add_f32 v[112:113], v[110:111], v[100:101]
	s_nop 0
	v_pk_add_f32 v[110:111], v[112:113], v[110:111] neg_lo:[0,1] neg_hi:[0,1]
	s_nop 0
	v_pk_add_f32 v[100:101], v[100:101], v[110:111] neg_lo:[0,1] neg_hi:[0,1]
	s_nop 0
	v_pk_add_f32 v[98:99], v[98:99], v[100:101]
	s_nop 0
	v_pk_add_f32 v[100:101], v[112:113], v[98:99]
	s_nop 0
	v_pk_add_f32 v[114:115], v[106:107], v[100:101]
	v_pk_add_f32 v[110:111], v[100:101], v[112:113] neg_lo:[0,1] neg_hi:[0,1]
	v_mov_b32_e32 v116, v114
	v_pk_add_f32 v[104:105], v[116:117], v[104:105] neg_lo:[0,1] neg_hi:[0,1]
	v_mov_b32_e32 v116, v100
	v_mov_b32_e32 v117, v103
	v_pk_add_f32 v[116:117], v[116:117], v[104:105] neg_lo:[0,1] neg_hi:[0,1]
	v_mov_b32_e32 v109, v105
	v_mov_b32_e32 v100, v114
	v_mov_b32_e32 v105, v113
	v_pk_add_f32 v[104:105], v[100:101], v[104:105] neg_lo:[0,1] neg_hi:[0,1]
	v_mov_b32_e32 v112, v106
	v_mov_b32_e32 v113, v99
	v_mov_b32_e32 v111, v105
	v_pk_add_f32 v[120:121], v[114:115], v[106:107] neg_lo:[0,1] neg_hi:[0,1]
	v_pk_add_f32 v[112:113], v[112:113], v[104:105] neg_lo:[0,1] neg_hi:[0,1]
	v_pk_add_f32 v[104:105], v[98:99], v[110:111] neg_lo:[0,1] neg_hi:[0,1]
	v_mov_b32_e32 v99, v101
	v_pk_add_f32 v[100:101], v[114:115], v[120:121] neg_lo:[0,1] neg_hi:[0,1]
	v_pk_add_f32 v[118:119], v[102:103], v[108:109] neg_lo:[0,1] neg_hi:[0,1]
	v_mov_b32_e32 v111, v121
	v_mov_b32_e32 v103, v107
	v_mov_b32_e32 v109, v101
	v_pk_add_f32 v[98:99], v[98:99], v[110:111] neg_lo:[0,1] neg_hi:[0,1]
	v_pk_add_f32 v[100:101], v[102:103], v[108:109] neg_lo:[0,1] neg_hi:[0,1]
	v_pk_add_f32 v[112:113], v[116:117], v[112:113]
	v_pk_add_f32 v[98:99], v[98:99], v[100:101]
	v_mov_b32_e32 v101, v117
	v_pk_add_f32 v[102:103], v[112:113], v[98:99]
	v_mov_b32_e32 v99, v113
	v_pk_add_f32 v[100:101], v[98:99], v[100:101] neg_lo:[0,1] neg_hi:[0,1]
	v_pk_add_f32 v[106:107], v[114:115], v[102:103]
	v_pk_add_f32 v[98:99], v[98:99], v[100:101] neg_lo:[0,1] neg_hi:[0,1]
	v_pk_add_f32 v[104:105], v[104:105], v[100:101] neg_lo:[0,1] neg_hi:[0,1]
	v_pk_add_f32 v[98:99], v[118:119], v[98:99] neg_lo:[0,1] neg_hi:[0,1]
	v_pk_add_f32 v[100:101], v[106:107], v[114:115] neg_lo:[0,1] neg_hi:[0,1]
	v_pk_add_f32 v[98:99], v[104:105], v[98:99]
	v_pk_add_f32 v[100:101], v[102:103], v[100:101] neg_lo:[0,1] neg_hi:[0,1]
	v_mul_f32_e64 v102, |v83|, s19
	v_pk_add_f32 v[98:99], v[98:99], v[100:101]
	v_min_f32_e32 v83, 0, v83
	v_pk_add_f32 v[98:99], v[106:107], v[98:99]
	s_nop 0
	v_cndmask_b32_e32 v64, v94, v98, vcc
	v_cmp_neq_f32_e32 vcc, s33, v129
	s_nop 1
	v_cndmask_b32_e32 v98, v94, v99, vcc
	v_cmp_ngt_f32_e32 vcc, -1.0, v129
	s_nop 1
	v_cndmask_b32_e32 v98, v95, v98, vcc
	v_cmp_ngt_f32_e32 vcc, -1.0, v128
	s_nop 1
	v_cndmask_b32_e32 v64, v95, v64, vcc
	v_cmp_neq_f32_e32 vcc, -1.0, v128
	s_nop 1
	v_cndmask_b32_e32 v64, v96, v64, vcc
; __device__ __forceinline__ void p1_side_task(int c, LAS unsigned char* lds, const bf16_t* XN, const bf16_t* WIN, const float* b_f, float* LF, bf16_t* Kb, bf16_t* Vb, bf16_t* P1b) {
;     ...
;             for (int j = 0; j < 4; ++j) { const float xx = acc[g][j] + bfh; const float v = (fminf(xx, 0.f) - log1pf(__expf(-fabsf(xx)))) * LOG2E; const int m = 4 * fq + j;
;                 if (g < 2) { const int row = 32 * c + 16 * g + m; LF[(size_t)((row >> 12) * NH + fr) * KVROWS + 64 + (row & 4095)] = v; }
	v_cmp_neq_f32_e32 vcc, -1.0, v129
	s_nop 1
	v_cndmask_b32_e32 v98, v96, v98, vcc
	v_cmp_lt_f32_e64 vcc, |v129|, s23
	s_nop 1
	v_cndmask_b32_e32 v99, v98, v129, vcc
	v_cmp_lt_f32_e64 vcc, |v128|, s23
	v_exp_f32_e32 v129, v102
	s_nop 0
	v_cndmask_b32_e32 v98, v64, v128, vcc
	v_add_f32_e32 v64, v82, v97
	v_mul_f32_e64 v82, |v64|, s19
	v_exp_f32_e32 v128, v82
	v_pk_add_f32 v[88:89], v[88:89], v[98:99] neg_lo:[0,1] neg_hi:[0,1]
	v_min_f32_e32 v82, 0, v64
	v_pk_mul_f32 v[98:99], v[88:89], s[22:23] op_sel_hi:[1,0]
	v_add_f32_e32 v64, 1.0, v128
	v_cvt_f64_f32_e32 v[88:89], v64
	v_frexp_exp_i32_f64_e32 v100, v[88:89]
	v_add_f32_e32 v88, -1.0, v64
	v_sub_f32_e32 v89, v128, v88
	v_sub_f32_e32 v88, v88, v64
	v_add_f32_e32 v88, 1.0, v88
	v_add_f32_e32 v104, 1.0, v129
	v_add_f32_e32 v102, v89, v88
	v_cvt_f64_f32_e32 v[88:89], v104
	v_frexp_exp_i32_f64_e32 v88, v[88:89]
	v_frexp_mant_f32_e32 v89, v104
	v_cmp_gt_f32_e32 vcc, s21, v89
	v_frexp_mant_f32_e32 v101, v64
	v_add_f32_e32 v103, -1.0, v104
	v_subbrev_co_u32_e32 v89, vcc, 0, v88, vcc
	v_cmp_gt_f32_e32 vcc, s21, v101
	v_sub_f32_e32 v105, v129, v103
	v_sub_f32_e32 v103, v103, v104
	v_subbrev_co_u32_e32 v101, vcc, 0, v100, vcc
	v_sub_u32_e32 v100, 0, v101
	v_add_f32_e32 v103, 1.0, v103
	v_ldexp_f32 v88, v64, v100
	v_sub_u32_e32 v64, 0, v89
	v_add_f32_e32 v105, v105, v103
	v_cvt_f32_i32_e32 v103, v89
	v_ldexp_f32 v89, v104, v64
	v_pk_add_f32 v[114:115], v[88:89], 1.0 op_sel_hi:[1,0]
	v_ldexp_f32 v100, v102, v100
	v_pk_add_f32 v[116:117], v[114:115], -1.0 op_sel_hi:[1,0]
	v_cvt_f32_i32_e32 v102, v101
	v_ldexp_f32 v101, v105, v64
	v_pk_add_f32 v[116:117], v[88:89], v[116:117] neg_lo:[0,1] neg_hi:[0,1]
	v_pk_add_f32 v[110:111], v[88:89], -1.0 op_sel_hi:[1,0]
	v_pk_add_f32 v[116:117], v[100:101], v[116:117]
	v_pk_add_f32 v[112:113], v[110:111], 1.0 op_sel_hi:[1,0]
	v_pk_add_f32 v[118:119], v[114:115], v[116:117]
	v_pk_add_f32 v[88:89], v[88:89], v[112:113] neg_lo:[0,1] neg_hi:[0,1]
	v_rcp_f32_e32 v120, v118
	v_rcp_f32_e32 v121, v119
	v_pk_add_f32 v[88:89], v[100:101], v[88:89]
	v_pk_add_f32 v[114:115], v[118:119], v[114:115] neg_lo:[0,1] neg_hi:[0,1]
	v_pk_add_f32 v[100:101], v[110:111], v[88:89]
	v_pk_add_f32 v[114:115], v[116:117], v[114:115] neg_lo:[0,1] neg_hi:[0,1]
	v_pk_mul_f32 v[112:113], v[100:101], v[120:121]
	v_pk_add_f32 v[110:111], v[100:101], v[110:111] neg_lo:[0,1] neg_hi:[0,1]
	v_pk_mul_f32 v[122:123], v[118:119], v[112:113]
	v_pk_add_f32 v[88:89], v[88:89], v[110:111] neg_lo:[0,1] neg_hi:[0,1]
	v_pk_fma_f32 v[116:117], v[112:113], v[118:119], v[122:123] neg_lo:[0,0,1] neg_hi:[0,0,1]
	v_pk_mul_f32 v[104:105], v[102:103], s[12:13] op_sel_hi:[1,0]
	v_pk_fma_f32 v[116:117], v[112:113], v[114:115], v[116:117]
	v_pk_fma_f32 v[106:107], v[102:103], s[12:13], v[104:105] op_sel_hi:[1,0,1] neg_lo:[0,0,1] neg_hi:[0,0,1]
	v_pk_add_f32 v[124:125], v[122:123], v[116:117]
	v_pk_fma_f32 v[102:103], v[102:103], s[14:15], v[106:107] op_sel_hi:[1,0,1]
	v_pk_add_f32 v[126:127], v[100:101], v[124:125] neg_lo:[0,1] neg_hi:[0,1]
	v_pk_add_f32 v[122:123], v[124:125], v[122:123] neg_lo:[0,1] neg_hi:[0,1]
	v_pk_add_f32 v[100:101], v[100:101], v[126:127] neg_lo:[0,1] neg_hi:[0,1]
	v_pk_add_f32 v[116:117], v[122:123], v[116:117] neg_lo:[0,1] neg_hi:[0,1]
	v_pk_add_f32 v[100:101], v[100:101], v[124:125] neg_lo:[0,1] neg_hi:[0,1]
	v_pk_add_f32 v[106:107], v[104:105], v[102:103]
	v_pk_add_f32 v[88:89], v[88:89], v[100:101]
	v_pk_add_f32 v[108:109], v[106:107], v[104:105] neg_lo:[0,1] neg_hi:[0,1]
	v_pk_add_f32 v[88:89], v[116:117], v[88:89]
	v_mov_b32_e32 v104, v106
	v_pk_add_f32 v[100:101], v[126:127], v[88:89]
	v_cmp_neq_f32_e32 vcc, s33, v128
	v_pk_mul_f32 v[110:111], v[120:121], v[100:101]
	s_nop 0
	v_pk_mul_f32 v[116:117], v[118:119], v[110:111]
	v_pk_add_f32 v[122:123], v[112:113], v[110:111]
	v_pk_fma_f32 v[118:119], v[110:111], v[118:119], v[116:117] neg_lo:[0,0,1] neg_hi:[0,0,1]
	v_pk_add_f32 v[112:113], v[122:123], v[112:113] neg_lo:[0,1] neg_hi:[0,1]
	s_nop 0
	v_pk_add_f32 v[112:113], v[110:111], v[112:113] neg_lo:[0,1] neg_hi:[0,1]
	v_pk_fma_f32 v[110:111], v[110:111], v[114:115], v[118:119]
	s_nop 0
	v_pk_add_f32 v[114:115], v[116:117], v[110:111]
	s_nop 0
	v_pk_add_f32 v[118:119], v[100:101], v[114:115] neg_lo:[0,1] neg_hi:[0,1]
	v_pk_add_f32 v[116:117], v[114:115], v[116:117] neg_lo:[0,1] neg_hi:[0,1]
	s_nop 0
	v_pk_add_f32 v[110:111], v[116:117], v[110:111] neg_lo:[0,1] neg_hi:[0,1]
	v_pk_add_f32 v[116:117], v[126:127], v[100:101] neg_lo:[0,1] neg_hi:[0,1]
	v_pk_add_f32 v[100:101], v[100:101], v[118:119] neg_lo:[0,1] neg_hi:[0,1]
	v_pk_add_f32 v[88:89], v[88:89], v[116:117]
	v_pk_add_f32 v[100:101], v[100:101], v[114:115] neg_lo:[0,1] neg_hi:[0,1]
	v_mov_b32_e32 v115, v107
	v_pk_add_f32 v[88:89], v[88:89], v[100:101]
	s_nop 0
	v_pk_add_f32 v[88:89], v[110:111], v[88:89]
	s_nop 0
	v_pk_add_f32 v[88:89], v[118:119], v[88:89]
	s_nop 0
	v_pk_mul_f32 v[88:89], v[120:121], v[88:89]
	s_nop 0
	v_pk_add_f32 v[88:89], v[112:113], v[88:89]
	s_nop 0
	v_pk_add_f32 v[100:101], v[122:123], v[88:89]
	s_nop 0
	v_pk_add_f32 v[112:113], v[100:101], v[122:123] neg_lo:[0,1] neg_hi:[0,1]
	v_ldexp_f32 v110, v100, 1
	v_pk_add_f32 v[88:89], v[88:89], v[112:113] neg_lo:[0,1] neg_hi:[0,1]
	v_pk_mul_f32 v[112:113], v[100:101], v[100:101]
	v_ldexp_f32 v111, v101, 1
	v_pk_fma_f32 v[84:85], v[112:113], s[18:19], v[84:85] op_sel_hi:[1,0,0]
	v_pk_mul_f32 v[100:101], v[100:101], v[112:113]
	v_pk_fma_f32 v[84:85], v[112:113], v[84:85], s[20:21] op_sel_hi:[1,1,0]
	v_ldexp_f32 v88, v88, 1
	v_pk_mul_f32 v[84:85], v[100:101], v[84:85]
	v_ldexp_f32 v89, v89, 1
	v_pk_add_f32 v[100:101], v[110:111], v[84:85]
	s_nop 0
; __device__ __forceinline__ void p1_side_task(int c, LAS unsigned char* lds, const bf16_t* XN, const bf16_t* WIN, const float* b_f, float* LF, bf16_t* Kb, bf16_t* Vb, bf16_t* P1b) {
;     ...
;         for (int g = 0; g < 5; ++g) { f32x4 s = red[g * 64 + lane];
; #pragma unroll
;             for (int ww = 1; ww < 8; ++ww) s += red[(ww * 5 + g) * 64 + lane];
;             acc[g] = s; }
;         const float bfh = b_f[fr];
; #pragma unroll
;         for (int g = 0; g < 3; ++g)
; #pragma unroll
;             for (int j = 0; j < 4; ++j) { const float xx = acc[g][j] + bfh; const float v = (fminf(xx, 0.f) - log1pf(__expf(-fabsf(xx)))) * LOG2E; const int m = 4 * fq + j;
;                 if (g < 2) { const int row = 32 * c + 16 * g + m; LF[(size_t)((row >> 12) * NH + fr) * KVROWS + 64 + (row & 4095)] = v; }
;                 else if (c == 0) { LF[(size_t)fr * KVROWS + 48 + m] = v; LF[(size_t)(NH + fr) * KVROWS + 48 + m] = v; } }
	v_pk_add_f32 v[110:111], v[100:101], v[110:111] neg_lo:[0,1] neg_hi:[0,1]
	s_nop 0
	v_pk_add_f32 v[84:85], v[84:85], v[110:111] neg_lo:[0,1] neg_hi:[0,1]
	s_nop 0
	v_pk_add_f32 v[84:85], v[88:89], v[84:85]
	s_nop 0
	v_pk_add_f32 v[88:89], v[100:101], v[84:85]
	s_nop 0
	v_pk_add_f32 v[112:113], v[106:107], v[88:89]
	v_pk_add_f32 v[110:111], v[88:89], v[100:101] neg_lo:[0,1] neg_hi:[0,1]
	v_mov_b32_e32 v114, v112
	v_pk_add_f32 v[104:105], v[114:115], v[104:105] neg_lo:[0,1] neg_hi:[0,1]
	v_mov_b32_e32 v114, v88
	v_mov_b32_e32 v115, v103
	v_pk_add_f32 v[114:115], v[114:115], v[104:105] neg_lo:[0,1] neg_hi:[0,1]
	v_mov_b32_e32 v109, v105
	v_mov_b32_e32 v88, v112
	v_mov_b32_e32 v105, v101
	v_pk_add_f32 v[100:101], v[88:89], v[104:105] neg_lo:[0,1] neg_hi:[0,1]
	v_mov_b32_e32 v104, v106
	v_mov_b32_e32 v105, v85
	v_mov_b32_e32 v111, v101
	v_pk_add_f32 v[118:119], v[112:113], v[106:107] neg_lo:[0,1] neg_hi:[0,1]
	v_pk_add_f32 v[104:105], v[104:105], v[100:101] neg_lo:[0,1] neg_hi:[0,1]
	v_pk_add_f32 v[100:101], v[84:85], v[110:111] neg_lo:[0,1] neg_hi:[0,1]
	v_mov_b32_e32 v85, v89
	v_pk_add_f32 v[88:89], v[112:113], v[118:119] neg_lo:[0,1] neg_hi:[0,1]
	v_pk_add_f32 v[116:117], v[102:103], v[108:109] neg_lo:[0,1] neg_hi:[0,1]
	v_mov_b32_e32 v111, v119
	v_mov_b32_e32 v103, v107
	v_mov_b32_e32 v109, v89
	v_pk_add_f32 v[84:85], v[84:85], v[110:111] neg_lo:[0,1] neg_hi:[0,1]
	v_pk_add_f32 v[88:89], v[102:103], v[108:109] neg_lo:[0,1] neg_hi:[0,1]
	v_pk_add_f32 v[104:105], v[114:115], v[104:105]
	v_pk_add_f32 v[84:85], v[84:85], v[88:89]
	v_mov_b32_e32 v89, v115
	v_pk_add_f32 v[102:103], v[104:105], v[84:85]
	v_mov_b32_e32 v85, v105
	v_pk_add_f32 v[88:89], v[84:85], v[88:89] neg_lo:[0,1] neg_hi:[0,1]
	v_pk_add_f32 v[106:107], v[112:113], v[102:103]
	v_pk_add_f32 v[84:85], v[84:85], v[88:89] neg_lo:[0,1] neg_hi:[0,1]
	v_pk_add_f32 v[100:101], v[100:101], v[88:89] neg_lo:[0,1] neg_hi:[0,1]
	v_pk_add_f32 v[84:85], v[116:117], v[84:85] neg_lo:[0,1] neg_hi:[0,1]
	v_pk_add_f32 v[88:89], v[106:107], v[112:113] neg_lo:[0,1] neg_hi:[0,1]
	v_pk_add_f32 v[84:85], v[100:101], v[84:85]
	v_pk_add_f32 v[88:89], v[102:103], v[88:89] neg_lo:[0,1] neg_hi:[0,1]
	s_nop 0
	v_pk_add_f32 v[84:85], v[84:85], v[88:89]
	s_nop 0
	v_pk_add_f32 v[84:85], v[106:107], v[84:85]
	s_nop 0
	v_cndmask_b32_e32 v64, v94, v84, vcc
	v_cmp_neq_f32_e32 vcc, s33, v129
	s_nop 1
	v_cndmask_b32_e32 v84, v94, v85, vcc
	v_cmp_ngt_f32_e32 vcc, -1.0, v129
	s_nop 1
	v_cndmask_b32_e32 v84, v95, v84, vcc
	v_cmp_ngt_f32_e32 vcc, -1.0, v128
	s_nop 1
	v_cndmask_b32_e32 v64, v95, v64, vcc
	v_cmp_neq_f32_e32 vcc, -1.0, v128
	s_nop 1
	v_cndmask_b32_e32 v64, v96, v64, vcc
	v_cmp_neq_f32_e32 vcc, -1.0, v129
	s_nop 1
	v_cndmask_b32_e32 v84, v96, v84, vcc
	v_cmp_lt_f32_e64 vcc, |v129|, s23
	s_nop 1
	v_cndmask_b32_e32 v85, v84, v129, vcc
	v_cmp_lt_f32_e64 vcc, |v128|, s23
	s_nop 1
	v_cndmask_b32_e32 v84, v64, v128, vcc
	v_pk_add_f32 v[82:83], v[82:83], v[84:85] neg_lo:[0,1] neg_hi:[0,1]
	s_nop 0
	v_pk_mul_f32 v[100:101], v[82:83], s[22:23] op_sel_hi:[1,0]
	global_store_dwordx4 v[86:87], v[98:101], off offset:320
	s_cbranch_scc1 .LBB0_426
	ds_read_b128 v[82:85], v91 offset:2048
	ds_read_b128 v[86:89], v91 offset:7168
	ds_read_b128 v[98:101], v91 offset:12288
	ds_read_b128 v[102:105], v91 offset:17408
	ds_read_b128 v[106:109], v91 offset:22528
	ds_read_b128 v[110:113], v91 offset:27648
	ds_read_b128 v[114:117], v91 offset:32768
	ds_read_b128 v[118:121], v91 offset:37888
	s_waitcnt lgkmcnt(6)
	v_pk_add_f32 v[82:83], v[82:83], v[86:87]
	v_pk_add_f32 v[84:85], v[84:85], v[88:89]
	s_waitcnt lgkmcnt(5)
	v_pk_add_f32 v[82:83], v[82:83], v[98:99]
	v_pk_add_f32 v[84:85], v[84:85], v[100:101]
	s_waitcnt lgkmcnt(4)
	v_pk_add_f32 v[82:83], v[82:83], v[102:103]
	s_waitcnt lgkmcnt(3)
	v_pk_add_f32 v[82:83], v[82:83], v[106:107]
	s_waitcnt lgkmcnt(2)
	v_pk_add_f32 v[82:83], v[82:83], v[110:111]
	s_waitcnt lgkmcnt(1)
	v_pk_add_f32 v[82:83], v[82:83], v[114:115]
	s_waitcnt lgkmcnt(0)
	v_pk_add_f32 v[86:87], v[82:83], v[118:119]
	s_nop 0
	v_add_f32_e32 v64, v86, v97
	v_mul_f32_e64 v82, |v64|, s19
	v_exp_f32_e32 v86, v82
	v_pk_add_f32 v[82:83], v[84:85], v[104:105]
	v_add_f32_e32 v87, v87, v97
	v_min_f32_e32 v64, 0, v64
	v_add_f32_e32 v88, 1.0, v86
	v_cvt_f64_f32_e32 v[84:85], v88
	v_frexp_exp_i32_f64_e32 v84, v[84:85]
	v_frexp_mant_f32_e32 v85, v88
	v_cmp_gt_f32_e32 vcc, s21, v85
	v_add_f32_e32 v101, -1.0, v88
	v_sub_f32_e32 v102, v86, v101
	v_subbrev_co_u32_e32 v84, vcc, 0, v84, vcc
	v_cvt_f32_i32_e32 v85, v84
	v_sub_u32_e32 v84, 0, v84
	v_ldexp_f32 v99, v88, v84
	v_sub_f32_e32 v88, v101, v88
	v_add_f32_e32 v88, 1.0, v88
	v_add_f32_e32 v101, 1.0, v99
	v_add_f32_e32 v88, v102, v88
	v_add_f32_e32 v102, -1.0, v101
	v_ldexp_f32 v84, v88, v84
	v_sub_f32_e32 v102, v99, v102
	v_add_f32_e32 v102, v84, v102
	v_add_f32_e32 v100, -1.0, v99
	v_add_f32_e32 v103, v101, v102
	v_add_f32_e32 v88, 1.0, v100
	v_rcp_f32_e32 v104, v103
	v_sub_f32_e32 v88, v99, v88
	v_add_f32_e32 v84, v84, v88
	v_add_f32_e32 v88, v100, v84
	v_mul_f32_e32 v99, v88, v104
	v_mul_f32_e32 v105, v103, v99
	v_sub_f32_e32 v101, v103, v101
	v_sub_f32_e32 v101, v102, v101
	v_fma_f32 v102, v99, v103, -v105
	v_fmac_f32_e32 v102, v99, v101
	v_add_f32_e32 v106, v105, v102
	v_sub_f32_e32 v107, v88, v106
	v_sub_f32_e32 v100, v88, v100
	v_sub_f32_e32 v88, v88, v107
	v_sub_f32_e32 v105, v106, v105
	v_sub_f32_e32 v84, v84, v100
	v_sub_f32_e32 v88, v88, v106
	v_sub_f32_e32 v102, v105, v102
	v_add_f32_e32 v84, v84, v88
	v_add_f32_e32 v84, v102, v84
	v_add_f32_e32 v88, v107, v84
	v_mul_f32_e32 v100, v104, v88
	v_mul_f32_e32 v105, v103, v100
	v_add_f32_e32 v102, v99, v100
; __device__ __forceinline__ void p1_side_task(int c, LAS unsigned char* lds, const bf16_t* XN, const bf16_t* WIN, const float* b_f, float* LF, bf16_t* Kb, bf16_t* Vb, bf16_t* P1b) {
;     ...
;             for (int j = 0; j < 4; ++j) { const float xx = acc[g][j] + bfh; const float v = (fminf(xx, 0.f) - log1pf(__expf(-fabsf(xx)))) * LOG2E; const int m = 4 * fq + j;
;                 if (g < 2) { const int row = 32 * c + 16 * g + m; LF[(size_t)((row >> 12) * NH + fr) * KVROWS + 64 + (row & 4095)] = v; }
;                 else if (c == 0) { LF[(size_t)fr * KVROWS + 48 + m] = v; LF[(size_t)(NH + fr) * KVROWS + 48 + m] = v; } }
	v_fma_f32 v103, v100, v103, -v105
	v_sub_f32_e32 v99, v102, v99
	v_fmac_f32_e32 v103, v100, v101
	v_sub_f32_e32 v99, v100, v99
	v_add_f32_e32 v100, v105, v103
	v_sub_f32_e32 v101, v88, v100
	v_sub_f32_e32 v105, v100, v105
	v_sub_f32_e32 v103, v105, v103
	v_sub_f32_e32 v105, v107, v88
	v_sub_f32_e32 v88, v88, v101
	v_add_f32_e32 v84, v84, v105
	v_sub_f32_e32 v88, v88, v100
	v_add_f32_e32 v84, v84, v88
	v_add_f32_e32 v84, v103, v84
	v_add_f32_e32 v84, v101, v84
	v_mul_f32_e32 v84, v104, v84
	v_add_f32_e32 v84, v99, v84
	v_add_f32_e32 v88, v102, v84
	v_mul_f32_e32 v100, v88, v88
	v_fmamk_f32 v103, v100, 0x3e9b6dac, v93
	v_mul_f32_e32 v101, v88, v100
	v_fmaak_f32 v100, v100, v103, 0x3f2aaada
	v_ldexp_f32 v99, v88, 1
	v_mul_f32_e32 v100, v101, v100
	v_add_f32_e32 v101, v99, v100
	v_sub_f32_e32 v88, v88, v102
	v_mul_f32_e32 v89, 0x3f317218, v85
	v_sub_f32_e32 v84, v84, v88
	v_sub_f32_e32 v88, v101, v99
	v_fma_f32 v98, v85, s12, -v89
	v_ldexp_f32 v84, v84, 1
	v_sub_f32_e32 v88, v100, v88
	v_fmac_f32_e32 v98, 0xb102e308, v85
	v_add_f32_e32 v84, v84, v88
	v_add_f32_e32 v85, v89, v98
	v_add_f32_e32 v88, v101, v84
	v_add_f32_e32 v99, v85, v88
	v_sub_f32_e32 v89, v85, v89
	v_sub_f32_e32 v89, v98, v89
	v_sub_f32_e32 v98, v88, v101
	v_sub_f32_e32 v100, v99, v85
	v_sub_f32_e32 v84, v84, v98
	v_sub_f32_e32 v88, v88, v100
	v_sub_f32_e32 v100, v99, v100
	v_add_f32_e32 v98, v89, v84
	v_sub_f32_e32 v85, v85, v100
	v_add_f32_e32 v85, v88, v85
	v_sub_f32_e32 v100, v98, v89
	v_add_f32_e32 v85, v98, v85
	v_sub_f32_e32 v98, v98, v100
	v_add_f32_e32 v88, v99, v85
	v_sub_f32_e32 v84, v84, v100
	v_sub_f32_e32 v89, v89, v98
	v_add_f32_e32 v84, v84, v89
	v_sub_f32_e32 v89, v88, v99
	v_sub_f32_e32 v85, v85, v89
	v_add_f32_e32 v84, v84, v85
	v_mul_f32_e64 v85, |v87|, s19
	v_add_f32_e32 v84, v88, v84
	v_cmp_neq_f32_e32 vcc, s33, v86
	v_exp_f32_e32 v88, v85
	v_pk_add_f32 v[82:83], v[82:83], v[108:109]
	v_cndmask_b32_e32 v84, v94, v84, vcc
	v_cmp_ngt_f32_e32 vcc, -1.0, v86
	v_pk_add_f32 v[82:83], v[82:83], v[112:113]
	s_nop 0
	v_cndmask_b32_e32 v84, v95, v84, vcc
	v_cmp_neq_f32_e32 vcc, -1.0, v86
	v_pk_add_f32 v[82:83], v[82:83], v[116:117]
	s_nop 0
	v_cndmask_b32_e32 v84, v96, v84, vcc
	v_cmp_lt_f32_e64 vcc, |v86|, s23
	v_pk_add_f32 v[82:83], v[82:83], v[120:121]
	s_nop 0
	v_cndmask_b32_e32 v84, v84, v86, vcc
	v_add_f32_e32 v86, 1.0, v88
	v_sub_f32_e32 v64, v64, v84
	v_cvt_f64_f32_e32 v[84:85], v86
	v_frexp_exp_i32_f64_e32 v84, v[84:85]
	v_frexp_mant_f32_e32 v85, v86
	v_cmp_gt_f32_e32 vcc, s21, v85
	v_add_f32_e32 v100, -1.0, v86
	v_sub_f32_e32 v101, v88, v100
	v_subbrev_co_u32_e32 v84, vcc, 0, v84, vcc
	v_cvt_f32_i32_e32 v85, v84
	v_sub_u32_e32 v84, 0, v84
	v_ldexp_f32 v98, v86, v84
	v_sub_f32_e32 v86, v100, v86
	v_add_f32_e32 v86, 1.0, v86
	v_add_f32_e32 v100, 1.0, v98
	v_add_f32_e32 v86, v101, v86
	v_add_f32_e32 v101, -1.0, v100
	v_ldexp_f32 v84, v86, v84
	v_sub_f32_e32 v101, v98, v101
	v_add_f32_e32 v101, v84, v101
	v_add_f32_e32 v99, -1.0, v98
	v_add_f32_e32 v102, v100, v101
	v_add_f32_e32 v86, 1.0, v99
	v_rcp_f32_e32 v103, v102
	v_sub_f32_e32 v86, v98, v86
	v_add_f32_e32 v84, v84, v86
	v_add_f32_e32 v86, v99, v84
	v_mul_f32_e32 v98, v86, v103
	v_mul_f32_e32 v104, v102, v98
	v_sub_f32_e32 v100, v102, v100
	v_sub_f32_e32 v100, v101, v100
	v_fma_f32 v101, v98, v102, -v104
	v_fmac_f32_e32 v101, v98, v100
	v_add_f32_e32 v105, v104, v101
	v_sub_f32_e32 v106, v86, v105
	v_sub_f32_e32 v99, v86, v99
	v_sub_f32_e32 v86, v86, v106
	v_sub_f32_e32 v104, v105, v104
	v_sub_f32_e32 v84, v84, v99
	v_sub_f32_e32 v86, v86, v105
	v_sub_f32_e32 v101, v104, v101
	v_add_f32_e32 v84, v84, v86
	v_add_f32_e32 v84, v101, v84
	v_add_f32_e32 v86, v106, v84
	v_mul_f32_e32 v99, v103, v86
	v_mul_f32_e32 v104, v102, v99
	v_add_f32_e32 v101, v98, v99
	v_fma_f32 v102, v99, v102, -v104
	v_sub_f32_e32 v98, v101, v98
	v_fmac_f32_e32 v102, v99, v100
	v_sub_f32_e32 v98, v99, v98
	v_add_f32_e32 v99, v104, v102
	v_sub_f32_e32 v100, v86, v99
	v_sub_f32_e32 v104, v99, v104
	v_sub_f32_e32 v102, v104, v102
	v_sub_f32_e32 v104, v106, v86
	v_sub_f32_e32 v86, v86, v100
	v_add_f32_e32 v84, v84, v104
	v_sub_f32_e32 v86, v86, v99
	v_add_f32_e32 v84, v84, v86
	v_add_f32_e32 v84, v102, v84
	v_add_f32_e32 v84, v100, v84
	v_mul_f32_e32 v84, v103, v84
	v_add_f32_e32 v84, v98, v84
	v_add_f32_e32 v86, v101, v84
	v_mul_f32_e32 v99, v86, v86
	v_fmamk_f32 v102, v99, 0x3e9b6dac, v93
	v_mul_f32_e32 v100, v86, v99
	v_fmaak_f32 v99, v99, v102, 0x3f2aaada
	v_ldexp_f32 v98, v86, 1
	v_mul_f32_e32 v99, v100, v99
	v_mul_f32_e32 v64, 0x3fb8aa3b, v64
	v_add_f32_e32 v100, v98, v99
	v_sub_f32_e32 v86, v86, v101
	global_store_dword v[68:69], v64, off offset:192
	global_store_dword v[70:71], v64, off
	v_min_f32_e32 v64, 0, v87
	v_mul_f32_e32 v87, 0x3f317218, v85
	v_sub_f32_e32 v84, v84, v86
	v_sub_f32_e32 v86, v100, v98
	v_fma_f32 v89, v85, s12, -v87
	v_ldexp_f32 v84, v84, 1
	v_sub_f32_e32 v86, v99, v86
	v_fmac_f32_e32 v89, 0xb102e308, v85
	v_add_f32_e32 v84, v84, v86
	v_add_f32_e32 v85, v87, v89
	v_add_f32_e32 v86, v100, v84
	v_add_f32_e32 v98, v85, v86
	v_sub_f32_e32 v87, v85, v87
	v_sub_f32_e32 v87, v89, v87
	v_sub_f32_e32 v89, v86, v100
	v_sub_f32_e32 v99, v98, v85
	v_sub_f32_e32 v84, v84, v89
	v_sub_f32_e32 v86, v86, v99
	v_sub_f32_e32 v99, v98, v99
	v_add_f32_e32 v89, v87, v84
	v_sub_f32_e32 v85, v85, v99
	v_add_f32_e32 v85, v86, v85
	v_sub_f32_e32 v99, v89, v87
	v_add_f32_e32 v85, v89, v85
	v_sub_f32_e32 v89, v89, v99
	v_add_f32_e32 v86, v98, v85
	v_sub_f32_e32 v84, v84, v99
	v_sub_f32_e32 v87, v87, v89
	v_add_f32_e32 v84, v84, v87
	v_sub_f32_e32 v87, v86, v98
	v_sub_f32_e32 v85, v85, v87
	v_add_f32_e32 v82, v82, v97
; __device__ __forceinline__ void p1_side_task(int c, LAS unsigned char* lds, const bf16_t* XN, const bf16_t* WIN, const float* b_f, float* LF, bf16_t* Kb, bf16_t* Vb, bf16_t* P1b) {
;     ...
;             for (int j = 0; j < 4; ++j) { const float xx = acc[g][j] + bfh; const float v = (fminf(xx, 0.f) - log1pf(__expf(-fabsf(xx)))) * LOG2E; const int m = 4 * fq + j;
;                 if (g < 2) { const int row = 32 * c + 16 * g + m; LF[(size_t)((row >> 12) * NH + fr) * KVROWS + 64 + (row & 4095)] = v; }
;                 else if (c == 0) { LF[(size_t)fr * KVROWS + 48 + m] = v; LF[(size_t)(NH + fr) * KVROWS + 48 + m] = v; } }
	v_add_f32_e32 v84, v84, v85
	v_mul_f32_e64 v85, |v82|, s19
	v_add_f32_e32 v84, v86, v84
	v_cmp_neq_f32_e32 vcc, s33, v88
	v_exp_f32_e32 v86, v85
	s_nop 0
	v_cndmask_b32_e32 v84, v94, v84, vcc
	v_cmp_ngt_f32_e32 vcc, -1.0, v88
	v_add_f32_e32 v87, 1.0, v86
	v_add_f32_e32 v99, -1.0, v87
	v_cndmask_b32_e32 v84, v95, v84, vcc
	v_cmp_neq_f32_e32 vcc, -1.0, v88
	v_sub_f32_e32 v100, v86, v99
	s_nop 0
	v_cndmask_b32_e32 v84, v96, v84, vcc
	v_cmp_lt_f32_e64 vcc, |v88|, s23
	s_nop 1
	v_cndmask_b32_e32 v84, v84, v88, vcc
	v_sub_f32_e32 v64, v64, v84
	v_cvt_f64_f32_e32 v[84:85], v87
	v_frexp_exp_i32_f64_e32 v84, v[84:85]
	v_frexp_mant_f32_e32 v85, v87
	v_cmp_gt_f32_e32 vcc, s21, v85
	v_mul_f32_e32 v64, 0x3fb8aa3b, v64
	global_store_dword v[68:69], v64, off offset:196
	global_store_dword v[72:73], v64, off
	v_subbrev_co_u32_e32 v84, vcc, 0, v84, vcc
	v_cvt_f32_i32_e32 v85, v84
	v_sub_u32_e32 v84, 0, v84
	v_ldexp_f32 v89, v87, v84
	v_sub_f32_e32 v87, v99, v87
	v_add_f32_e32 v87, 1.0, v87
	v_add_f32_e32 v99, 1.0, v89
	v_add_f32_e32 v87, v100, v87
	v_add_f32_e32 v100, -1.0, v99
	v_ldexp_f32 v84, v87, v84
	v_sub_f32_e32 v100, v89, v100
	v_add_f32_e32 v100, v84, v100
	v_add_f32_e32 v98, -1.0, v89
	v_add_f32_e32 v101, v99, v100
	v_add_f32_e32 v87, 1.0, v98
	v_rcp_f32_e32 v102, v101
	v_sub_f32_e32 v87, v89, v87
	v_add_f32_e32 v84, v84, v87
	v_add_f32_e32 v87, v98, v84
	v_mul_f32_e32 v89, v87, v102
	v_mul_f32_e32 v103, v101, v89
	v_sub_f32_e32 v99, v101, v99
	v_sub_f32_e32 v99, v100, v99
	v_fma_f32 v100, v89, v101, -v103
	v_fmac_f32_e32 v100, v89, v99
	v_add_f32_e32 v104, v103, v100
	v_sub_f32_e32 v105, v87, v104
	v_sub_f32_e32 v98, v87, v98
	v_sub_f32_e32 v87, v87, v105
	v_sub_f32_e32 v103, v104, v103
	v_sub_f32_e32 v84, v84, v98
	v_sub_f32_e32 v87, v87, v104
	v_sub_f32_e32 v100, v103, v100
	v_add_f32_e32 v84, v84, v87
	v_add_f32_e32 v84, v100, v84
	v_add_f32_e32 v87, v105, v84
	v_mul_f32_e32 v98, v102, v87
	v_mul_f32_e32 v103, v101, v98
	v_add_f32_e32 v100, v89, v98
	v_fma_f32 v101, v98, v101, -v103
	v_sub_f32_e32 v89, v100, v89
	v_fmac_f32_e32 v101, v98, v99
	v_sub_f32_e32 v89, v98, v89
	v_add_f32_e32 v98, v103, v101
	v_sub_f32_e32 v99, v87, v98
	v_sub_f32_e32 v103, v98, v103
	v_sub_f32_e32 v101, v103, v101
	v_sub_f32_e32 v103, v105, v87
	v_sub_f32_e32 v87, v87, v99
	v_add_f32_e32 v84, v84, v103
	v_sub_f32_e32 v87, v87, v98
	v_add_f32_e32 v84, v84, v87
	v_add_f32_e32 v84, v101, v84
	v_add_f32_e32 v84, v99, v84
	v_mul_f32_e32 v84, v102, v84
	v_add_f32_e32 v84, v89, v84
	v_add_f32_e32 v87, v100, v84
	v_mul_f32_e32 v98, v87, v87
	v_fmamk_f32 v101, v98, 0x3e9b6dac, v93
	v_mul_f32_e32 v99, v87, v98
	v_fmaak_f32 v98, v98, v101, 0x3f2aaada
	v_ldexp_f32 v89, v87, 1
	v_mul_f32_e32 v98, v99, v98
	v_add_f32_e32 v99, v89, v98
	v_sub_f32_e32 v87, v87, v100
	v_min_f32_e32 v64, 0, v82
	v_mul_f32_e32 v82, 0x3f317218, v85
	v_sub_f32_e32 v84, v84, v87
	v_sub_f32_e32 v87, v99, v89
	v_fma_f32 v88, v85, s12, -v82
	v_ldexp_f32 v84, v84, 1
	v_sub_f32_e32 v87, v98, v87
	v_fmac_f32_e32 v88, 0xb102e308, v85
	v_add_f32_e32 v84, v84, v87
	v_add_f32_e32 v85, v82, v88
	v_add_f32_e32 v87, v99, v84
	v_add_f32_e32 v89, v85, v87
	v_sub_f32_e32 v82, v85, v82
	v_sub_f32_e32 v82, v88, v82
	v_sub_f32_e32 v88, v87, v99
	v_sub_f32_e32 v98, v89, v85
	v_sub_f32_e32 v84, v84, v88
	v_sub_f32_e32 v87, v87, v98
	v_sub_f32_e32 v98, v89, v98
	v_add_f32_e32 v88, v82, v84
	v_sub_f32_e32 v85, v85, v98
	v_add_f32_e32 v85, v87, v85
	v_sub_f32_e32 v98, v88, v82
	v_add_f32_e32 v85, v88, v85
	v_sub_f32_e32 v88, v88, v98
	v_add_f32_e32 v87, v89, v85
	v_sub_f32_e32 v84, v84, v98
	v_sub_f32_e32 v82, v82, v88
	v_add_f32_e32 v82, v84, v82
	v_sub_f32_e32 v84, v87, v89
	v_sub_f32_e32 v84, v85, v84
	v_add_f32_e32 v82, v82, v84
	v_add_f32_e32 v84, v83, v97
	v_mul_f32_e64 v83, |v84|, s19
	v_add_f32_e32 v82, v87, v82
	v_cmp_neq_f32_e32 vcc, s33, v86
	v_exp_f32_e32 v85, v83
	s_nop 0
	v_cndmask_b32_e32 v82, v94, v82, vcc
	v_cmp_ngt_f32_e32 vcc, -1.0, v86
	s_nop 1
; __device__ __forceinline__ void p1_side_task(int c, LAS unsigned char* lds, const bf16_t* XN, const bf16_t* WIN, const float* b_f, float* LF, bf16_t* Kb, bf16_t* Vb, bf16_t* P1b) {
;     ...
;             for (int j = 0; j < 4; ++j) { const float xx = acc[g][j] + bfh; const float v = (fminf(xx, 0.f) - log1pf(__expf(-fabsf(xx)))) * LOG2E; const int m = 4 * fq + j;
;                 if (g < 2) { const int row = 32 * c + 16 * g + m; LF[(size_t)((row >> 12) * NH + fr) * KVROWS + 64 + (row & 4095)] = v; }
;                 else if (c == 0) { LF[(size_t)fr * KVROWS + 48 + m] = v; LF[(size_t)(NH + fr) * KVROWS + 48 + m] = v; } }
	v_cndmask_b32_e32 v82, v95, v82, vcc
	v_cmp_neq_f32_e32 vcc, -1.0, v86
	s_nop 1
	v_cndmask_b32_e32 v82, v96, v82, vcc
	v_cmp_lt_f32_e64 vcc, |v86|, s23
	s_nop 1
	v_cndmask_b32_e32 v82, v82, v86, vcc
	v_add_f32_e32 v86, 1.0, v85
	v_sub_f32_e32 v64, v64, v82
	v_cvt_f64_f32_e32 v[82:83], v86
	v_frexp_exp_i32_f64_e32 v82, v[82:83]
	v_frexp_mant_f32_e32 v83, v86
	v_cmp_gt_f32_e32 vcc, s21, v83
	v_add_f32_e32 v97, -1.0, v86
	v_sub_f32_e32 v98, v85, v97
	v_subbrev_co_u32_e32 v82, vcc, 0, v82, vcc
	v_cvt_f32_i32_e32 v83, v82
	v_sub_u32_e32 v82, 0, v82
	v_ldexp_f32 v88, v86, v82
	v_sub_f32_e32 v86, v97, v86
	v_add_f32_e32 v86, 1.0, v86
	v_add_f32_e32 v97, 1.0, v88
	v_add_f32_e32 v86, v98, v86
	v_add_f32_e32 v98, -1.0, v97
	v_ldexp_f32 v82, v86, v82
	v_sub_f32_e32 v98, v88, v98
	v_add_f32_e32 v98, v82, v98
	v_add_f32_e32 v89, -1.0, v88
	v_add_f32_e32 v99, v97, v98
	v_add_f32_e32 v86, 1.0, v89
	v_rcp_f32_e32 v100, v99
	v_sub_f32_e32 v86, v88, v86
	v_add_f32_e32 v82, v82, v86
	v_add_f32_e32 v86, v89, v82
	v_mul_f32_e32 v88, v86, v100
	v_mul_f32_e32 v101, v99, v88
	v_sub_f32_e32 v97, v99, v97
	v_sub_f32_e32 v97, v98, v97
	v_fma_f32 v98, v88, v99, -v101
	v_fmac_f32_e32 v98, v88, v97
	v_add_f32_e32 v102, v101, v98
	v_sub_f32_e32 v103, v86, v102
	v_sub_f32_e32 v89, v86, v89
	v_sub_f32_e32 v86, v86, v103
	v_sub_f32_e32 v101, v102, v101
	v_sub_f32_e32 v82, v82, v89
	v_sub_f32_e32 v86, v86, v102
	v_sub_f32_e32 v98, v101, v98
	v_add_f32_e32 v82, v82, v86
	v_add_f32_e32 v82, v98, v82
	v_add_f32_e32 v86, v103, v82
	v_mul_f32_e32 v89, v100, v86
	v_mul_f32_e32 v101, v99, v89
	v_add_f32_e32 v98, v88, v89
	v_fma_f32 v99, v89, v99, -v101
	v_sub_f32_e32 v88, v98, v88
	v_fmac_f32_e32 v99, v89, v97
	v_sub_f32_e32 v88, v89, v88
	v_add_f32_e32 v89, v101, v99
	v_sub_f32_e32 v97, v86, v89
	v_sub_f32_e32 v101, v89, v101
	v_sub_f32_e32 v99, v101, v99
	v_sub_f32_e32 v101, v103, v86
	v_sub_f32_e32 v86, v86, v97
	v_add_f32_e32 v82, v82, v101
	v_sub_f32_e32 v86, v86, v89
	v_add_f32_e32 v82, v82, v86
	v_add_f32_e32 v82, v99, v82
	v_add_f32_e32 v82, v97, v82
	v_mul_f32_e32 v82, v100, v82
	v_add_f32_e32 v82, v88, v82
	v_add_f32_e32 v86, v98, v82
	v_mul_f32_e32 v89, v86, v86
	v_fmamk_f32 v99, v89, 0x3e9b6dac, v93
	v_mul_f32_e32 v97, v86, v89
	v_fmaak_f32 v89, v89, v99, 0x3f2aaada
	v_ldexp_f32 v88, v86, 1
	v_mul_f32_e32 v89, v97, v89
	v_mul_f32_e32 v64, 0x3fb8aa3b, v64
	v_add_f32_e32 v97, v88, v89
	v_sub_f32_e32 v86, v86, v98
	global_store_dword v[68:69], v64, off offset:200
	global_store_dword v[74:75], v64, off
	v_min_f32_e32 v64, 0, v84
	v_mul_f32_e32 v84, 0x3f317218, v83
	v_sub_f32_e32 v82, v82, v86
	v_sub_f32_e32 v86, v97, v88
	v_fma_f32 v87, v83, s12, -v84
	v_ldexp_f32 v82, v82, 1
	v_sub_f32_e32 v86, v89, v86
	v_fmac_f32_e32 v87, 0xb102e308, v83
	v_add_f32_e32 v82, v82, v86
	v_add_f32_e32 v83, v84, v87
	v_add_f32_e32 v86, v97, v82
	v_add_f32_e32 v88, v83, v86
	v_sub_f32_e32 v84, v83, v84
	v_sub_f32_e32 v84, v87, v84
	v_sub_f32_e32 v87, v86, v97
	v_sub_f32_e32 v89, v88, v83
	v_sub_f32_e32 v82, v82, v87
	v_sub_f32_e32 v86, v86, v89
	v_sub_f32_e32 v89, v88, v89
	v_add_f32_e32 v87, v84, v82
	v_sub_f32_e32 v83, v83, v89
	v_add_f32_e32 v83, v86, v83
	v_sub_f32_e32 v89, v87, v84
	v_add_f32_e32 v83, v87, v83
	v_sub_f32_e32 v87, v87, v89
	v_add_f32_e32 v86, v88, v83
	v_sub_f32_e32 v82, v82, v89
	v_sub_f32_e32 v84, v84, v87
	v_add_f32_e32 v82, v82, v84
	v_sub_f32_e32 v84, v86, v88
	v_sub_f32_e32 v83, v83, v84
	v_add_f32_e32 v82, v82, v83
	v_add_f32_e32 v82, v86, v82
	v_cmp_neq_f32_e32 vcc, s33, v85
	s_nop 1
	v_cndmask_b32_e32 v82, v94, v82, vcc
	v_cmp_ngt_f32_e32 vcc, -1.0, v85
	s_nop 1
	v_cndmask_b32_e32 v82, v95, v82, vcc
	v_cmp_neq_f32_e32 vcc, -1.0, v85
	s_nop 1
	v_cndmask_b32_e32 v82, v96, v82, vcc
	v_cmp_lt_f32_e64 vcc, |v85|, s23
	s_nop 1
	v_cndmask_b32_e32 v82, v82, v85, vcc
	v_sub_f32_e32 v64, v64, v82
	v_mul_f32_e32 v64, 0x3fb8aa3b, v64
	global_store_dword v[68:69], v64, off offset:204
	global_store_dword v[76:77], v64, off
